# e31: e29 + loop-edge rotation (7.11): K-loop counter/pointer bumps and exit test moved in front of the loop-back barrier in all 7 GEMM K loops
# baseline (speedup 1.0000x reference)
; #define PG8_STAGE_A(bufoff, gbase) PG8_STAGE(bufoff, gbase, voffA, a64)
; #define PG8_STAGE_B(bufoff, bp, hb, tz) do { if (BMODE == 1 && (tz)) PG8_STAGE(bufoff, (bp) + (hb) * 4096, voffT, t64); else PG8_STAGE(bufoff, (bp) + (hb) * bhstep, voffB, b64); } while (0)
; #define PG8_LDA(dst, b, h) do { _Pragma("unroll") for (int m = 0; m < 4; ++m) _Pragma("unroll") for (int k = 0; k < 2; ++k) dst[m][k] = *(const LAS f16x8*)(lds + PG8_SA(b, h) + aoff + m * 2048 + k * 1024); } while (0)
; #define PG8_LDB(dst, b, h) do { _Pragma("unroll") for (int n = 0; n < 2; ++n) _Pragma("unroll") for (int k = 0; k < 2; ++k) dst[n][k] = *(const LAS f16x8*)(lds + PG8_SB(b, h) + boff + n * 2048 + k * 1024); } while (0)
; #define PG8_MMA(ai, bj, At, Bt) do { __builtin_amdgcn_s_setprio(1); _Pragma("unroll") for (int m = 0; m < 4; ++m) _Pragma("unroll") for (int n = 0; n < 2; ++n) _Pragma("unroll") for (int k = 0; k < 2; ++k) \
;         acc[ai][bj][m][n] = MFMA16(Bt[n][k], At[m][k], acc[ai][bj][m][n]); __builtin_amdgcn_s_setprio(0); } while (0)
; #define PG8_WAIT_V(n) asm volatile("s_waitcnt vmcnt(" #n ")" ::: "memory")
; #define PG8_BAR __builtin_amdgcn_s_barrier()
; template <class CF, class Epi, class Sched, bool ALIGN_EPI, bool SP2>
; __device__ __forceinline__ void gemm_phase(LAS unsigned char* lds, const char* gA, const char* gB, const Sched& S, const Epi& E, const char* gB2 = nullptr) {
;     ...
;         for (int t = 0; t < nt; t += 2) {
;             const bool last = (t == nt - 2);
;             const bool tz = BMODE == 1 && !last && (t + 2 >= 4);
;             const char* a1 = cA + (size_t)(t + 1) * akstep;
;             const char* a2 = last ? nA : cA + (size_t)(t + 2) * akstep;
;             const char* b2 = last ? nB : (tz ? cT - (size_t)(t - 2) * 2048 : cB + (size_t)(t + 2) * bkstep);
;             const char* a3 = a2 + akstep; const char* b3 = tz ? b2 - 2048 : b2 + bkstep;
;             PG8_LDB(B0, 0, 0); PG8_LDB(B1, 0, 1); PG8_SCHED; PG8_LDA(At, 0, 0); PG8_STAGE_A(PG8_SA(1, 1), a1 + ahstep);
;             PG8_WAIT_V(8); PG8_WAIT_L(0); PG8_BAR; PG8_MMA(0, 0, At, B0); PG8_MMA(0, 1, At, B1); PG8_BAR; PG8_SCHED;
;             PG8_LDA(At, 0, 1); PG8_STAGE_B(PG8_SB(0, 0), b2, 0, tz); PG8_STAGE_B(PG8_SB(0, 1), b2, 1, tz); PG8_STAGE_A(PG8_SA(0, 0), a2);
;             PG8_WAIT_V(8); PG8_WAIT_L(0); PG8_BAR; PG8_MMA(1, 0, At, B0); PG8_MMA(1, 1, At, B1); PG8_BAR; PG8_SCHED;
.LBB0_296:
	ds_read_b128 v[144:147], v157
	ds_read_b128 v[148:151], v157 offset:1024
	ds_read_b128 v[160:163], v157 offset:2048
	ds_read_b128 v[164:167], v157 offset:3072
	ds_read_b128 v[168:171], v158
	ds_read_b128 v[172:175], v158 offset:1024
	ds_read_b128 v[176:179], v158 offset:2048
	ds_read_b128 v[180:183], v158 offset:3072
	s_add_u32 s64, s62, 0xfff80080
	s_addc_u32 s65, s63, -1
	s_cmp_eq_u32 s57, 28
	s_cselect_b32 s65, s5, s65
	s_cselect_b32 s64, s18, s64
	s_cselect_b32 s71, s19, s21
	s_cselect_b32 s70, s55, s20
	v_lshl_add_u64 v[152:153], s[62:63], 0, v[138:139]
	s_add_i32 m0, s37, 0xc000
	ds_read_b128 v[184:187], v159
	ds_read_b128 v[188:191], v159 offset:1024
	ds_read_b128 v[192:195], v159 offset:2048
	ds_read_b128 v[196:199], v159 offset:3072
	ds_read_b128 v[200:203], v159 offset:4096
	ds_read_b128 v[204:207], v159 offset:5120
	ds_read_b128 v[208:211], v159 offset:6144
	ds_read_b128 v[214:217], v159 offset:7168
	global_load_lds_dwordx4 v[152:153], off
	v_lshl_add_u64 v[152:153], v[152:153], 0, s[10:11]
	s_add_i32 m0, s37, 0xe000
	s_nop 0
	global_load_lds_dwordx4 v[152:153], off
	s_waitcnt vmcnt(8)
	s_waitcnt lgkmcnt(0)
	s_barrier
	s_setprio 1
	s_waitcnt lgkmcnt(0)
	v_mfma_f32_16x16x32_bf16 v[126:129], v[144:147], v[184:187], v[126:129]
	v_mfma_f32_16x16x32_bf16 v[122:125], v[160:163], v[184:187], v[122:125]
	v_mfma_f32_16x16x32_bf16 v[110:113], v[144:147], v[192:195], v[110:113]
	v_mfma_f32_16x16x32_bf16 v[106:109], v[160:163], v[192:195], v[106:109]
	v_mfma_f32_16x16x32_bf16 v[94:97], v[144:147], v[200:203], v[94:97]
	v_mfma_f32_16x16x32_bf16 v[90:93], v[160:163], v[200:203], v[90:93]
	v_mfma_f32_16x16x32_bf16 v[78:81], v[144:147], v[208:211], v[78:81]
	v_mfma_f32_16x16x32_bf16 v[74:77], v[160:163], v[208:211], v[74:77]
	v_mfma_f32_16x16x32_bf16 v[126:129], v[148:151], v[188:191], v[126:129]
	v_mfma_f32_16x16x32_bf16 v[122:125], v[164:167], v[188:191], v[122:125]
	v_mfma_f32_16x16x32_bf16 v[110:113], v[148:151], v[196:199], v[110:113]
	v_mfma_f32_16x16x32_bf16 v[106:109], v[164:167], v[196:199], v[106:109]
	v_mfma_f32_16x16x32_bf16 v[94:97], v[148:151], v[204:207], v[94:97]
	v_mfma_f32_16x16x32_bf16 v[90:93], v[164:167], v[204:207], v[90:93]
	v_mfma_f32_16x16x32_bf16 v[78:81], v[148:151], v[214:217], v[78:81]
	v_mfma_f32_16x16x32_bf16 v[74:77], v[164:167], v[214:217], v[74:77]
	s_setprio 0
	s_setprio 1
	v_mfma_f32_16x16x32_bf16 v[118:121], v[168:171], v[184:187], v[118:121]
	v_mfma_f32_16x16x32_bf16 v[114:117], v[176:179], v[184:187], v[114:117]
	v_mfma_f32_16x16x32_bf16 v[102:105], v[168:171], v[192:195], v[102:105]
	v_mfma_f32_16x16x32_bf16 v[98:101], v[176:179], v[192:195], v[98:101]
	v_mfma_f32_16x16x32_bf16 v[86:89], v[168:171], v[200:203], v[86:89]
	v_mfma_f32_16x16x32_bf16 v[82:85], v[176:179], v[200:203], v[82:85]
	v_mfma_f32_16x16x32_bf16 v[70:73], v[168:171], v[208:211], v[70:73]
	v_mfma_f32_16x16x32_bf16 v[66:69], v[176:179], v[208:211], v[66:69]
	v_mfma_f32_16x16x32_bf16 v[118:121], v[172:175], v[188:191], v[118:121]
	v_mfma_f32_16x16x32_bf16 v[114:117], v[180:183], v[188:191], v[114:117]
	v_mfma_f32_16x16x32_bf16 v[102:105], v[172:175], v[196:199], v[102:105]
	v_mfma_f32_16x16x32_bf16 v[98:101], v[180:183], v[196:199], v[98:101]
	v_mfma_f32_16x16x32_bf16 v[86:89], v[172:175], v[204:207], v[86:89]
	v_mfma_f32_16x16x32_bf16 v[82:85], v[180:183], v[204:207], v[82:85]
	v_mfma_f32_16x16x32_bf16 v[70:73], v[172:175], v[214:217], v[70:73]
	v_mfma_f32_16x16x32_bf16 v[66:69], v[180:183], v[214:217], v[66:69]
	s_setprio 0
	s_barrier
	v_lshl_add_u64 v[152:153], s[70:71], 0, v[134:135]
	s_add_i32 s70, s85, s67
	s_mov_b32 m0, s70
	ds_read_b128 v[184:187], v159 offset:16384
	ds_read_b128 v[188:191], v159 offset:17408
	ds_read_b128 v[192:195], v159 offset:18432
	ds_read_b128 v[196:199], v159 offset:19456
	ds_read_b128 v[200:203], v159 offset:20480
	ds_read_b128 v[204:207], v159 offset:21504
	ds_read_b128 v[208:211], v159 offset:22528
	ds_read_b128 v[214:217], v159 offset:23552
	global_load_lds_dwordx4 v[152:153], off
	v_lshl_add_u64 v[218:219], v[152:153], 0, s[10:11]
	s_add_i32 m0, s70, 0x2000
	s_add_i32 s70, s86, s67
	global_load_lds_dwordx4 v[218:219], off
	v_lshl_add_u64 v[218:219], v[152:153], 0, s[12:13]
	s_mov_b32 m0, s70
	s_nop 0
	global_load_lds_dwordx4 v[218:219], off
	v_lshl_add_u64 v[218:219], v[152:153], 0, s[14:15]
	s_add_i32 m0, s70, 0x2000
	s_nop 0
	global_load_lds_dwordx4 v[218:219], off
	v_lshl_add_u64 v[218:219], s[64:65], 0, v[132:133]
	s_mov_b32 m0, s37
	v_lshl_add_u64 v[220:221], v[218:219], 0, s[10:11]
	global_load_lds_dwordx4 v[218:219], off
	s_mov_b32 m0, s68
	s_nop 0
	global_load_lds_dwordx4 v[220:221], off
	s_waitcnt vmcnt(8)
	s_waitcnt lgkmcnt(0)
	s_barrier
; #define PG8_STAGE_A(bufoff, gbase) PG8_STAGE(bufoff, gbase, voffA, a64)
; #define PG8_LDA(dst, b, h) do { _Pragma("unroll") for (int m = 0; m < 4; ++m) _Pragma("unroll") for (int k = 0; k < 2; ++k) dst[m][k] = *(const LAS f16x8*)(lds + PG8_SA(b, h) + aoff + m * 2048 + k * 1024); } while (0)
; #define PG8_LDB(dst, b, h) do { _Pragma("unroll") for (int n = 0; n < 2; ++n) _Pragma("unroll") for (int k = 0; k < 2; ++k) dst[n][k] = *(const LAS f16x8*)(lds + PG8_SB(b, h) + boff + n * 2048 + k * 1024); } while (0)
; #define PG8_MMA(ai, bj, At, Bt) do { __builtin_amdgcn_s_setprio(1); _Pragma("unroll") for (int m = 0; m < 4; ++m) _Pragma("unroll") for (int n = 0; n < 2; ++n) _Pragma("unroll") for (int k = 0; k < 2; ++k) \
;         acc[ai][bj][m][n] = MFMA16(Bt[n][k], At[m][k], acc[ai][bj][m][n]); __builtin_amdgcn_s_setprio(0); } while (0)
; #define PG8_WAIT_V(n) asm volatile("s_waitcnt vmcnt(" #n ")" ::: "memory")
; #define PG8_WAIT_L(n) asm volatile("s_waitcnt lgkmcnt(" #n ")" ::: "memory")
; #define PG8_BAR __builtin_amdgcn_s_barrier()
; #define PG8_SCHED __builtin_amdgcn_sched_barrier(0)
; template <class CF, class Epi, class Sched, bool ALIGN_EPI, bool SP2>
; __device__ __forceinline__ void gemm_phase(LAS unsigned char* lds, const char* gA, const char* gB, const Sched& S, const Epi& E, const char* gB2 = nullptr) {
;     ...
;             PG8_WAIT_V(8); PG8_WAIT_L(0); PG8_BAR; PG8_MMA(1, 0, At, B0); PG8_MMA(1, 1, At, B1); PG8_BAR; PG8_SCHED;
;             PG8_LDB(B0, 1, 0); PG8_LDB(B1, 1, 1); PG8_SCHED; PG8_LDA(At, 1, 0); PG8_STAGE_A(PG8_SA(0, 1), a2 + ahstep);
;             PG8_WAIT_V(8); PG8_WAIT_L(0); PG8_BAR; PG8_MMA(0, 0, At, B0); PG8_MMA(0, 1, At, B1); PG8_BAR; PG8_SCHED;
	s_setprio 1
	s_waitcnt lgkmcnt(0)
	v_mfma_f32_16x16x32_bf16 v[62:65], v[144:147], v[184:187], v[62:65]
	v_mfma_f32_16x16x32_bf16 v[58:61], v[160:163], v[184:187], v[58:61]
	v_mfma_f32_16x16x32_bf16 v[46:49], v[144:147], v[192:195], v[46:49]
	v_mfma_f32_16x16x32_bf16 v[42:45], v[160:163], v[192:195], v[42:45]
	v_mfma_f32_16x16x32_bf16 v[30:33], v[144:147], v[200:203], v[30:33]
	v_mfma_f32_16x16x32_bf16 v[26:29], v[160:163], v[200:203], v[26:29]
	v_mfma_f32_16x16x32_bf16 v[14:17], v[144:147], v[208:211], v[14:17]
	v_mfma_f32_16x16x32_bf16 v[10:13], v[160:163], v[208:211], v[10:13]
	v_mfma_f32_16x16x32_bf16 v[62:65], v[148:151], v[188:191], v[62:65]
	v_mfma_f32_16x16x32_bf16 v[58:61], v[164:167], v[188:191], v[58:61]
	v_mfma_f32_16x16x32_bf16 v[46:49], v[148:151], v[196:199], v[46:49]
	v_mfma_f32_16x16x32_bf16 v[42:45], v[164:167], v[196:199], v[42:45]
	v_mfma_f32_16x16x32_bf16 v[30:33], v[148:151], v[204:207], v[30:33]
	v_mfma_f32_16x16x32_bf16 v[26:29], v[164:167], v[204:207], v[26:29]
	v_mfma_f32_16x16x32_bf16 v[14:17], v[148:151], v[214:217], v[14:17]
	v_mfma_f32_16x16x32_bf16 v[10:13], v[164:167], v[214:217], v[10:13]
	s_setprio 0
	s_setprio 1
	v_mfma_f32_16x16x32_bf16 v[54:57], v[168:171], v[184:187], v[54:57]
	v_mfma_f32_16x16x32_bf16 v[50:53], v[176:179], v[184:187], v[50:53]
	v_mfma_f32_16x16x32_bf16 v[38:41], v[168:171], v[192:195], v[38:41]
	v_mfma_f32_16x16x32_bf16 v[34:37], v[176:179], v[192:195], v[34:37]
	v_mfma_f32_16x16x32_bf16 v[22:25], v[168:171], v[200:203], v[22:25]
	v_mfma_f32_16x16x32_bf16 v[18:21], v[176:179], v[200:203], v[18:21]
	v_mfma_f32_16x16x32_bf16 v[6:9], v[168:171], v[208:211], v[6:9]
	v_mfma_f32_16x16x32_bf16 v[2:5], v[176:179], v[208:211], v[2:5]
	v_mfma_f32_16x16x32_bf16 v[54:57], v[172:175], v[188:191], v[54:57]
	v_mfma_f32_16x16x32_bf16 v[50:53], v[180:183], v[188:191], v[50:53]
	v_mfma_f32_16x16x32_bf16 v[38:41], v[172:175], v[196:199], v[38:41]
	v_mfma_f32_16x16x32_bf16 v[34:37], v[180:183], v[196:199], v[34:37]
	v_mfma_f32_16x16x32_bf16 v[22:25], v[172:175], v[204:207], v[22:25]
	v_mfma_f32_16x16x32_bf16 v[18:21], v[180:183], v[204:207], v[18:21]
	v_mfma_f32_16x16x32_bf16 v[6:9], v[172:175], v[214:217], v[6:9]
	v_mfma_f32_16x16x32_bf16 v[2:5], v[180:183], v[214:217], v[2:5]
	s_setprio 0
	s_barrier
	s_add_i32 s64, 0, 0x18000
	v_add_u32_e32 v136, s64, v155
	s_add_i32 s65, 0, 0x1c000
	ds_read_b128 v[144:147], v136
	ds_read_b128 v[148:151], v136 offset:1024
	ds_read_b128 v[160:163], v136 offset:2048
	ds_read_b128 v[164:167], v136 offset:3072
	v_add_u32_e32 v136, s65, v155
	ds_read_b128 v[168:171], v136
	ds_read_b128 v[172:175], v136 offset:1024
	ds_read_b128 v[176:179], v136 offset:2048
	ds_read_b128 v[180:183], v136 offset:3072
	s_mov_b32 m0, s69
	v_lshl_add_u64 v[220:221], v[218:219], 0, s[12:13]
	ds_read_b128 v[184:187], v159 offset:32768
	ds_read_b128 v[188:191], v159 offset:33792
	ds_read_b128 v[192:195], v159 offset:34816
	ds_read_b128 v[196:199], v159 offset:35840
	ds_read_b128 v[200:203], v159 offset:36864
	ds_read_b128 v[204:207], v159 offset:37888
	ds_read_b128 v[208:211], v159 offset:38912
	ds_read_b128 v[214:217], v159 offset:39936
	global_load_lds_dwordx4 v[220:221], off
	v_lshl_add_u64 v[220:221], v[218:219], 0, s[14:15]
	s_mov_b32 m0, s78
	s_nop 0
	global_load_lds_dwordx4 v[220:221], off
	s_waitcnt vmcnt(8)
	s_waitcnt lgkmcnt(0)
	s_barrier
	s_setprio 1
	s_waitcnt lgkmcnt(0)
	v_mfma_f32_16x16x32_bf16 v[126:129], v[144:147], v[184:187], v[126:129]
	v_mfma_f32_16x16x32_bf16 v[122:125], v[160:163], v[184:187], v[122:125]
	v_mfma_f32_16x16x32_bf16 v[110:113], v[144:147], v[192:195], v[110:113]
	v_mfma_f32_16x16x32_bf16 v[106:109], v[160:163], v[192:195], v[106:109]
	v_mfma_f32_16x16x32_bf16 v[94:97], v[144:147], v[200:203], v[94:97]
	v_mfma_f32_16x16x32_bf16 v[90:93], v[160:163], v[200:203], v[90:93]
	v_mfma_f32_16x16x32_bf16 v[78:81], v[144:147], v[208:211], v[78:81]
	v_mfma_f32_16x16x32_bf16 v[74:77], v[160:163], v[208:211], v[74:77]
	v_mfma_f32_16x16x32_bf16 v[126:129], v[148:151], v[188:191], v[126:129]
	v_mfma_f32_16x16x32_bf16 v[122:125], v[164:167], v[188:191], v[122:125]
	v_mfma_f32_16x16x32_bf16 v[110:113], v[148:151], v[196:199], v[110:113]
	v_mfma_f32_16x16x32_bf16 v[106:109], v[164:167], v[196:199], v[106:109]
	v_mfma_f32_16x16x32_bf16 v[94:97], v[148:151], v[204:207], v[94:97]
	v_mfma_f32_16x16x32_bf16 v[90:93], v[164:167], v[204:207], v[90:93]
	v_mfma_f32_16x16x32_bf16 v[78:81], v[148:151], v[214:217], v[78:81]
	v_mfma_f32_16x16x32_bf16 v[74:77], v[164:167], v[214:217], v[74:77]
	s_setprio 0
	s_setprio 1
	v_mfma_f32_16x16x32_bf16 v[118:121], v[168:171], v[184:187], v[118:121]
	v_mfma_f32_16x16x32_bf16 v[114:117], v[176:179], v[184:187], v[114:117]
	v_mfma_f32_16x16x32_bf16 v[102:105], v[168:171], v[192:195], v[102:105]
	v_mfma_f32_16x16x32_bf16 v[98:101], v[176:179], v[192:195], v[98:101]
	v_mfma_f32_16x16x32_bf16 v[86:89], v[168:171], v[200:203], v[86:89]
	v_mfma_f32_16x16x32_bf16 v[82:85], v[176:179], v[200:203], v[82:85]
	v_mfma_f32_16x16x32_bf16 v[70:73], v[168:171], v[208:211], v[70:73]
	v_mfma_f32_16x16x32_bf16 v[66:69], v[176:179], v[208:211], v[66:69]
	v_mfma_f32_16x16x32_bf16 v[118:121], v[172:175], v[188:191], v[118:121]
	v_mfma_f32_16x16x32_bf16 v[114:117], v[180:183], v[188:191], v[114:117]
	v_mfma_f32_16x16x32_bf16 v[102:105], v[172:175], v[196:199], v[102:105]
	v_mfma_f32_16x16x32_bf16 v[98:101], v[180:183], v[196:199], v[98:101]
	v_mfma_f32_16x16x32_bf16 v[86:89], v[172:175], v[204:207], v[86:89]
	v_mfma_f32_16x16x32_bf16 v[82:85], v[180:183], v[204:207], v[82:85]
	v_mfma_f32_16x16x32_bf16 v[70:73], v[172:175], v[214:217], v[70:73]
	v_mfma_f32_16x16x32_bf16 v[66:69], v[180:183], v[214:217], v[66:69]
	s_setprio 0
	s_barrier
; #define PG8_STAGE_A(bufoff, gbase) PG8_STAGE(bufoff, gbase, voffA, a64)
; #define PG8_STAGE_B(bufoff, bp, hb, tz) do { if (BMODE == 1 && (tz)) PG8_STAGE(bufoff, (bp) + (hb) * 4096, voffT, t64); else PG8_STAGE(bufoff, (bp) + (hb) * bhstep, voffB, b64); } while (0)
; #define PG8_LDA(dst, b, h) do { _Pragma("unroll") for (int m = 0; m < 4; ++m) _Pragma("unroll") for (int k = 0; k < 2; ++k) dst[m][k] = *(const LAS f16x8*)(lds + PG8_SA(b, h) + aoff + m * 2048 + k * 1024); } while (0)
; #define PG8_LDB(dst, b, h) do { _Pragma("unroll") for (int n = 0; n < 2; ++n) _Pragma("unroll") for (int k = 0; k < 2; ++k) dst[n][k] = *(const LAS f16x8*)(lds + PG8_SB(b, h) + boff + n * 2048 + k * 1024); } while (0)
; #define PG8_MMA(ai, bj, At, Bt) do { __builtin_amdgcn_s_setprio(1); _Pragma("unroll") for (int m = 0; m < 4; ++m) _Pragma("unroll") for (int n = 0; n < 2; ++n) _Pragma("unroll") for (int k = 0; k < 2; ++k) \
;         acc[ai][bj][m][n] = MFMA16(Bt[n][k], At[m][k], acc[ai][bj][m][n]); __builtin_amdgcn_s_setprio(0); } while (0)
; #define PG8_WAIT_V(n) asm volatile("s_waitcnt vmcnt(" #n ")" ::: "memory")
; #define PG8_WAIT_L(n) asm volatile("s_waitcnt lgkmcnt(" #n ")" ::: "memory")
; #define PG8_BAR __builtin_amdgcn_s_barrier()
; #define PG8_SCHED __builtin_amdgcn_sched_barrier(0)
; template <class CF, class Epi, class Sched, bool ALIGN_EPI, bool SP2>
; __device__ __forceinline__ void gemm_phase(LAS unsigned char* lds, const char* gA, const char* gB, const Sched& S, const Epi& E, const char* gB2 = nullptr) {
;     ...
;             PG8_LDB(B0, 1, 0); PG8_LDB(B1, 1, 1); PG8_SCHED; PG8_LDA(At, 1, 0); PG8_STAGE_A(PG8_SA(0, 1), a2 + ahstep);
;             PG8_WAIT_V(8); PG8_WAIT_L(0); PG8_BAR; PG8_MMA(0, 0, At, B0); PG8_MMA(0, 1, At, B1); PG8_BAR; PG8_SCHED;
;             PG8_LDA(At, 1, 1); PG8_STAGE_B(PG8_SB(1, 0), b3, 0, tz); PG8_STAGE_B(PG8_SB(1, 1), b3, 1, tz); PG8_STAGE_A(PG8_SA(1, 0), a3);
;             PG8_WAIT_V(8); PG8_WAIT_L(0); PG8_BAR; PG8_MMA(1, 0, At, B0); PG8_MMA(1, 1, At, B1); PG8_BAR; PG8_SCHED;
;         }
	s_add_i32 s64, s64, s67
	v_lshl_add_u64 v[220:221], v[152:153], 0, s[28:29]
	s_mov_b32 m0, s64
	ds_read_b128 v[184:187], v159 offset:49152
	ds_read_b128 v[188:191], v159 offset:50176
	ds_read_b128 v[192:195], v159 offset:51200
	ds_read_b128 v[196:199], v159 offset:52224
	ds_read_b128 v[200:203], v159 offset:53248
	ds_read_b128 v[204:207], v159 offset:54272
	ds_read_b128 v[208:211], v159 offset:55296
	ds_read_b128 v[214:217], v159 offset:56320
	global_load_lds_dwordx4 v[220:221], off
	v_lshl_add_u64 v[220:221], v[152:153], 0, s[30:31]
	s_add_i32 m0, s64, 0x2000
	s_add_i32 s64, s65, s67
	global_load_lds_dwordx4 v[220:221], off
	v_lshl_add_u64 v[220:221], v[152:153], 0, s[34:35]
	s_mov_b32 m0, s64
	v_lshl_add_u64 v[152:153], v[152:153], 0, s[40:41]
	global_load_lds_dwordx4 v[220:221], off
	s_add_i32 m0, s64, 0x2000
	s_nop 0
	global_load_lds_dwordx4 v[152:153], off
	v_lshl_add_u64 v[152:153], v[218:219], 0, s[28:29]
	s_mov_b32 m0, s80
	s_nop 0
	global_load_lds_dwordx4 v[152:153], off
	v_lshl_add_u64 v[152:153], v[218:219], 0, s[30:31]
	s_mov_b32 m0, s81
	s_nop 0
	global_load_lds_dwordx4 v[152:153], off
	s_waitcnt vmcnt(8)
	s_waitcnt lgkmcnt(0)
	s_barrier
	s_setprio 1
	s_waitcnt lgkmcnt(0)
	v_mfma_f32_16x16x32_bf16 v[62:65], v[144:147], v[184:187], v[62:65]
	v_mfma_f32_16x16x32_bf16 v[58:61], v[160:163], v[184:187], v[58:61]
	v_mfma_f32_16x16x32_bf16 v[46:49], v[144:147], v[192:195], v[46:49]
	v_mfma_f32_16x16x32_bf16 v[42:45], v[160:163], v[192:195], v[42:45]
	v_mfma_f32_16x16x32_bf16 v[30:33], v[144:147], v[200:203], v[30:33]
	v_mfma_f32_16x16x32_bf16 v[26:29], v[160:163], v[200:203], v[26:29]
	v_mfma_f32_16x16x32_bf16 v[14:17], v[144:147], v[208:211], v[14:17]
	v_mfma_f32_16x16x32_bf16 v[10:13], v[160:163], v[208:211], v[10:13]
	v_mfma_f32_16x16x32_bf16 v[62:65], v[148:151], v[188:191], v[62:65]
	v_mfma_f32_16x16x32_bf16 v[58:61], v[164:167], v[188:191], v[58:61]
	v_mfma_f32_16x16x32_bf16 v[46:49], v[148:151], v[196:199], v[46:49]
	v_mfma_f32_16x16x32_bf16 v[42:45], v[164:167], v[196:199], v[42:45]
	v_mfma_f32_16x16x32_bf16 v[30:33], v[148:151], v[204:207], v[30:33]
	v_mfma_f32_16x16x32_bf16 v[26:29], v[164:167], v[204:207], v[26:29]
	v_mfma_f32_16x16x32_bf16 v[14:17], v[148:151], v[214:217], v[14:17]
	v_mfma_f32_16x16x32_bf16 v[10:13], v[164:167], v[214:217], v[10:13]
	s_setprio 0
	s_setprio 1
	v_mfma_f32_16x16x32_bf16 v[54:57], v[168:171], v[184:187], v[54:57]
	v_mfma_f32_16x16x32_bf16 v[50:53], v[176:179], v[184:187], v[50:53]
	v_mfma_f32_16x16x32_bf16 v[38:41], v[168:171], v[192:195], v[38:41]
	v_mfma_f32_16x16x32_bf16 v[34:37], v[176:179], v[192:195], v[34:37]
	v_mfma_f32_16x16x32_bf16 v[22:25], v[168:171], v[200:203], v[22:25]
	v_mfma_f32_16x16x32_bf16 v[18:21], v[176:179], v[200:203], v[18:21]
	v_mfma_f32_16x16x32_bf16 v[6:9], v[168:171], v[208:211], v[6:9]
	v_mfma_f32_16x16x32_bf16 v[2:5], v[176:179], v[208:211], v[2:5]
	v_mfma_f32_16x16x32_bf16 v[54:57], v[172:175], v[188:191], v[54:57]
	v_mfma_f32_16x16x32_bf16 v[50:53], v[180:183], v[188:191], v[50:53]
	v_mfma_f32_16x16x32_bf16 v[38:41], v[172:175], v[196:199], v[38:41]
	v_mfma_f32_16x16x32_bf16 v[34:37], v[180:183], v[196:199], v[34:37]
	v_mfma_f32_16x16x32_bf16 v[22:25], v[172:175], v[204:207], v[22:25]
	v_mfma_f32_16x16x32_bf16 v[18:21], v[180:183], v[204:207], v[18:21]
	v_mfma_f32_16x16x32_bf16 v[6:9], v[172:175], v[214:217], v[6:9]
	v_mfma_f32_16x16x32_bf16 v[2:5], v[180:183], v[214:217], v[2:5]
	s_setprio 0
	s_add_i32 s57, s57, 2
	s_add_u32 s62, s62, 0x100
	s_addc_u32 s63, s63, 0
	s_add_u32 s20, s20, 0x100
	s_addc_u32 s21, s21, 0
	s_cmp_gt_u32 s57, 29
	s_barrier
	s_cbranch_scc0 .LBB0_296
	s_and_b64 vcc, exec, s[44:45]
	s_cbranch_vccz .LBB0_299
	s_barrier

; #define PG8_STAGE_A(bufoff, gbase) PG8_STAGE(bufoff, gbase, voffA, a64)
; #define PG8_STAGE_B(bufoff, bp, hb, tz) do { if (BMODE == 1 && (tz)) PG8_STAGE(bufoff, (bp) + (hb) * 4096, voffT, t64); else PG8_STAGE(bufoff, (bp) + (hb) * bhstep, voffB, b64); } while (0)
; #define PG8_LDA(dst, b, h) do { _Pragma("unroll") for (int m = 0; m < 4; ++m) _Pragma("unroll") for (int k = 0; k < 2; ++k) dst[m][k] = *(const LAS f16x8*)(lds + PG8_SA(b, h) + aoff + m * 2048 + k * 1024); } while (0)
; #define PG8_LDB(dst, b, h) do { _Pragma("unroll") for (int n = 0; n < 2; ++n) _Pragma("unroll") for (int k = 0; k < 2; ++k) dst[n][k] = *(const LAS f16x8*)(lds + PG8_SB(b, h) + boff + n * 2048 + k * 1024); } while (0)
; #define PG8_MMA(ai, bj, At, Bt) do { __builtin_amdgcn_s_setprio(1); _Pragma("unroll") for (int m = 0; m < 4; ++m) _Pragma("unroll") for (int n = 0; n < 2; ++n) _Pragma("unroll") for (int k = 0; k < 2; ++k) \
;         acc[ai][bj][m][n] = MFMA16(Bt[n][k], At[m][k], acc[ai][bj][m][n]); __builtin_amdgcn_s_setprio(0); } while (0)
; #define PG8_WAIT_V(n) asm volatile("s_waitcnt vmcnt(" #n ")" ::: "memory")
; #define PG8_WAIT_L(n) asm volatile("s_waitcnt lgkmcnt(" #n ")" ::: "memory")
; #define PG8_BAR __builtin_amdgcn_s_barrier()
; #define PG8_SCHED __builtin_amdgcn_sched_barrier(0)
; template <class CF, class Epi, class Sched, bool ALIGN_EPI, bool SP2>
; __device__ __forceinline__ void gemm_phase(LAS unsigned char* lds, const char* gA, const char* gB, const Sched& S, const Epi& E, const char* gB2 = nullptr) {
;     ...
;             PG8_LDB(B0, 0, 0); PG8_LDB(B1, 0, 1); PG8_SCHED; PG8_LDA(At, 0, 0); PG8_STAGE_A(PG8_SA(1, 1), a1 + ahstep);
;             PG8_WAIT_V(8); PG8_WAIT_L(0); PG8_BAR; PG8_MMA(0, 0, At, B0); PG8_MMA(0, 1, At, B1); PG8_BAR; PG8_SCHED;
;             PG8_LDA(At, 0, 1); PG8_STAGE_B(PG8_SB(0, 0), b2, 0, tz); PG8_STAGE_B(PG8_SB(0, 1), b2, 1, tz); PG8_STAGE_A(PG8_SA(0, 0), a2);
;             PG8_WAIT_V(8); PG8_WAIT_L(0); PG8_BAR; PG8_MMA(1, 0, At, B0); PG8_MMA(1, 1, At, B1); PG8_BAR; PG8_SCHED;
.LBB0_495:
	ds_read_b128 v[142:145], v137
	ds_read_b128 v[146:149], v137 offset:1024
	ds_read_b128 v[150:153], v137 offset:2048
	ds_read_b128 v[154:157], v137 offset:3072
	ds_read_b128 v[158:161], v138
	ds_read_b128 v[162:165], v138 offset:1024
	ds_read_b128 v[166:169], v138 offset:2048
	ds_read_b128 v[170:173], v138 offset:3072
	s_add_u32 s72, s44, s54
	s_addc_u32 s73, s45, s55
	s_add_u32 s72, s72, 0x6100100
	s_addc_u32 s73, s73, 0
	s_add_u32 s74, s20, s54
	s_addc_u32 s75, s21, s55
	s_cmpk_eq_i32 s54, 0xf00
	s_cselect_b32 s73, s3, s73
	s_cselect_b32 s72, s2, s72
	s_cselect_b32 s75, s5, s75
	s_cselect_b32 s74, s4, s74
	v_lshl_add_u64 v[206:207], v[134:135], 0, s[54:55]
	s_mov_b32 m0, s62
	v_lshl_add_u64 v[208:209], v[206:207], 0, s[56:57]
	ds_read_b128 v[174:177], v139
	ds_read_b128 v[178:181], v139 offset:1024
	ds_read_b128 v[182:185], v139 offset:2048
	ds_read_b128 v[186:189], v139 offset:3072
	ds_read_b128 v[190:193], v139 offset:4096
	ds_read_b128 v[194:197], v139 offset:5120
	ds_read_b128 v[198:201], v139 offset:6144
	ds_read_b128 v[202:205], v139 offset:7168
	global_load_lds_dwordx4 v[208:209], off
	v_lshl_add_u64 v[206:207], v[206:207], 0, s[58:59]
	s_mov_b32 m0, s63
	s_nop 0
	global_load_lds_dwordx4 v[206:207], off
	s_waitcnt vmcnt(8)
	s_waitcnt lgkmcnt(0)
	s_barrier
	s_setprio 1
	s_waitcnt lgkmcnt(0)
	v_mfma_f32_16x16x32_bf16 v[126:129], v[142:145], v[174:177], v[126:129]
	v_mfma_f32_16x16x32_bf16 v[122:125], v[150:153], v[174:177], v[122:125]
	v_mfma_f32_16x16x32_bf16 v[110:113], v[142:145], v[182:185], v[110:113]
	v_mfma_f32_16x16x32_bf16 v[106:109], v[150:153], v[182:185], v[106:109]
	v_mfma_f32_16x16x32_bf16 v[94:97], v[142:145], v[190:193], v[94:97]
	v_mfma_f32_16x16x32_bf16 v[90:93], v[150:153], v[190:193], v[90:93]
	v_mfma_f32_16x16x32_bf16 v[78:81], v[142:145], v[198:201], v[78:81]
	v_mfma_f32_16x16x32_bf16 v[74:77], v[150:153], v[198:201], v[74:77]
	v_mfma_f32_16x16x32_bf16 v[126:129], v[146:149], v[178:181], v[126:129]
	v_mfma_f32_16x16x32_bf16 v[122:125], v[154:157], v[178:181], v[122:125]
	v_mfma_f32_16x16x32_bf16 v[110:113], v[146:149], v[186:189], v[110:113]
	v_mfma_f32_16x16x32_bf16 v[106:109], v[154:157], v[186:189], v[106:109]
	v_mfma_f32_16x16x32_bf16 v[94:97], v[146:149], v[194:197], v[94:97]
	v_mfma_f32_16x16x32_bf16 v[90:93], v[154:157], v[194:197], v[90:93]
	v_mfma_f32_16x16x32_bf16 v[78:81], v[146:149], v[202:205], v[78:81]
	v_mfma_f32_16x16x32_bf16 v[74:77], v[154:157], v[202:205], v[74:77]
	s_setprio 0
	s_setprio 1
	v_mfma_f32_16x16x32_bf16 v[118:121], v[158:161], v[174:177], v[118:121]
	v_mfma_f32_16x16x32_bf16 v[114:117], v[166:169], v[174:177], v[114:117]
	v_mfma_f32_16x16x32_bf16 v[102:105], v[158:161], v[182:185], v[102:105]
	v_mfma_f32_16x16x32_bf16 v[98:101], v[166:169], v[182:185], v[98:101]
	v_mfma_f32_16x16x32_bf16 v[86:89], v[158:161], v[190:193], v[86:89]
	v_mfma_f32_16x16x32_bf16 v[82:85], v[166:169], v[190:193], v[82:85]
	v_mfma_f32_16x16x32_bf16 v[70:73], v[158:161], v[198:201], v[70:73]
	v_mfma_f32_16x16x32_bf16 v[66:69], v[166:169], v[198:201], v[66:69]
	v_mfma_f32_16x16x32_bf16 v[118:121], v[162:165], v[178:181], v[118:121]
	v_mfma_f32_16x16x32_bf16 v[114:117], v[170:173], v[178:181], v[114:117]
	v_mfma_f32_16x16x32_bf16 v[102:105], v[162:165], v[186:189], v[102:105]
	v_mfma_f32_16x16x32_bf16 v[98:101], v[170:173], v[186:189], v[98:101]
	v_mfma_f32_16x16x32_bf16 v[86:89], v[162:165], v[194:197], v[86:89]
	v_mfma_f32_16x16x32_bf16 v[82:85], v[170:173], v[194:197], v[82:85]
	v_mfma_f32_16x16x32_bf16 v[70:73], v[162:165], v[202:205], v[70:73]
	v_mfma_f32_16x16x32_bf16 v[66:69], v[170:173], v[202:205], v[66:69]
	s_setprio 0
	s_barrier
	s_mov_b32 m0, s64
	v_lshl_add_u64 v[206:207], s[74:75], 0, v[130:131]
	ds_read_b128 v[174:177], v139 offset:16384
	ds_read_b128 v[178:181], v139 offset:17408
	ds_read_b128 v[182:185], v139 offset:18432
	ds_read_b128 v[186:189], v139 offset:19456
	ds_read_b128 v[190:193], v139 offset:20480
	ds_read_b128 v[194:197], v139 offset:21504
	ds_read_b128 v[198:201], v139 offset:22528
	ds_read_b128 v[202:205], v139 offset:23552
	global_load_lds_dwordx4 v[206:207], off
	v_lshl_add_u64 v[208:209], v[206:207], 0, s[6:7]
	s_mov_b32 m0, s65
	s_nop 0
	global_load_lds_dwordx4 v[208:209], off
	v_lshl_add_u64 v[208:209], v[206:207], 0, s[8:9]
	s_mov_b32 m0, s66
	s_nop 0
	global_load_lds_dwordx4 v[208:209], off
	v_lshl_add_u64 v[208:209], v[206:207], 0, s[10:11]
	s_mov_b32 m0, s67
	s_nop 0
	global_load_lds_dwordx4 v[208:209], off
	v_lshl_add_u64 v[208:209], s[72:73], 0, v[132:133]
	s_mov_b32 m0, s1
	v_lshl_add_u64 v[210:211], v[208:209], 0, s[6:7]
	global_load_lds_dwordx4 v[208:209], off
	s_mov_b32 m0, s31
	s_nop 0
	global_load_lds_dwordx4 v[210:211], off
	s_waitcnt vmcnt(8)
	s_waitcnt lgkmcnt(0)
	s_barrier
; #define PG8_STAGE_A(bufoff, gbase) PG8_STAGE(bufoff, gbase, voffA, a64)
; #define PG8_LDA(dst, b, h) do { _Pragma("unroll") for (int m = 0; m < 4; ++m) _Pragma("unroll") for (int k = 0; k < 2; ++k) dst[m][k] = *(const LAS f16x8*)(lds + PG8_SA(b, h) + aoff + m * 2048 + k * 1024); } while (0)
; #define PG8_LDB(dst, b, h) do { _Pragma("unroll") for (int n = 0; n < 2; ++n) _Pragma("unroll") for (int k = 0; k < 2; ++k) dst[n][k] = *(const LAS f16x8*)(lds + PG8_SB(b, h) + boff + n * 2048 + k * 1024); } while (0)
; #define PG8_MMA(ai, bj, At, Bt) do { __builtin_amdgcn_s_setprio(1); _Pragma("unroll") for (int m = 0; m < 4; ++m) _Pragma("unroll") for (int n = 0; n < 2; ++n) _Pragma("unroll") for (int k = 0; k < 2; ++k) \
;         acc[ai][bj][m][n] = MFMA16(Bt[n][k], At[m][k], acc[ai][bj][m][n]); __builtin_amdgcn_s_setprio(0); } while (0)
; #define PG8_WAIT_V(n) asm volatile("s_waitcnt vmcnt(" #n ")" ::: "memory")
; #define PG8_WAIT_L(n) asm volatile("s_waitcnt lgkmcnt(" #n ")" ::: "memory")
; #define PG8_BAR __builtin_amdgcn_s_barrier()
; #define PG8_SCHED __builtin_amdgcn_sched_barrier(0)
; template <class CF, class Epi, class Sched, bool ALIGN_EPI, bool SP2>
; __device__ __forceinline__ void gemm_phase(LAS unsigned char* lds, const char* gA, const char* gB, const Sched& S, const Epi& E, const char* gB2 = nullptr) {
;     ...
;             PG8_WAIT_V(8); PG8_WAIT_L(0); PG8_BAR; PG8_MMA(1, 0, At, B0); PG8_MMA(1, 1, At, B1); PG8_BAR; PG8_SCHED;
;             PG8_LDB(B0, 1, 0); PG8_LDB(B1, 1, 1); PG8_SCHED; PG8_LDA(At, 1, 0); PG8_STAGE_A(PG8_SA(0, 1), a2 + ahstep);
;             PG8_WAIT_V(8); PG8_WAIT_L(0); PG8_BAR; PG8_MMA(0, 0, At, B0); PG8_MMA(0, 1, At, B1); PG8_BAR; PG8_SCHED;
	s_setprio 1
	s_waitcnt lgkmcnt(0)
	v_mfma_f32_16x16x32_bf16 v[62:65], v[142:145], v[174:177], v[62:65]
	v_mfma_f32_16x16x32_bf16 v[58:61], v[150:153], v[174:177], v[58:61]
	v_mfma_f32_16x16x32_bf16 v[46:49], v[142:145], v[182:185], v[46:49]
	v_mfma_f32_16x16x32_bf16 v[42:45], v[150:153], v[182:185], v[42:45]
	v_mfma_f32_16x16x32_bf16 v[30:33], v[142:145], v[190:193], v[30:33]
	v_mfma_f32_16x16x32_bf16 v[26:29], v[150:153], v[190:193], v[26:29]
	v_mfma_f32_16x16x32_bf16 v[14:17], v[142:145], v[198:201], v[14:17]
	v_mfma_f32_16x16x32_bf16 v[10:13], v[150:153], v[198:201], v[10:13]
	v_mfma_f32_16x16x32_bf16 v[62:65], v[146:149], v[178:181], v[62:65]
	v_mfma_f32_16x16x32_bf16 v[58:61], v[154:157], v[178:181], v[58:61]
	v_mfma_f32_16x16x32_bf16 v[46:49], v[146:149], v[186:189], v[46:49]
	v_mfma_f32_16x16x32_bf16 v[42:45], v[154:157], v[186:189], v[42:45]
	v_mfma_f32_16x16x32_bf16 v[30:33], v[146:149], v[194:197], v[30:33]
	v_mfma_f32_16x16x32_bf16 v[26:29], v[154:157], v[194:197], v[26:29]
	v_mfma_f32_16x16x32_bf16 v[14:17], v[146:149], v[202:205], v[14:17]
	v_mfma_f32_16x16x32_bf16 v[10:13], v[154:157], v[202:205], v[10:13]
	s_setprio 0
	s_setprio 1
	v_mfma_f32_16x16x32_bf16 v[54:57], v[158:161], v[174:177], v[54:57]
	v_mfma_f32_16x16x32_bf16 v[50:53], v[166:169], v[174:177], v[50:53]
	v_mfma_f32_16x16x32_bf16 v[38:41], v[158:161], v[182:185], v[38:41]
	v_mfma_f32_16x16x32_bf16 v[34:37], v[166:169], v[182:185], v[34:37]
	v_mfma_f32_16x16x32_bf16 v[22:25], v[158:161], v[190:193], v[22:25]
	v_mfma_f32_16x16x32_bf16 v[18:21], v[166:169], v[190:193], v[18:21]
	v_mfma_f32_16x16x32_bf16 v[6:9], v[158:161], v[198:201], v[6:9]
	v_mfma_f32_16x16x32_bf16 v[2:5], v[166:169], v[198:201], v[2:5]
	v_mfma_f32_16x16x32_bf16 v[54:57], v[162:165], v[178:181], v[54:57]
	v_mfma_f32_16x16x32_bf16 v[50:53], v[170:173], v[178:181], v[50:53]
	v_mfma_f32_16x16x32_bf16 v[38:41], v[162:165], v[186:189], v[38:41]
	v_mfma_f32_16x16x32_bf16 v[34:37], v[170:173], v[186:189], v[34:37]
	v_mfma_f32_16x16x32_bf16 v[22:25], v[162:165], v[194:197], v[22:25]
	v_mfma_f32_16x16x32_bf16 v[18:21], v[170:173], v[194:197], v[18:21]
	v_mfma_f32_16x16x32_bf16 v[6:9], v[162:165], v[202:205], v[6:9]
	v_mfma_f32_16x16x32_bf16 v[2:5], v[170:173], v[202:205], v[2:5]
	s_setprio 0
	s_barrier
	ds_read_b128 v[142:145], v140
	ds_read_b128 v[146:149], v140 offset:1024
	ds_read_b128 v[150:153], v140 offset:2048
	ds_read_b128 v[154:157], v140 offset:3072
	ds_read_b128 v[158:161], v141
	ds_read_b128 v[162:165], v141 offset:1024
	ds_read_b128 v[166:169], v141 offset:2048
	ds_read_b128 v[170:173], v141 offset:3072
	s_mov_b32 m0, s33
	v_lshl_add_u64 v[210:211], v[208:209], 0, s[8:9]
	ds_read_b128 v[174:177], v139 offset:32768
	ds_read_b128 v[178:181], v139 offset:33792
	ds_read_b128 v[182:185], v139 offset:34816
	ds_read_b128 v[186:189], v139 offset:35840
	ds_read_b128 v[190:193], v139 offset:36864
	ds_read_b128 v[194:197], v139 offset:37888
	ds_read_b128 v[198:201], v139 offset:38912
	ds_read_b128 v[202:205], v139 offset:39936
	global_load_lds_dwordx4 v[210:211], off
	v_lshl_add_u64 v[210:211], v[208:209], 0, s[10:11]
	s_mov_b32 m0, s35
	s_nop 0
	global_load_lds_dwordx4 v[210:211], off
	s_waitcnt vmcnt(8)
	s_waitcnt lgkmcnt(0)
	s_barrier
	s_setprio 1
	s_waitcnt lgkmcnt(0)
	v_mfma_f32_16x16x32_bf16 v[126:129], v[142:145], v[174:177], v[126:129]
	v_mfma_f32_16x16x32_bf16 v[122:125], v[150:153], v[174:177], v[122:125]
	v_mfma_f32_16x16x32_bf16 v[110:113], v[142:145], v[182:185], v[110:113]
	v_mfma_f32_16x16x32_bf16 v[106:109], v[150:153], v[182:185], v[106:109]
	v_mfma_f32_16x16x32_bf16 v[94:97], v[142:145], v[190:193], v[94:97]
	v_mfma_f32_16x16x32_bf16 v[90:93], v[150:153], v[190:193], v[90:93]
	v_mfma_f32_16x16x32_bf16 v[78:81], v[142:145], v[198:201], v[78:81]
	v_mfma_f32_16x16x32_bf16 v[74:77], v[150:153], v[198:201], v[74:77]
	v_mfma_f32_16x16x32_bf16 v[126:129], v[146:149], v[178:181], v[126:129]
	v_mfma_f32_16x16x32_bf16 v[122:125], v[154:157], v[178:181], v[122:125]
	v_mfma_f32_16x16x32_bf16 v[110:113], v[146:149], v[186:189], v[110:113]
	v_mfma_f32_16x16x32_bf16 v[106:109], v[154:157], v[186:189], v[106:109]
	v_mfma_f32_16x16x32_bf16 v[94:97], v[146:149], v[194:197], v[94:97]
	v_mfma_f32_16x16x32_bf16 v[90:93], v[154:157], v[194:197], v[90:93]
	v_mfma_f32_16x16x32_bf16 v[78:81], v[146:149], v[202:205], v[78:81]
	v_mfma_f32_16x16x32_bf16 v[74:77], v[154:157], v[202:205], v[74:77]
	s_setprio 0
	s_setprio 1
	v_mfma_f32_16x16x32_bf16 v[118:121], v[158:161], v[174:177], v[118:121]
	v_mfma_f32_16x16x32_bf16 v[114:117], v[166:169], v[174:177], v[114:117]
	v_mfma_f32_16x16x32_bf16 v[102:105], v[158:161], v[182:185], v[102:105]
	v_mfma_f32_16x16x32_bf16 v[98:101], v[166:169], v[182:185], v[98:101]
	v_mfma_f32_16x16x32_bf16 v[86:89], v[158:161], v[190:193], v[86:89]
	v_mfma_f32_16x16x32_bf16 v[82:85], v[166:169], v[190:193], v[82:85]
	v_mfma_f32_16x16x32_bf16 v[70:73], v[158:161], v[198:201], v[70:73]
	v_mfma_f32_16x16x32_bf16 v[66:69], v[166:169], v[198:201], v[66:69]
	v_mfma_f32_16x16x32_bf16 v[118:121], v[162:165], v[178:181], v[118:121]
	v_mfma_f32_16x16x32_bf16 v[114:117], v[170:173], v[178:181], v[114:117]
	v_mfma_f32_16x16x32_bf16 v[102:105], v[162:165], v[186:189], v[102:105]
	v_mfma_f32_16x16x32_bf16 v[98:101], v[170:173], v[186:189], v[98:101]
	v_mfma_f32_16x16x32_bf16 v[86:89], v[162:165], v[194:197], v[86:89]
	v_mfma_f32_16x16x32_bf16 v[82:85], v[170:173], v[194:197], v[82:85]
	v_mfma_f32_16x16x32_bf16 v[70:73], v[162:165], v[202:205], v[70:73]
	v_mfma_f32_16x16x32_bf16 v[66:69], v[170:173], v[202:205], v[66:69]
	s_setprio 0
	s_barrier
; #define PG8_STAGE_A(bufoff, gbase) PG8_STAGE(bufoff, gbase, voffA, a64)
; #define PG8_STAGE_B(bufoff, bp, hb, tz) do { if (BMODE == 1 && (tz)) PG8_STAGE(bufoff, (bp) + (hb) * 4096, voffT, t64); else PG8_STAGE(bufoff, (bp) + (hb) * bhstep, voffB, b64); } while (0)
; #define PG8_LDA(dst, b, h) do { _Pragma("unroll") for (int m = 0; m < 4; ++m) _Pragma("unroll") for (int k = 0; k < 2; ++k) dst[m][k] = *(const LAS f16x8*)(lds + PG8_SA(b, h) + aoff + m * 2048 + k * 1024); } while (0)
; #define PG8_LDB(dst, b, h) do { _Pragma("unroll") for (int n = 0; n < 2; ++n) _Pragma("unroll") for (int k = 0; k < 2; ++k) dst[n][k] = *(const LAS f16x8*)(lds + PG8_SB(b, h) + boff + n * 2048 + k * 1024); } while (0)
; #define PG8_MMA(ai, bj, At, Bt) do { __builtin_amdgcn_s_setprio(1); _Pragma("unroll") for (int m = 0; m < 4; ++m) _Pragma("unroll") for (int n = 0; n < 2; ++n) _Pragma("unroll") for (int k = 0; k < 2; ++k) \
;         acc[ai][bj][m][n] = MFMA16(Bt[n][k], At[m][k], acc[ai][bj][m][n]); __builtin_amdgcn_s_setprio(0); } while (0)
; #define PG8_WAIT_V(n) asm volatile("s_waitcnt vmcnt(" #n ")" ::: "memory")
; #define PG8_WAIT_L(n) asm volatile("s_waitcnt lgkmcnt(" #n ")" ::: "memory")
; #define PG8_BAR __builtin_amdgcn_s_barrier()
; #define PG8_SCHED __builtin_amdgcn_sched_barrier(0)
; template <class CF, class Epi, class Sched, bool ALIGN_EPI, bool SP2>
; __device__ __forceinline__ void gemm_phase(LAS unsigned char* lds, const char* gA, const char* gB, const Sched& S, const Epi& E, const char* gB2 = nullptr) {
;     ...
;             PG8_LDB(B0, 1, 0); PG8_LDB(B1, 1, 1); PG8_SCHED; PG8_LDA(At, 1, 0); PG8_STAGE_A(PG8_SA(0, 1), a2 + ahstep);
;             PG8_WAIT_V(8); PG8_WAIT_L(0); PG8_BAR; PG8_MMA(0, 0, At, B0); PG8_MMA(0, 1, At, B1); PG8_BAR; PG8_SCHED;
;             PG8_LDA(At, 1, 1); PG8_STAGE_B(PG8_SB(1, 0), b3, 0, tz); PG8_STAGE_B(PG8_SB(1, 1), b3, 1, tz); PG8_STAGE_A(PG8_SA(1, 0), a3);
;             PG8_WAIT_V(8); PG8_WAIT_L(0); PG8_BAR; PG8_MMA(1, 0, At, B0); PG8_MMA(1, 1, At, B1); PG8_BAR; PG8_SCHED;
;         }
	s_mov_b32 m0, s68
	v_lshl_add_u64 v[210:211], v[206:207], 0, s[12:13]
	ds_read_b128 v[174:177], v139 offset:49152
	ds_read_b128 v[178:181], v139 offset:50176
	ds_read_b128 v[182:185], v139 offset:51200
	ds_read_b128 v[186:189], v139 offset:52224
	ds_read_b128 v[190:193], v139 offset:53248
	ds_read_b128 v[194:197], v139 offset:54272
	ds_read_b128 v[198:201], v139 offset:55296
	ds_read_b128 v[202:205], v139 offset:56320
	global_load_lds_dwordx4 v[210:211], off
	v_lshl_add_u64 v[210:211], v[206:207], 0, s[14:15]
	s_mov_b32 m0, s69
	s_nop 0
	global_load_lds_dwordx4 v[210:211], off
	v_lshl_add_u64 v[210:211], v[206:207], 0, s[36:37]
	s_mov_b32 m0, s70
	v_lshl_add_u64 v[206:207], v[206:207], 0, s[40:41]
	global_load_lds_dwordx4 v[210:211], off
	s_mov_b32 m0, s71
	s_nop 0
	global_load_lds_dwordx4 v[206:207], off
	v_lshl_add_u64 v[206:207], v[208:209], 0, s[12:13]
	s_mov_b32 m0, s18
	s_nop 0
	global_load_lds_dwordx4 v[206:207], off
	v_lshl_add_u64 v[206:207], v[208:209], 0, s[14:15]
	s_mov_b32 m0, s19
	s_nop 0
	global_load_lds_dwordx4 v[206:207], off
	s_waitcnt vmcnt(8)
	s_waitcnt lgkmcnt(0)
	s_barrier
	s_setprio 1
	s_waitcnt lgkmcnt(0)
	v_mfma_f32_16x16x32_bf16 v[62:65], v[142:145], v[174:177], v[62:65]
	v_mfma_f32_16x16x32_bf16 v[58:61], v[150:153], v[174:177], v[58:61]
	v_mfma_f32_16x16x32_bf16 v[46:49], v[142:145], v[182:185], v[46:49]
	v_mfma_f32_16x16x32_bf16 v[42:45], v[150:153], v[182:185], v[42:45]
	v_mfma_f32_16x16x32_bf16 v[30:33], v[142:145], v[190:193], v[30:33]
	v_mfma_f32_16x16x32_bf16 v[26:29], v[150:153], v[190:193], v[26:29]
	v_mfma_f32_16x16x32_bf16 v[14:17], v[142:145], v[198:201], v[14:17]
	v_mfma_f32_16x16x32_bf16 v[10:13], v[150:153], v[198:201], v[10:13]
	v_mfma_f32_16x16x32_bf16 v[62:65], v[146:149], v[178:181], v[62:65]
	v_mfma_f32_16x16x32_bf16 v[58:61], v[154:157], v[178:181], v[58:61]
	v_mfma_f32_16x16x32_bf16 v[46:49], v[146:149], v[186:189], v[46:49]
	v_mfma_f32_16x16x32_bf16 v[42:45], v[154:157], v[186:189], v[42:45]
	v_mfma_f32_16x16x32_bf16 v[30:33], v[146:149], v[194:197], v[30:33]
	v_mfma_f32_16x16x32_bf16 v[26:29], v[154:157], v[194:197], v[26:29]
	v_mfma_f32_16x16x32_bf16 v[14:17], v[146:149], v[202:205], v[14:17]
	v_mfma_f32_16x16x32_bf16 v[10:13], v[154:157], v[202:205], v[10:13]
	s_setprio 0
	s_setprio 1
	v_mfma_f32_16x16x32_bf16 v[54:57], v[158:161], v[174:177], v[54:57]
	v_mfma_f32_16x16x32_bf16 v[50:53], v[166:169], v[174:177], v[50:53]
	v_mfma_f32_16x16x32_bf16 v[38:41], v[158:161], v[182:185], v[38:41]
	v_mfma_f32_16x16x32_bf16 v[34:37], v[166:169], v[182:185], v[34:37]
	v_mfma_f32_16x16x32_bf16 v[22:25], v[158:161], v[190:193], v[22:25]
	v_mfma_f32_16x16x32_bf16 v[18:21], v[166:169], v[190:193], v[18:21]
	v_mfma_f32_16x16x32_bf16 v[6:9], v[158:161], v[198:201], v[6:9]
	v_mfma_f32_16x16x32_bf16 v[2:5], v[166:169], v[198:201], v[2:5]
	v_mfma_f32_16x16x32_bf16 v[54:57], v[162:165], v[178:181], v[54:57]
	v_mfma_f32_16x16x32_bf16 v[50:53], v[170:173], v[178:181], v[50:53]
	v_mfma_f32_16x16x32_bf16 v[38:41], v[162:165], v[186:189], v[38:41]
	v_mfma_f32_16x16x32_bf16 v[34:37], v[170:173], v[186:189], v[34:37]
	v_mfma_f32_16x16x32_bf16 v[22:25], v[162:165], v[194:197], v[22:25]
	v_mfma_f32_16x16x32_bf16 v[18:21], v[170:173], v[194:197], v[18:21]
	v_mfma_f32_16x16x32_bf16 v[6:9], v[162:165], v[202:205], v[6:9]
	v_mfma_f32_16x16x32_bf16 v[2:5], v[170:173], v[202:205], v[2:5]
	s_setprio 0
	s_add_i32 s61, s61, 2
	s_add_u32 s54, s54, 0x100
	s_addc_u32 s55, s55, 0
	s_cmp_gt_u32 s61, 29
	s_barrier
	s_cbranch_scc0 .LBB0_495
	s_cmpk_lt_u32 s0, 0x100
	s_cbranch_scc0 .LBB0_498
	s_barrier

; #define PG8_STAGE_A(bufoff, gbase) PG8_STAGE(bufoff, gbase, voffA, a64)
; #define PG8_STAGE_B(bufoff, bp, hb, tz) do { if (BMODE == 1 && (tz)) PG8_STAGE(bufoff, (bp) + (hb) * 4096, voffT, t64); else PG8_STAGE(bufoff, (bp) + (hb) * bhstep, voffB, b64); } while (0)
; #define PG8_LDA(dst, b, h) do { _Pragma("unroll") for (int m = 0; m < 4; ++m) _Pragma("unroll") for (int k = 0; k < 2; ++k) dst[m][k] = *(const LAS f16x8*)(lds + PG8_SA(b, h) + aoff + m * 2048 + k * 1024); } while (0)
; #define PG8_LDB(dst, b, h) do { _Pragma("unroll") for (int n = 0; n < 2; ++n) _Pragma("unroll") for (int k = 0; k < 2; ++k) dst[n][k] = *(const LAS f16x8*)(lds + PG8_SB(b, h) + boff + n * 2048 + k * 1024); } while (0)
; #define PG8_MMA(ai, bj, At, Bt) do { __builtin_amdgcn_s_setprio(1); _Pragma("unroll") for (int m = 0; m < 4; ++m) _Pragma("unroll") for (int n = 0; n < 2; ++n) _Pragma("unroll") for (int k = 0; k < 2; ++k) \
;         acc[ai][bj][m][n] = MFMA16(Bt[n][k], At[m][k], acc[ai][bj][m][n]); __builtin_amdgcn_s_setprio(0); } while (0)
; #define PG8_WAIT_V(n) asm volatile("s_waitcnt vmcnt(" #n ")" ::: "memory")
; #define PG8_WAIT_L(n) asm volatile("s_waitcnt lgkmcnt(" #n ")" ::: "memory")
; #define PG8_BAR __builtin_amdgcn_s_barrier()
; #define PG8_SCHED __builtin_amdgcn_sched_barrier(0)
; template <class CF, class Epi, class Sched, bool ALIGN_EPI, bool SP2>
; __device__ __forceinline__ void gemm_phase(LAS unsigned char* lds, const char* gA, const char* gB, const Sched& S, const Epi& E, const char* gB2 = nullptr) {
;     ...
;             PG8_LDB(B0, 0, 0); PG8_LDB(B1, 0, 1); PG8_SCHED; PG8_LDA(At, 0, 0); PG8_STAGE_A(PG8_SA(1, 1), a1 + ahstep);
;             PG8_WAIT_V(8); PG8_WAIT_L(0); PG8_BAR; PG8_MMA(0, 0, At, B0); PG8_MMA(0, 1, At, B1); PG8_BAR; PG8_SCHED;
;             PG8_LDA(At, 0, 1); PG8_STAGE_B(PG8_SB(0, 0), b2, 0, tz); PG8_STAGE_B(PG8_SB(0, 1), b2, 1, tz); PG8_STAGE_A(PG8_SA(0, 0), a2);
;             PG8_WAIT_V(8); PG8_WAIT_L(0); PG8_BAR; PG8_MMA(1, 0, At, B0); PG8_MMA(1, 1, At, B1); PG8_BAR; PG8_SCHED;
.LBB0_864:
	ds_read_b128 v[138:141], v152
	ds_read_b128 v[156:159], v152 offset:1024
	ds_read_b128 v[160:163], v152 offset:2048
	ds_read_b128 v[164:167], v152 offset:3072
	ds_read_b128 v[168:171], v153
	ds_read_b128 v[172:175], v153 offset:1024
	ds_read_b128 v[176:179], v153 offset:2048
	ds_read_b128 v[180:183], v153 offset:3072
	s_add_u32 s71, s82, 0xfffd0080
	s_addc_u32 s72, s83, -1
	s_cmp_eq_u32 s65, 4
	s_cselect_b32 s73, s79, s72
	s_cselect_b32 s72, s78, s71
	s_cselect_b32 s75, s18, s21
	s_cselect_b32 s74, s19, s20
	v_lshl_add_u64 v[220:221], s[82:83], 0, v[136:137]
	s_add_i32 m0, s94, 0xc000
	ds_read_b128 v[184:187], v154
	ds_read_b128 v[188:191], v154 offset:1024
	ds_read_b128 v[192:195], v154 offset:2048
	ds_read_b128 v[196:199], v154 offset:3072
	ds_read_b128 v[200:203], v154 offset:4096
	ds_read_b128 v[204:207], v154 offset:5120
	ds_read_b128 v[208:211], v154 offset:6144
	ds_read_b128 v[216:219], v154 offset:7168
	global_load_lds_dwordx4 v[220:221], off
	v_lshl_add_u64 v[220:221], v[220:221], 0, s[14:15]
	s_add_i32 m0, s94, 0xe000
	s_nop 0
	global_load_lds_dwordx4 v[220:221], off
	s_waitcnt vmcnt(8)
	s_waitcnt lgkmcnt(0)
	s_barrier
	s_setprio 1
	s_waitcnt lgkmcnt(0)
	v_mfma_f32_16x16x32_bf16 v[126:129], v[138:141], v[184:187], v[126:129]
	v_mfma_f32_16x16x32_bf16 v[122:125], v[160:163], v[184:187], v[122:125]
	v_mfma_f32_16x16x32_bf16 v[118:121], v[138:141], v[192:195], v[118:121]
	v_mfma_f32_16x16x32_bf16 v[110:113], v[160:163], v[192:195], v[110:113]
	v_mfma_f32_16x16x32_bf16 v[102:105], v[138:141], v[200:203], v[102:105]
	v_mfma_f32_16x16x32_bf16 v[94:97], v[160:163], v[200:203], v[94:97]
	v_mfma_f32_16x16x32_bf16 v[86:89], v[138:141], v[208:211], v[86:89]
	v_mfma_f32_16x16x32_bf16 v[78:81], v[160:163], v[208:211], v[78:81]
	v_mfma_f32_16x16x32_bf16 v[126:129], v[156:159], v[188:191], v[126:129]
	v_mfma_f32_16x16x32_bf16 v[122:125], v[164:167], v[188:191], v[122:125]
	v_mfma_f32_16x16x32_bf16 v[118:121], v[156:159], v[196:199], v[118:121]
	v_mfma_f32_16x16x32_bf16 v[110:113], v[164:167], v[196:199], v[110:113]
	v_mfma_f32_16x16x32_bf16 v[102:105], v[156:159], v[204:207], v[102:105]
	v_mfma_f32_16x16x32_bf16 v[94:97], v[164:167], v[204:207], v[94:97]
	v_mfma_f32_16x16x32_bf16 v[86:89], v[156:159], v[216:219], v[86:89]
	v_mfma_f32_16x16x32_bf16 v[78:81], v[164:167], v[216:219], v[78:81]
	s_setprio 0
	s_setprio 1
	v_mfma_f32_16x16x32_bf16 v[114:117], v[168:171], v[184:187], v[114:117]
	v_mfma_f32_16x16x32_bf16 v[106:109], v[176:179], v[184:187], v[106:109]
	v_mfma_f32_16x16x32_bf16 v[98:101], v[168:171], v[192:195], v[98:101]
	v_mfma_f32_16x16x32_bf16 v[90:93], v[176:179], v[192:195], v[90:93]
	v_mfma_f32_16x16x32_bf16 v[82:85], v[168:171], v[200:203], v[82:85]
	v_mfma_f32_16x16x32_bf16 v[74:77], v[176:179], v[200:203], v[74:77]
	v_mfma_f32_16x16x32_bf16 v[70:73], v[168:171], v[208:211], v[70:73]
	v_mfma_f32_16x16x32_bf16 v[66:69], v[176:179], v[208:211], v[66:69]
	v_mfma_f32_16x16x32_bf16 v[114:117], v[172:175], v[188:191], v[114:117]
	v_mfma_f32_16x16x32_bf16 v[106:109], v[180:183], v[188:191], v[106:109]
	v_mfma_f32_16x16x32_bf16 v[98:101], v[172:175], v[196:199], v[98:101]
	v_mfma_f32_16x16x32_bf16 v[90:93], v[180:183], v[196:199], v[90:93]
	v_mfma_f32_16x16x32_bf16 v[82:85], v[172:175], v[204:207], v[82:85]
	v_mfma_f32_16x16x32_bf16 v[74:77], v[180:183], v[204:207], v[74:77]
	v_mfma_f32_16x16x32_bf16 v[70:73], v[172:175], v[216:219], v[70:73]
	v_mfma_f32_16x16x32_bf16 v[66:69], v[180:183], v[216:219], v[66:69]
	s_setprio 0
	s_barrier
	s_add_i32 s71, s87, s35
	v_lshl_add_u64 v[220:221], s[74:75], 0, v[134:135]
	s_mov_b32 m0, s71
	ds_read_b128 v[184:187], v154 offset:16384
	ds_read_b128 v[188:191], v154 offset:17408
	ds_read_b128 v[192:195], v154 offset:18432
	ds_read_b128 v[196:199], v154 offset:19456
	ds_read_b128 v[200:203], v154 offset:20480
	ds_read_b128 v[204:207], v154 offset:21504
	ds_read_b128 v[208:211], v154 offset:22528
	ds_read_b128 v[216:219], v154 offset:23552
	global_load_lds_dwordx4 v[220:221], off
	v_lshl_add_u64 v[222:223], v[220:221], 0, s[4:5]
	s_add_i32 m0, s71, 0x2000
	s_add_i32 s71, s88, s35
	global_load_lds_dwordx4 v[222:223], off
	v_lshl_add_u64 v[222:223], v[220:221], 0, s[6:7]
	s_mov_b32 m0, s71
	s_nop 0
	global_load_lds_dwordx4 v[222:223], off
	v_lshl_add_u64 v[222:223], v[220:221], 0, s[12:13]
	s_add_i32 m0, s71, 0x2000
	s_nop 0
	global_load_lds_dwordx4 v[222:223], off
	v_lshl_add_u64 v[222:223], s[72:73], 0, v[130:131]
	s_mov_b32 m0, s94
	v_lshl_add_u64 v[224:225], v[222:223], 0, s[14:15]
	global_load_lds_dwordx4 v[222:223], off
	s_mov_b32 m0, s95
	s_nop 0
	global_load_lds_dwordx4 v[224:225], off
	s_waitcnt vmcnt(8)
	s_waitcnt lgkmcnt(0)
	s_barrier
; #define PG8_STAGE_A(bufoff, gbase) PG8_STAGE(bufoff, gbase, voffA, a64)
; #define PG8_STAGE_B(bufoff, bp, hb, tz) do { if (BMODE == 1 && (tz)) PG8_STAGE(bufoff, (bp) + (hb) * 4096, voffT, t64); else PG8_STAGE(bufoff, (bp) + (hb) * bhstep, voffB, b64); } while (0)
; #define PG8_LDA(dst, b, h) do { _Pragma("unroll") for (int m = 0; m < 4; ++m) _Pragma("unroll") for (int k = 0; k < 2; ++k) dst[m][k] = *(const LAS f16x8*)(lds + PG8_SA(b, h) + aoff + m * 2048 + k * 1024); } while (0)
; #define PG8_LDB(dst, b, h) do { _Pragma("unroll") for (int n = 0; n < 2; ++n) _Pragma("unroll") for (int k = 0; k < 2; ++k) dst[n][k] = *(const LAS f16x8*)(lds + PG8_SB(b, h) + boff + n * 2048 + k * 1024); } while (0)
; #define PG8_MMA(ai, bj, At, Bt) do { __builtin_amdgcn_s_setprio(1); _Pragma("unroll") for (int m = 0; m < 4; ++m) _Pragma("unroll") for (int n = 0; n < 2; ++n) _Pragma("unroll") for (int k = 0; k < 2; ++k) \
;         acc[ai][bj][m][n] = MFMA16(Bt[n][k], At[m][k], acc[ai][bj][m][n]); __builtin_amdgcn_s_setprio(0); } while (0)
; #define PG8_WAIT_V(n) asm volatile("s_waitcnt vmcnt(" #n ")" ::: "memory")
; #define PG8_WAIT_L(n) asm volatile("s_waitcnt lgkmcnt(" #n ")" ::: "memory")
; #define PG8_BAR __builtin_amdgcn_s_barrier()
; template <class CF, class Epi, class Sched, bool ALIGN_EPI, bool SP2>
; __device__ __forceinline__ void gemm_phase(LAS unsigned char* lds, const char* gA, const char* gB, const Sched& S, const Epi& E, const char* gB2 = nullptr) {
;     ...
;             PG8_WAIT_V(8); PG8_WAIT_L(0); PG8_BAR; PG8_MMA(0, 0, At, B0); PG8_MMA(0, 1, At, B1); PG8_BAR; PG8_SCHED;
;             PG8_LDA(At, 0, 1); PG8_STAGE_B(PG8_SB(0, 0), b2, 0, tz); PG8_STAGE_B(PG8_SB(0, 1), b2, 1, tz); PG8_STAGE_A(PG8_SA(0, 0), a2);
;             PG8_WAIT_V(8); PG8_WAIT_L(0); PG8_BAR; PG8_MMA(1, 0, At, B0); PG8_MMA(1, 1, At, B1); PG8_BAR; PG8_SCHED;
;             PG8_LDB(B0, 1, 0); PG8_LDB(B1, 1, 1); PG8_SCHED; PG8_LDA(At, 1, 0); PG8_STAGE_A(PG8_SA(0, 1), a2 + ahstep);
;             PG8_WAIT_V(8); PG8_WAIT_L(0); PG8_BAR; PG8_MMA(0, 0, At, B0); PG8_MMA(0, 1, At, B1); PG8_BAR; PG8_SCHED;
;             PG8_LDA(At, 1, 1); PG8_STAGE_B(PG8_SB(1, 0), b3, 0, tz); PG8_STAGE_B(PG8_SB(1, 1), b3, 1, tz); PG8_STAGE_A(PG8_SA(1, 0), a3);
;             PG8_WAIT_V(8); PG8_WAIT_L(0); PG8_BAR; PG8_MMA(1, 0, At, B0); PG8_MMA(1, 1, At, B1); PG8_BAR; PG8_SCHED;
	s_setprio 1
	s_waitcnt lgkmcnt(0)
	v_mfma_f32_16x16x32_bf16 v[62:65], v[138:141], v[184:187], v[62:65]
	v_mfma_f32_16x16x32_bf16 v[58:61], v[160:163], v[184:187], v[58:61]
	v_mfma_f32_16x16x32_bf16 v[54:57], v[138:141], v[192:195], v[54:57]
	v_mfma_f32_16x16x32_bf16 v[46:49], v[160:163], v[192:195], v[46:49]
	v_mfma_f32_16x16x32_bf16 v[38:41], v[138:141], v[200:203], v[38:41]
	v_mfma_f32_16x16x32_bf16 v[30:33], v[160:163], v[200:203], v[30:33]
	v_mfma_f32_16x16x32_bf16 v[22:25], v[138:141], v[208:211], v[22:25]
	v_mfma_f32_16x16x32_bf16 v[14:17], v[160:163], v[208:211], v[14:17]
	v_mfma_f32_16x16x32_bf16 v[62:65], v[156:159], v[188:191], v[62:65]
	v_mfma_f32_16x16x32_bf16 v[58:61], v[164:167], v[188:191], v[58:61]
	v_mfma_f32_16x16x32_bf16 v[54:57], v[156:159], v[196:199], v[54:57]
	v_mfma_f32_16x16x32_bf16 v[46:49], v[164:167], v[196:199], v[46:49]
	v_mfma_f32_16x16x32_bf16 v[38:41], v[156:159], v[204:207], v[38:41]
	v_mfma_f32_16x16x32_bf16 v[30:33], v[164:167], v[204:207], v[30:33]
	v_mfma_f32_16x16x32_bf16 v[22:25], v[156:159], v[216:219], v[22:25]
	v_mfma_f32_16x16x32_bf16 v[14:17], v[164:167], v[216:219], v[14:17]
	s_setprio 0
	s_setprio 1
	v_mfma_f32_16x16x32_bf16 v[50:53], v[168:171], v[184:187], v[50:53]
	v_mfma_f32_16x16x32_bf16 v[42:45], v[176:179], v[184:187], v[42:45]
	v_mfma_f32_16x16x32_bf16 v[34:37], v[168:171], v[192:195], v[34:37]
	v_mfma_f32_16x16x32_bf16 v[26:29], v[176:179], v[192:195], v[26:29]
	v_mfma_f32_16x16x32_bf16 v[18:21], v[168:171], v[200:203], v[18:21]
	v_mfma_f32_16x16x32_bf16 v[10:13], v[176:179], v[200:203], v[10:13]
	v_mfma_f32_16x16x32_bf16 v[6:9], v[168:171], v[208:211], v[6:9]
	v_mfma_f32_16x16x32_bf16 v[2:5], v[176:179], v[208:211], v[2:5]
	v_mfma_f32_16x16x32_bf16 v[50:53], v[172:175], v[188:191], v[50:53]
	v_mfma_f32_16x16x32_bf16 v[42:45], v[180:183], v[188:191], v[42:45]
	v_mfma_f32_16x16x32_bf16 v[34:37], v[172:175], v[196:199], v[34:37]
	v_mfma_f32_16x16x32_bf16 v[26:29], v[180:183], v[196:199], v[26:29]
	v_mfma_f32_16x16x32_bf16 v[18:21], v[172:175], v[204:207], v[18:21]
	v_mfma_f32_16x16x32_bf16 v[10:13], v[180:183], v[204:207], v[10:13]
	v_mfma_f32_16x16x32_bf16 v[6:9], v[172:175], v[216:219], v[6:9]
	v_mfma_f32_16x16x32_bf16 v[2:5], v[180:183], v[216:219], v[2:5]
	s_setprio 0
	s_barrier
	s_add_i32 s71, 0, 0x18000
	v_add_u32_e32 v155, s71, v150
	s_add_i32 s72, 0, 0x1c000
	ds_read_b128 v[138:141], v155
	ds_read_b128 v[156:159], v155 offset:1024
	ds_read_b128 v[160:163], v155 offset:2048
	ds_read_b128 v[164:167], v155 offset:3072
	v_add_u32_e32 v155, s72, v150
	ds_read_b128 v[168:171], v155
	ds_read_b128 v[172:175], v155 offset:1024
	ds_read_b128 v[176:179], v155 offset:2048
	ds_read_b128 v[180:183], v155 offset:3072
	s_mov_b32 m0, s96
	v_lshl_add_u64 v[224:225], v[222:223], 0, s[12:13]
	ds_read_b128 v[184:187], v154 offset:32768
	ds_read_b128 v[188:191], v154 offset:33792
	ds_read_b128 v[192:195], v154 offset:34816
	ds_read_b128 v[196:199], v154 offset:35840
	ds_read_b128 v[200:203], v154 offset:36864
	ds_read_b128 v[204:207], v154 offset:37888
	ds_read_b128 v[208:211], v154 offset:38912
	ds_read_b128 v[216:219], v154 offset:39936
	global_load_lds_dwordx4 v[224:225], off
	v_lshl_add_u64 v[224:225], v[222:223], 0, s[36:37]
	s_mov_b32 m0, s97
	s_nop 0
	global_load_lds_dwordx4 v[224:225], off
	s_waitcnt vmcnt(8)
	s_waitcnt lgkmcnt(0)
	s_barrier
	s_setprio 1
	s_waitcnt lgkmcnt(0)
	v_mfma_f32_16x16x32_bf16 v[126:129], v[138:141], v[184:187], v[126:129]
	v_mfma_f32_16x16x32_bf16 v[122:125], v[160:163], v[184:187], v[122:125]
	v_mfma_f32_16x16x32_bf16 v[118:121], v[138:141], v[192:195], v[118:121]
	v_mfma_f32_16x16x32_bf16 v[110:113], v[160:163], v[192:195], v[110:113]
	v_mfma_f32_16x16x32_bf16 v[102:105], v[138:141], v[200:203], v[102:105]
	v_mfma_f32_16x16x32_bf16 v[94:97], v[160:163], v[200:203], v[94:97]
	v_mfma_f32_16x16x32_bf16 v[86:89], v[138:141], v[208:211], v[86:89]
	v_mfma_f32_16x16x32_bf16 v[78:81], v[160:163], v[208:211], v[78:81]
	v_mfma_f32_16x16x32_bf16 v[126:129], v[156:159], v[188:191], v[126:129]
	v_mfma_f32_16x16x32_bf16 v[122:125], v[164:167], v[188:191], v[122:125]
	v_mfma_f32_16x16x32_bf16 v[118:121], v[156:159], v[196:199], v[118:121]
	v_mfma_f32_16x16x32_bf16 v[110:113], v[164:167], v[196:199], v[110:113]
	v_mfma_f32_16x16x32_bf16 v[102:105], v[156:159], v[204:207], v[102:105]
	v_mfma_f32_16x16x32_bf16 v[94:97], v[164:167], v[204:207], v[94:97]
	v_mfma_f32_16x16x32_bf16 v[86:89], v[156:159], v[216:219], v[86:89]
	v_mfma_f32_16x16x32_bf16 v[78:81], v[164:167], v[216:219], v[78:81]
	s_setprio 0
	s_setprio 1
	v_mfma_f32_16x16x32_bf16 v[114:117], v[168:171], v[184:187], v[114:117]
	v_mfma_f32_16x16x32_bf16 v[106:109], v[176:179], v[184:187], v[106:109]
	v_mfma_f32_16x16x32_bf16 v[98:101], v[168:171], v[192:195], v[98:101]
	v_mfma_f32_16x16x32_bf16 v[90:93], v[176:179], v[192:195], v[90:93]
	v_mfma_f32_16x16x32_bf16 v[82:85], v[168:171], v[200:203], v[82:85]
	v_mfma_f32_16x16x32_bf16 v[74:77], v[176:179], v[200:203], v[74:77]
	v_mfma_f32_16x16x32_bf16 v[70:73], v[168:171], v[208:211], v[70:73]
	v_mfma_f32_16x16x32_bf16 v[66:69], v[176:179], v[208:211], v[66:69]
	v_mfma_f32_16x16x32_bf16 v[114:117], v[172:175], v[188:191], v[114:117]
	v_mfma_f32_16x16x32_bf16 v[106:109], v[180:183], v[188:191], v[106:109]
	v_mfma_f32_16x16x32_bf16 v[98:101], v[172:175], v[196:199], v[98:101]
	v_mfma_f32_16x16x32_bf16 v[90:93], v[180:183], v[196:199], v[90:93]
	v_mfma_f32_16x16x32_bf16 v[82:85], v[172:175], v[204:207], v[82:85]
	v_mfma_f32_16x16x32_bf16 v[74:77], v[180:183], v[204:207], v[74:77]
	v_mfma_f32_16x16x32_bf16 v[70:73], v[172:175], v[216:219], v[70:73]
	v_mfma_f32_16x16x32_bf16 v[66:69], v[180:183], v[216:219], v[66:69]
	s_setprio 0
	s_barrier
; #define PG8_STAGE_A(bufoff, gbase) PG8_STAGE(bufoff, gbase, voffA, a64)
; #define PG8_STAGE_B(bufoff, bp, hb, tz) do { if (BMODE == 1 && (tz)) PG8_STAGE(bufoff, (bp) + (hb) * 4096, voffT, t64); else PG8_STAGE(bufoff, (bp) + (hb) * bhstep, voffB, b64); } while (0)
; #define PG8_LDA(dst, b, h) do { _Pragma("unroll") for (int m = 0; m < 4; ++m) _Pragma("unroll") for (int k = 0; k < 2; ++k) dst[m][k] = *(const LAS f16x8*)(lds + PG8_SA(b, h) + aoff + m * 2048 + k * 1024); } while (0)
; #define PG8_LDB(dst, b, h) do { _Pragma("unroll") for (int n = 0; n < 2; ++n) _Pragma("unroll") for (int k = 0; k < 2; ++k) dst[n][k] = *(const LAS f16x8*)(lds + PG8_SB(b, h) + boff + n * 2048 + k * 1024); } while (0)
; #define PG8_MMA(ai, bj, At, Bt) do { __builtin_amdgcn_s_setprio(1); _Pragma("unroll") for (int m = 0; m < 4; ++m) _Pragma("unroll") for (int n = 0; n < 2; ++n) _Pragma("unroll") for (int k = 0; k < 2; ++k) \
;         acc[ai][bj][m][n] = MFMA16(Bt[n][k], At[m][k], acc[ai][bj][m][n]); __builtin_amdgcn_s_setprio(0); } while (0)
; #define PG8_WAIT_V(n) asm volatile("s_waitcnt vmcnt(" #n ")" ::: "memory")
; #define PG8_WAIT_L(n) asm volatile("s_waitcnt lgkmcnt(" #n ")" ::: "memory")
; #define PG8_BAR __builtin_amdgcn_s_barrier()
; template <class CF, class Epi, class Sched, bool ALIGN_EPI, bool SP2>
; __device__ __forceinline__ void gemm_phase(LAS unsigned char* lds, const char* gA, const char* gB, const Sched& S, const Epi& E, const char* gB2 = nullptr) {
;     ...
;             PG8_WAIT_V(8); PG8_WAIT_L(0); PG8_BAR; PG8_MMA(0, 0, At, B0); PG8_MMA(0, 1, At, B1); PG8_BAR; PG8_SCHED;
;             PG8_LDA(At, 0, 1); PG8_STAGE_B(PG8_SB(0, 0), b2, 0, tz); PG8_STAGE_B(PG8_SB(0, 1), b2, 1, tz); PG8_STAGE_A(PG8_SA(0, 0), a2);
;             PG8_WAIT_V(8); PG8_WAIT_L(0); PG8_BAR; PG8_MMA(1, 0, At, B0); PG8_MMA(1, 1, At, B1); PG8_BAR; PG8_SCHED;
;             PG8_LDB(B0, 1, 0); PG8_LDB(B1, 1, 1); PG8_SCHED; PG8_LDA(At, 1, 0); PG8_STAGE_A(PG8_SA(0, 1), a2 + ahstep);
;             PG8_WAIT_V(8); PG8_WAIT_L(0); PG8_BAR; PG8_MMA(0, 0, At, B0); PG8_MMA(0, 1, At, B1); PG8_BAR; PG8_SCHED;
;             PG8_LDA(At, 1, 1); PG8_STAGE_B(PG8_SB(1, 0), b3, 0, tz); PG8_STAGE_B(PG8_SB(1, 1), b3, 1, tz); PG8_STAGE_A(PG8_SA(1, 0), a3);
;             PG8_WAIT_V(8); PG8_WAIT_L(0); PG8_BAR; PG8_MMA(1, 0, At, B0); PG8_MMA(1, 1, At, B1); PG8_BAR; PG8_SCHED;
	s_add_i32 s71, s71, s35
	v_lshl_add_u64 v[224:225], v[220:221], 0, s[44:45]
	s_mov_b32 m0, s71
	ds_read_b128 v[184:187], v154 offset:49152
	ds_read_b128 v[188:191], v154 offset:50176
	ds_read_b128 v[192:195], v154 offset:51200
	ds_read_b128 v[196:199], v154 offset:52224
	ds_read_b128 v[200:203], v154 offset:53248
	ds_read_b128 v[204:207], v154 offset:54272
	ds_read_b128 v[208:211], v154 offset:55296
	ds_read_b128 v[216:219], v154 offset:56320
	global_load_lds_dwordx4 v[224:225], off
	v_lshl_add_u64 v[224:225], v[220:221], 0, s[54:55]
	s_add_i32 m0, s71, 0x2000
	s_add_i32 s71, s72, s35
	global_load_lds_dwordx4 v[224:225], off
	v_lshl_add_u64 v[224:225], v[220:221], 0, s[58:59]
	s_mov_b32 m0, s71
	v_lshl_add_u64 v[220:221], v[220:221], 0, s[60:61]
	global_load_lds_dwordx4 v[224:225], off
	s_add_i32 m0, s71, 0x2000
	s_nop 0
	global_load_lds_dwordx4 v[220:221], off
	v_lshl_add_u64 v[220:221], v[222:223], 0, s[44:45]
	s_mov_b32 m0, s92
	s_nop 0
	global_load_lds_dwordx4 v[220:221], off
	v_lshl_add_u64 v[220:221], v[222:223], 0, s[56:57]
	s_mov_b32 m0, s93
	s_nop 0
	global_load_lds_dwordx4 v[220:221], off
	s_waitcnt vmcnt(8)
	s_waitcnt lgkmcnt(0)
	s_barrier
	s_setprio 1
	s_waitcnt lgkmcnt(0)
	v_mfma_f32_16x16x32_bf16 v[62:65], v[138:141], v[184:187], v[62:65]
	v_mfma_f32_16x16x32_bf16 v[58:61], v[160:163], v[184:187], v[58:61]
	v_mfma_f32_16x16x32_bf16 v[54:57], v[138:141], v[192:195], v[54:57]
	v_mfma_f32_16x16x32_bf16 v[46:49], v[160:163], v[192:195], v[46:49]
	v_mfma_f32_16x16x32_bf16 v[38:41], v[138:141], v[200:203], v[38:41]
	v_mfma_f32_16x16x32_bf16 v[30:33], v[160:163], v[200:203], v[30:33]
	v_mfma_f32_16x16x32_bf16 v[22:25], v[138:141], v[208:211], v[22:25]
	v_mfma_f32_16x16x32_bf16 v[14:17], v[160:163], v[208:211], v[14:17]
	v_mfma_f32_16x16x32_bf16 v[62:65], v[156:159], v[188:191], v[62:65]
	v_mfma_f32_16x16x32_bf16 v[58:61], v[164:167], v[188:191], v[58:61]
	v_mfma_f32_16x16x32_bf16 v[54:57], v[156:159], v[196:199], v[54:57]
	v_mfma_f32_16x16x32_bf16 v[46:49], v[164:167], v[196:199], v[46:49]
	v_mfma_f32_16x16x32_bf16 v[38:41], v[156:159], v[204:207], v[38:41]
	v_mfma_f32_16x16x32_bf16 v[30:33], v[164:167], v[204:207], v[30:33]
	v_mfma_f32_16x16x32_bf16 v[22:25], v[156:159], v[216:219], v[22:25]
	v_mfma_f32_16x16x32_bf16 v[14:17], v[164:167], v[216:219], v[14:17]
	s_setprio 0
	s_setprio 1
	v_mfma_f32_16x16x32_bf16 v[50:53], v[168:171], v[184:187], v[50:53]
	v_mfma_f32_16x16x32_bf16 v[42:45], v[176:179], v[184:187], v[42:45]
	v_mfma_f32_16x16x32_bf16 v[34:37], v[168:171], v[192:195], v[34:37]
	v_mfma_f32_16x16x32_bf16 v[26:29], v[176:179], v[192:195], v[26:29]
	v_mfma_f32_16x16x32_bf16 v[18:21], v[168:171], v[200:203], v[18:21]
	v_mfma_f32_16x16x32_bf16 v[10:13], v[176:179], v[200:203], v[10:13]
	v_mfma_f32_16x16x32_bf16 v[6:9], v[168:171], v[208:211], v[6:9]
	v_mfma_f32_16x16x32_bf16 v[2:5], v[176:179], v[208:211], v[2:5]
	v_mfma_f32_16x16x32_bf16 v[50:53], v[172:175], v[188:191], v[50:53]
	v_mfma_f32_16x16x32_bf16 v[42:45], v[180:183], v[188:191], v[42:45]
	v_mfma_f32_16x16x32_bf16 v[34:37], v[172:175], v[196:199], v[34:37]
	v_mfma_f32_16x16x32_bf16 v[26:29], v[180:183], v[196:199], v[26:29]
	v_mfma_f32_16x16x32_bf16 v[18:21], v[172:175], v[204:207], v[18:21]
	v_mfma_f32_16x16x32_bf16 v[10:13], v[180:183], v[204:207], v[10:13]
	v_mfma_f32_16x16x32_bf16 v[6:9], v[172:175], v[216:219], v[6:9]
	v_mfma_f32_16x16x32_bf16 v[2:5], v[180:183], v[216:219], v[2:5]
	s_setprio 0
	s_add_i32 s65, s65, 2
	s_add_u32 s82, s82, 0x100
	s_addc_u32 s83, s83, 0
	s_add_u32 s20, s20, 0x100
	s_addc_u32 s21, s21, 0
	s_cmp_gt_u32 s65, 5
	s_barrier
	s_cbranch_scc0 .LBB0_864
	s_and_b64 vcc, exec, s[62:63]
	s_cbranch_vccz .LBB0_867
	s_barrier

;     __device__ bool next(int i, Unit& u) const { const int L = i * G + vc; if (L >= n) return false; u.g = L / (npm * npn); u.pm = (L / npn) % npm; u.pn = L % npn; return true; }
; #define PG8_STAGE_A(bufoff, gbase) PG8_STAGE(bufoff, gbase, voffA, a64)
; #define PG8_STAGE_B(bufoff, bp, hb, tz) do { if (BMODE == 1 && (tz)) PG8_STAGE(bufoff, (bp) + (hb) * 4096, voffT, t64); else PG8_STAGE(bufoff, (bp) + (hb) * bhstep, voffB, b64); } while (0)
; #define PG8_LDA(dst, b, h) do { _Pragma("unroll") for (int m = 0; m < 4; ++m) _Pragma("unroll") for (int k = 0; k < 2; ++k) dst[m][k] = *(const LAS f16x8*)(lds + PG8_SA(b, h) + aoff + m * 2048 + k * 1024); } while (0)
; #define PG8_LDB(dst, b, h) do { _Pragma("unroll") for (int n = 0; n < 2; ++n) _Pragma("unroll") for (int k = 0; k < 2; ++k) dst[n][k] = *(const LAS f16x8*)(lds + PG8_SB(b, h) + boff + n * 2048 + k * 1024); } while (0)
; #define PG8_WAIT_V(n) asm volatile("s_waitcnt vmcnt(" #n ")" ::: "memory")
; #define PG8_WAIT_L(n) asm volatile("s_waitcnt lgkmcnt(" #n ")" ::: "memory")
; template <class CF, class Epi, class Sched, bool ALIGN_EPI, bool SP2>
; __device__ __forceinline__ void gemm_phase(LAS unsigned char* lds, const char* gA, const char* gB, const Sched& S, const Epi& E, const char* gB2 = nullptr) {
;     ...
;         const bool has_next = S.next(ui + 1, nxt);
;         const char* nA = has_next ? gA + (size_t)nxt.g * CF::A_G + (size_t)nxt.pm * CF::A_T : cA; const char* nB = has_next ? gB + (size_t)nxt.g * CF::B_G + (size_t)nxt.pn * CF::B_T : cB;
;         for (int t = 0; t < nt; t += 2) {
;             const bool last = (t == nt - 2);
;             const bool tz = BMODE == 1 && !last && (t + 2 >= 4);
;             const char* a1 = cA + (size_t)(t + 1) * akstep;
;             const char* a2 = last ? nA : cA + (size_t)(t + 2) * akstep;
;             const char* b2 = last ? nB : (tz ? cT - (size_t)(t - 2) * 2048 : cB + (size_t)(t + 2) * bkstep);
;             const char* a3 = a2 + akstep; const char* b3 = tz ? b2 - 2048 : b2 + bkstep;
;             PG8_LDB(B0, 0, 0); PG8_LDB(B1, 0, 1); PG8_SCHED; PG8_LDA(At, 0, 0); PG8_STAGE_A(PG8_SA(1, 1), a1 + ahstep);
;             PG8_WAIT_V(8); PG8_WAIT_L(0); PG8_BAR; PG8_MMA(0, 0, At, B0); PG8_MMA(0, 1, At, B1); PG8_BAR; PG8_SCHED;
;             PG8_LDA(At, 0, 1); PG8_STAGE_B(PG8_SB(0, 0), b2, 0, tz); PG8_STAGE_B(PG8_SB(0, 1), b2, 1, tz); PG8_STAGE_A(PG8_SA(0, 0), a2);
.LBB0_969:
	ds_read_b128 v[144:147], v138
	ds_read_b128 v[148:151], v138 offset:1024
	ds_read_b128 v[152:155], v138 offset:2048
	ds_read_b128 v[156:159], v138 offset:3072
	ds_read_b128 v[160:163], v139
	ds_read_b128 v[164:167], v139 offset:1024
	ds_read_b128 v[168:171], v139 offset:2048
	ds_read_b128 v[172:175], v139 offset:3072
	s_add_u32 s73, s44, s54
	s_addc_u32 s74, s45, s55
	s_add_u32 s73, s73, 0x6100100
	s_addc_u32 s74, s74, 0
	s_add_u32 s76, s20, s54
	s_addc_u32 s77, s21, s55
	s_cmpk_eq_i32 s54, 0xf00
	s_cselect_b32 s75, s3, s74
	s_cselect_b32 s74, s2, s73
	s_cselect_b32 s77, s5, s77
	s_cselect_b32 s76, s4, s76
	v_lshl_add_u64 v[208:209], v[132:133], 0, s[54:55]
	s_mov_b32 m0, s63
	v_lshl_add_u64 v[210:211], v[208:209], 0, s[56:57]
	ds_read_b128 v[176:179], v140
	ds_read_b128 v[180:183], v140 offset:1024
	ds_read_b128 v[184:187], v140 offset:2048
	ds_read_b128 v[188:191], v140 offset:3072
	ds_read_b128 v[192:195], v140 offset:4096
	ds_read_b128 v[196:199], v140 offset:5120
	ds_read_b128 v[200:203], v140 offset:6144
	ds_read_b128 v[204:207], v140 offset:7168
	global_load_lds_dwordx4 v[210:211], off
	v_lshl_add_u64 v[208:209], v[208:209], 0, s[58:59]
	s_mov_b32 m0, s64
	s_nop 0
	global_load_lds_dwordx4 v[208:209], off
	s_waitcnt vmcnt(8)
	s_waitcnt lgkmcnt(0)
	s_barrier
	s_setprio 1
	s_waitcnt lgkmcnt(0)
	v_mfma_f32_16x16x32_bf16 v[126:129], v[144:147], v[176:179], v[126:129]
	v_mfma_f32_16x16x32_bf16 v[122:125], v[152:155], v[176:179], v[122:125]
	v_mfma_f32_16x16x32_bf16 v[110:113], v[144:147], v[184:187], v[110:113]
	v_mfma_f32_16x16x32_bf16 v[106:109], v[152:155], v[184:187], v[106:109]
	v_mfma_f32_16x16x32_bf16 v[94:97], v[144:147], v[192:195], v[94:97]
	v_mfma_f32_16x16x32_bf16 v[90:93], v[152:155], v[192:195], v[90:93]
	v_mfma_f32_16x16x32_bf16 v[78:81], v[144:147], v[200:203], v[78:81]
	v_mfma_f32_16x16x32_bf16 v[74:77], v[152:155], v[200:203], v[74:77]
	v_mfma_f32_16x16x32_bf16 v[126:129], v[148:151], v[180:183], v[126:129]
	v_mfma_f32_16x16x32_bf16 v[122:125], v[156:159], v[180:183], v[122:125]
	v_mfma_f32_16x16x32_bf16 v[110:113], v[148:151], v[188:191], v[110:113]
	v_mfma_f32_16x16x32_bf16 v[106:109], v[156:159], v[188:191], v[106:109]
	v_mfma_f32_16x16x32_bf16 v[94:97], v[148:151], v[196:199], v[94:97]
	v_mfma_f32_16x16x32_bf16 v[90:93], v[156:159], v[196:199], v[90:93]
	v_mfma_f32_16x16x32_bf16 v[78:81], v[148:151], v[204:207], v[78:81]
	v_mfma_f32_16x16x32_bf16 v[74:77], v[156:159], v[204:207], v[74:77]
	s_setprio 0
	s_setprio 1
	v_mfma_f32_16x16x32_bf16 v[118:121], v[160:163], v[176:179], v[118:121]
	v_mfma_f32_16x16x32_bf16 v[114:117], v[168:171], v[176:179], v[114:117]
	v_mfma_f32_16x16x32_bf16 v[102:105], v[160:163], v[184:187], v[102:105]
	v_mfma_f32_16x16x32_bf16 v[98:101], v[168:171], v[184:187], v[98:101]
	v_mfma_f32_16x16x32_bf16 v[86:89], v[160:163], v[192:195], v[86:89]
	v_mfma_f32_16x16x32_bf16 v[82:85], v[168:171], v[192:195], v[82:85]
	v_mfma_f32_16x16x32_bf16 v[70:73], v[160:163], v[200:203], v[70:73]
	v_mfma_f32_16x16x32_bf16 v[66:69], v[168:171], v[200:203], v[66:69]
	v_mfma_f32_16x16x32_bf16 v[118:121], v[164:167], v[180:183], v[118:121]
	v_mfma_f32_16x16x32_bf16 v[114:117], v[172:175], v[180:183], v[114:117]
	v_mfma_f32_16x16x32_bf16 v[102:105], v[164:167], v[188:191], v[102:105]
	v_mfma_f32_16x16x32_bf16 v[98:101], v[172:175], v[188:191], v[98:101]
	v_mfma_f32_16x16x32_bf16 v[86:89], v[164:167], v[196:199], v[86:89]
	v_mfma_f32_16x16x32_bf16 v[82:85], v[172:175], v[196:199], v[82:85]
	v_mfma_f32_16x16x32_bf16 v[70:73], v[164:167], v[204:207], v[70:73]
	v_mfma_f32_16x16x32_bf16 v[66:69], v[172:175], v[204:207], v[66:69]
	s_setprio 0
	s_barrier
	s_mov_b32 m0, s65
	v_lshl_add_u64 v[208:209], s[76:77], 0, v[134:135]
	ds_read_b128 v[176:179], v140 offset:16384
	ds_read_b128 v[180:183], v140 offset:17408
	ds_read_b128 v[184:187], v140 offset:18432
	ds_read_b128 v[188:191], v140 offset:19456
	ds_read_b128 v[192:195], v140 offset:20480
	ds_read_b128 v[196:199], v140 offset:21504
	ds_read_b128 v[200:203], v140 offset:22528
	ds_read_b128 v[204:207], v140 offset:23552
	global_load_lds_dwordx4 v[208:209], off
	v_lshl_add_u64 v[210:211], v[208:209], 0, s[6:7]
	s_mov_b32 m0, s66
	s_nop 0
	global_load_lds_dwordx4 v[210:211], off
	v_lshl_add_u64 v[210:211], v[208:209], 0, s[10:11]
	s_mov_b32 m0, s67
	s_nop 0
	global_load_lds_dwordx4 v[210:211], off
	v_lshl_add_u64 v[210:211], v[208:209], 0, s[12:13]
	s_mov_b32 m0, s68
	s_nop 0
	global_load_lds_dwordx4 v[210:211], off
	v_lshl_add_u64 v[210:211], s[74:75], 0, v[136:137]
	s_mov_b32 m0, s1
	v_lshl_add_u64 v[220:221], v[210:211], 0, s[6:7]
	global_load_lds_dwordx4 v[210:211], off
	s_mov_b32 m0, s31
	s_nop 0
	global_load_lds_dwordx4 v[220:221], off
	s_waitcnt vmcnt(8)
	s_waitcnt lgkmcnt(0)
	s_barrier
; #define PG8_STAGE_A(bufoff, gbase) PG8_STAGE(bufoff, gbase, voffA, a64)
; #define PG8_STAGE_B(bufoff, bp, hb, tz) do { if (BMODE == 1 && (tz)) PG8_STAGE(bufoff, (bp) + (hb) * 4096, voffT, t64); else PG8_STAGE(bufoff, (bp) + (hb) * bhstep, voffB, b64); } while (0)
; #define PG8_LDA(dst, b, h) do { _Pragma("unroll") for (int m = 0; m < 4; ++m) _Pragma("unroll") for (int k = 0; k < 2; ++k) dst[m][k] = *(const LAS f16x8*)(lds + PG8_SA(b, h) + aoff + m * 2048 + k * 1024); } while (0)
; #define PG8_LDB(dst, b, h) do { _Pragma("unroll") for (int n = 0; n < 2; ++n) _Pragma("unroll") for (int k = 0; k < 2; ++k) dst[n][k] = *(const LAS f16x8*)(lds + PG8_SB(b, h) + boff + n * 2048 + k * 1024); } while (0)
; #define PG8_MMA(ai, bj, At, Bt) do { __builtin_amdgcn_s_setprio(1); _Pragma("unroll") for (int m = 0; m < 4; ++m) _Pragma("unroll") for (int n = 0; n < 2; ++n) _Pragma("unroll") for (int k = 0; k < 2; ++k) \
;         acc[ai][bj][m][n] = MFMA16(Bt[n][k], At[m][k], acc[ai][bj][m][n]); __builtin_amdgcn_s_setprio(0); } while (0)
; #define PG8_WAIT_V(n) asm volatile("s_waitcnt vmcnt(" #n ")" ::: "memory")
; #define PG8_WAIT_L(n) asm volatile("s_waitcnt lgkmcnt(" #n ")" ::: "memory")
; #define PG8_BAR __builtin_amdgcn_s_barrier()
; #define PG8_SCHED __builtin_amdgcn_sched_barrier(0)
; template <class CF, class Epi, class Sched, bool ALIGN_EPI, bool SP2>
; __device__ __forceinline__ void gemm_phase(LAS unsigned char* lds, const char* gA, const char* gB, const Sched& S, const Epi& E, const char* gB2 = nullptr) {
;     ...
;             PG8_LDA(At, 0, 1); PG8_STAGE_B(PG8_SB(0, 0), b2, 0, tz); PG8_STAGE_B(PG8_SB(0, 1), b2, 1, tz); PG8_STAGE_A(PG8_SA(0, 0), a2);
;             PG8_WAIT_V(8); PG8_WAIT_L(0); PG8_BAR; PG8_MMA(1, 0, At, B0); PG8_MMA(1, 1, At, B1); PG8_BAR; PG8_SCHED;
;             PG8_LDB(B0, 1, 0); PG8_LDB(B1, 1, 1); PG8_SCHED; PG8_LDA(At, 1, 0); PG8_STAGE_A(PG8_SA(0, 1), a2 + ahstep);
;             PG8_WAIT_V(8); PG8_WAIT_L(0); PG8_BAR; PG8_MMA(0, 0, At, B0); PG8_MMA(0, 1, At, B1); PG8_BAR; PG8_SCHED;
	s_setprio 1
	s_waitcnt lgkmcnt(0)
	v_mfma_f32_16x16x32_bf16 v[62:65], v[144:147], v[176:179], v[62:65]
	v_mfma_f32_16x16x32_bf16 v[58:61], v[152:155], v[176:179], v[58:61]
	v_mfma_f32_16x16x32_bf16 v[46:49], v[144:147], v[184:187], v[46:49]
	v_mfma_f32_16x16x32_bf16 v[42:45], v[152:155], v[184:187], v[42:45]
	v_mfma_f32_16x16x32_bf16 v[30:33], v[144:147], v[192:195], v[30:33]
	v_mfma_f32_16x16x32_bf16 v[26:29], v[152:155], v[192:195], v[26:29]
	v_mfma_f32_16x16x32_bf16 v[14:17], v[144:147], v[200:203], v[14:17]
	v_mfma_f32_16x16x32_bf16 v[10:13], v[152:155], v[200:203], v[10:13]
	v_mfma_f32_16x16x32_bf16 v[62:65], v[148:151], v[180:183], v[62:65]
	v_mfma_f32_16x16x32_bf16 v[58:61], v[156:159], v[180:183], v[58:61]
	v_mfma_f32_16x16x32_bf16 v[46:49], v[148:151], v[188:191], v[46:49]
	v_mfma_f32_16x16x32_bf16 v[42:45], v[156:159], v[188:191], v[42:45]
	v_mfma_f32_16x16x32_bf16 v[30:33], v[148:151], v[196:199], v[30:33]
	v_mfma_f32_16x16x32_bf16 v[26:29], v[156:159], v[196:199], v[26:29]
	v_mfma_f32_16x16x32_bf16 v[14:17], v[148:151], v[204:207], v[14:17]
	v_mfma_f32_16x16x32_bf16 v[10:13], v[156:159], v[204:207], v[10:13]
	s_setprio 0
	s_setprio 1
	v_mfma_f32_16x16x32_bf16 v[54:57], v[160:163], v[176:179], v[54:57]
	v_mfma_f32_16x16x32_bf16 v[50:53], v[168:171], v[176:179], v[50:53]
	v_mfma_f32_16x16x32_bf16 v[38:41], v[160:163], v[184:187], v[38:41]
	v_mfma_f32_16x16x32_bf16 v[34:37], v[168:171], v[184:187], v[34:37]
	v_mfma_f32_16x16x32_bf16 v[22:25], v[160:163], v[192:195], v[22:25]
	v_mfma_f32_16x16x32_bf16 v[18:21], v[168:171], v[192:195], v[18:21]
	v_mfma_f32_16x16x32_bf16 v[6:9], v[160:163], v[200:203], v[6:9]
	v_mfma_f32_16x16x32_bf16 v[2:5], v[168:171], v[200:203], v[2:5]
	v_mfma_f32_16x16x32_bf16 v[54:57], v[164:167], v[180:183], v[54:57]
	v_mfma_f32_16x16x32_bf16 v[50:53], v[172:175], v[180:183], v[50:53]
	v_mfma_f32_16x16x32_bf16 v[38:41], v[164:167], v[188:191], v[38:41]
	v_mfma_f32_16x16x32_bf16 v[34:37], v[172:175], v[188:191], v[34:37]
	v_mfma_f32_16x16x32_bf16 v[22:25], v[164:167], v[196:199], v[22:25]
	v_mfma_f32_16x16x32_bf16 v[18:21], v[172:175], v[196:199], v[18:21]
	v_mfma_f32_16x16x32_bf16 v[6:9], v[164:167], v[204:207], v[6:9]
	v_mfma_f32_16x16x32_bf16 v[2:5], v[172:175], v[204:207], v[2:5]
	s_setprio 0
	s_barrier
	ds_read_b128 v[144:147], v141
	ds_read_b128 v[148:151], v141 offset:1024
	ds_read_b128 v[152:155], v141 offset:2048
	ds_read_b128 v[156:159], v141 offset:3072
	ds_read_b128 v[160:163], v142
	ds_read_b128 v[164:167], v142 offset:1024
	ds_read_b128 v[168:171], v142 offset:2048
	ds_read_b128 v[172:175], v142 offset:3072
	s_mov_b32 m0, s33
	v_lshl_add_u64 v[220:221], v[210:211], 0, s[10:11]
	ds_read_b128 v[176:179], v140 offset:32768
	ds_read_b128 v[180:183], v140 offset:33792
	ds_read_b128 v[184:187], v140 offset:34816
	ds_read_b128 v[188:191], v140 offset:35840
	ds_read_b128 v[192:195], v140 offset:36864
	ds_read_b128 v[196:199], v140 offset:37888
	ds_read_b128 v[200:203], v140 offset:38912
	ds_read_b128 v[204:207], v140 offset:39936
	global_load_lds_dwordx4 v[220:221], off
	v_lshl_add_u64 v[220:221], v[210:211], 0, s[12:13]
	s_mov_b32 m0, s60
	s_nop 0
	global_load_lds_dwordx4 v[220:221], off
	s_waitcnt vmcnt(8)
	s_waitcnt lgkmcnt(0)
	s_barrier
	s_setprio 1
	s_waitcnt lgkmcnt(0)
	v_mfma_f32_16x16x32_bf16 v[126:129], v[144:147], v[176:179], v[126:129]
	v_mfma_f32_16x16x32_bf16 v[122:125], v[152:155], v[176:179], v[122:125]
	v_mfma_f32_16x16x32_bf16 v[110:113], v[144:147], v[184:187], v[110:113]
	v_mfma_f32_16x16x32_bf16 v[106:109], v[152:155], v[184:187], v[106:109]
	v_mfma_f32_16x16x32_bf16 v[94:97], v[144:147], v[192:195], v[94:97]
	v_mfma_f32_16x16x32_bf16 v[90:93], v[152:155], v[192:195], v[90:93]
	v_mfma_f32_16x16x32_bf16 v[78:81], v[144:147], v[200:203], v[78:81]
	v_mfma_f32_16x16x32_bf16 v[74:77], v[152:155], v[200:203], v[74:77]
	v_mfma_f32_16x16x32_bf16 v[126:129], v[148:151], v[180:183], v[126:129]
	v_mfma_f32_16x16x32_bf16 v[122:125], v[156:159], v[180:183], v[122:125]
	v_mfma_f32_16x16x32_bf16 v[110:113], v[148:151], v[188:191], v[110:113]
	v_mfma_f32_16x16x32_bf16 v[106:109], v[156:159], v[188:191], v[106:109]
	v_mfma_f32_16x16x32_bf16 v[94:97], v[148:151], v[196:199], v[94:97]
	v_mfma_f32_16x16x32_bf16 v[90:93], v[156:159], v[196:199], v[90:93]
	v_mfma_f32_16x16x32_bf16 v[78:81], v[148:151], v[204:207], v[78:81]
	v_mfma_f32_16x16x32_bf16 v[74:77], v[156:159], v[204:207], v[74:77]
	s_setprio 0
	s_setprio 1
	v_mfma_f32_16x16x32_bf16 v[118:121], v[160:163], v[176:179], v[118:121]
	v_mfma_f32_16x16x32_bf16 v[114:117], v[168:171], v[176:179], v[114:117]
	v_mfma_f32_16x16x32_bf16 v[102:105], v[160:163], v[184:187], v[102:105]
	v_mfma_f32_16x16x32_bf16 v[98:101], v[168:171], v[184:187], v[98:101]
	v_mfma_f32_16x16x32_bf16 v[86:89], v[160:163], v[192:195], v[86:89]
	v_mfma_f32_16x16x32_bf16 v[82:85], v[168:171], v[192:195], v[82:85]
	v_mfma_f32_16x16x32_bf16 v[70:73], v[160:163], v[200:203], v[70:73]
	v_mfma_f32_16x16x32_bf16 v[66:69], v[168:171], v[200:203], v[66:69]
	v_mfma_f32_16x16x32_bf16 v[118:121], v[164:167], v[180:183], v[118:121]
	v_mfma_f32_16x16x32_bf16 v[114:117], v[172:175], v[180:183], v[114:117]
	v_mfma_f32_16x16x32_bf16 v[102:105], v[164:167], v[188:191], v[102:105]
	v_mfma_f32_16x16x32_bf16 v[98:101], v[172:175], v[188:191], v[98:101]
	v_mfma_f32_16x16x32_bf16 v[86:89], v[164:167], v[196:199], v[86:89]
	v_mfma_f32_16x16x32_bf16 v[82:85], v[172:175], v[196:199], v[82:85]
	v_mfma_f32_16x16x32_bf16 v[70:73], v[164:167], v[204:207], v[70:73]
	v_mfma_f32_16x16x32_bf16 v[66:69], v[172:175], v[204:207], v[66:69]
	s_setprio 0
	s_barrier
; #define PG8_STAGE_A(bufoff, gbase) PG8_STAGE(bufoff, gbase, voffA, a64)
; #define PG8_STAGE_B(bufoff, bp, hb, tz) do { if (BMODE == 1 && (tz)) PG8_STAGE(bufoff, (bp) + (hb) * 4096, voffT, t64); else PG8_STAGE(bufoff, (bp) + (hb) * bhstep, voffB, b64); } while (0)
; #define PG8_LDA(dst, b, h) do { _Pragma("unroll") for (int m = 0; m < 4; ++m) _Pragma("unroll") for (int k = 0; k < 2; ++k) dst[m][k] = *(const LAS f16x8*)(lds + PG8_SA(b, h) + aoff + m * 2048 + k * 1024); } while (0)
; #define PG8_MMA(ai, bj, At, Bt) do { __builtin_amdgcn_s_setprio(1); _Pragma("unroll") for (int m = 0; m < 4; ++m) _Pragma("unroll") for (int n = 0; n < 2; ++n) _Pragma("unroll") for (int k = 0; k < 2; ++k) \
;         acc[ai][bj][m][n] = MFMA16(Bt[n][k], At[m][k], acc[ai][bj][m][n]); __builtin_amdgcn_s_setprio(0); } while (0)
; #define PG8_WAIT_V(n) asm volatile("s_waitcnt vmcnt(" #n ")" ::: "memory")
; #define PG8_WAIT_L(n) asm volatile("s_waitcnt lgkmcnt(" #n ")" ::: "memory")
; #define PG8_BAR __builtin_amdgcn_s_barrier()
; #define PG8_SCHED __builtin_amdgcn_sched_barrier(0)
; template <class CF, class Epi, class Sched, bool ALIGN_EPI, bool SP2>
; __device__ __forceinline__ void gemm_phase(LAS unsigned char* lds, const char* gA, const char* gB, const Sched& S, const Epi& E, const char* gB2 = nullptr) {
;     ...
;             PG8_WAIT_V(8); PG8_WAIT_L(0); PG8_BAR; PG8_MMA(0, 0, At, B0); PG8_MMA(0, 1, At, B1); PG8_BAR; PG8_SCHED;
;             PG8_LDA(At, 1, 1); PG8_STAGE_B(PG8_SB(1, 0), b3, 0, tz); PG8_STAGE_B(PG8_SB(1, 1), b3, 1, tz); PG8_STAGE_A(PG8_SA(1, 0), a3);
;             PG8_WAIT_V(8); PG8_WAIT_L(0); PG8_BAR; PG8_MMA(1, 0, At, B0); PG8_MMA(1, 1, At, B1); PG8_BAR; PG8_SCHED;
	s_mov_b32 m0, s69
	v_lshl_add_u64 v[220:221], v[208:209], 0, s[14:15]
	ds_read_b128 v[176:179], v140 offset:49152
	ds_read_b128 v[180:183], v140 offset:50176
	ds_read_b128 v[184:187], v140 offset:51200
	ds_read_b128 v[188:191], v140 offset:52224
	ds_read_b128 v[192:195], v140 offset:53248
	ds_read_b128 v[196:199], v140 offset:54272
	ds_read_b128 v[200:203], v140 offset:55296
	ds_read_b128 v[204:207], v140 offset:56320
	global_load_lds_dwordx4 v[220:221], off
	v_lshl_add_u64 v[220:221], v[208:209], 0, s[34:35]
	s_mov_b32 m0, s70
	s_nop 0
	global_load_lds_dwordx4 v[220:221], off
	v_lshl_add_u64 v[220:221], v[208:209], 0, s[36:37]
	s_mov_b32 m0, s71
	v_lshl_add_u64 v[208:209], v[208:209], 0, s[40:41]
	global_load_lds_dwordx4 v[220:221], off
	s_mov_b32 m0, s72
	s_nop 0
	global_load_lds_dwordx4 v[208:209], off
	v_lshl_add_u64 v[208:209], v[210:211], 0, s[14:15]
	s_mov_b32 m0, s18
	s_nop 0
	global_load_lds_dwordx4 v[208:209], off
	v_lshl_add_u64 v[208:209], v[210:211], 0, s[34:35]
	s_mov_b32 m0, s19
	s_nop 0
	global_load_lds_dwordx4 v[208:209], off
	s_waitcnt vmcnt(8)
	s_waitcnt lgkmcnt(0)
	s_barrier
	s_setprio 1
	s_waitcnt lgkmcnt(0)
	v_mfma_f32_16x16x32_bf16 v[62:65], v[144:147], v[176:179], v[62:65]
	v_mfma_f32_16x16x32_bf16 v[58:61], v[152:155], v[176:179], v[58:61]
	v_mfma_f32_16x16x32_bf16 v[46:49], v[144:147], v[184:187], v[46:49]
	v_mfma_f32_16x16x32_bf16 v[42:45], v[152:155], v[184:187], v[42:45]
	v_mfma_f32_16x16x32_bf16 v[30:33], v[144:147], v[192:195], v[30:33]
	v_mfma_f32_16x16x32_bf16 v[26:29], v[152:155], v[192:195], v[26:29]
	v_mfma_f32_16x16x32_bf16 v[14:17], v[144:147], v[200:203], v[14:17]
	v_mfma_f32_16x16x32_bf16 v[10:13], v[152:155], v[200:203], v[10:13]
	v_mfma_f32_16x16x32_bf16 v[62:65], v[148:151], v[180:183], v[62:65]
	v_mfma_f32_16x16x32_bf16 v[58:61], v[156:159], v[180:183], v[58:61]
	v_mfma_f32_16x16x32_bf16 v[46:49], v[148:151], v[188:191], v[46:49]
	v_mfma_f32_16x16x32_bf16 v[42:45], v[156:159], v[188:191], v[42:45]
	v_mfma_f32_16x16x32_bf16 v[30:33], v[148:151], v[196:199], v[30:33]
	v_mfma_f32_16x16x32_bf16 v[26:29], v[156:159], v[196:199], v[26:29]
	v_mfma_f32_16x16x32_bf16 v[14:17], v[148:151], v[204:207], v[14:17]
	v_mfma_f32_16x16x32_bf16 v[10:13], v[156:159], v[204:207], v[10:13]
	s_setprio 0
	s_setprio 1
	v_mfma_f32_16x16x32_bf16 v[54:57], v[160:163], v[176:179], v[54:57]
	v_mfma_f32_16x16x32_bf16 v[50:53], v[168:171], v[176:179], v[50:53]
	v_mfma_f32_16x16x32_bf16 v[38:41], v[160:163], v[184:187], v[38:41]
	v_mfma_f32_16x16x32_bf16 v[34:37], v[168:171], v[184:187], v[34:37]
	v_mfma_f32_16x16x32_bf16 v[22:25], v[160:163], v[192:195], v[22:25]
	v_mfma_f32_16x16x32_bf16 v[18:21], v[168:171], v[192:195], v[18:21]
	v_mfma_f32_16x16x32_bf16 v[6:9], v[160:163], v[200:203], v[6:9]
	v_mfma_f32_16x16x32_bf16 v[2:5], v[168:171], v[200:203], v[2:5]
	v_mfma_f32_16x16x32_bf16 v[54:57], v[164:167], v[180:183], v[54:57]
	v_mfma_f32_16x16x32_bf16 v[50:53], v[172:175], v[180:183], v[50:53]
	v_mfma_f32_16x16x32_bf16 v[38:41], v[164:167], v[188:191], v[38:41]
	v_mfma_f32_16x16x32_bf16 v[34:37], v[172:175], v[188:191], v[34:37]
	v_mfma_f32_16x16x32_bf16 v[22:25], v[164:167], v[196:199], v[22:25]
	v_mfma_f32_16x16x32_bf16 v[18:21], v[172:175], v[196:199], v[18:21]
	v_mfma_f32_16x16x32_bf16 v[6:9], v[164:167], v[204:207], v[6:9]
	v_mfma_f32_16x16x32_bf16 v[2:5], v[172:175], v[204:207], v[2:5]
	s_setprio 0
	s_add_i32 s62, s62, 2
	s_add_u32 s54, s54, 0x100
	s_addc_u32 s55, s55, 0
	s_cmp_gt_u32 s62, 29
	s_barrier
	s_cbranch_scc0 .LBB0_969
	s_cmpk_lt_u32 s0, 0x100
	s_cbranch_scc0 .LBB0_972
	s_barrier

; #define PG8_STAGE_A(bufoff, gbase) PG8_STAGE(bufoff, gbase, voffA, a64)
; #define PG8_STAGE_B(bufoff, bp, hb, tz) do { if (BMODE == 1 && (tz)) PG8_STAGE(bufoff, (bp) + (hb) * 4096, voffT, t64); else PG8_STAGE(bufoff, (bp) + (hb) * bhstep, voffB, b64); } while (0)
; #define PG8_LDA(dst, b, h) do { _Pragma("unroll") for (int m = 0; m < 4; ++m) _Pragma("unroll") for (int k = 0; k < 2; ++k) dst[m][k] = *(const LAS f16x8*)(lds + PG8_SA(b, h) + aoff + m * 2048 + k * 1024); } while (0)
; #define PG8_LDB(dst, b, h) do { _Pragma("unroll") for (int n = 0; n < 2; ++n) _Pragma("unroll") for (int k = 0; k < 2; ++k) dst[n][k] = *(const LAS f16x8*)(lds + PG8_SB(b, h) + boff + n * 2048 + k * 1024); } while (0)
; #define PG8_MMA(ai, bj, At, Bt) do { __builtin_amdgcn_s_setprio(1); _Pragma("unroll") for (int m = 0; m < 4; ++m) _Pragma("unroll") for (int n = 0; n < 2; ++n) _Pragma("unroll") for (int k = 0; k < 2; ++k) \
;         acc[ai][bj][m][n] = MFMA16(Bt[n][k], At[m][k], acc[ai][bj][m][n]); __builtin_amdgcn_s_setprio(0); } while (0)
; #define PG8_WAIT_V(n) asm volatile("s_waitcnt vmcnt(" #n ")" ::: "memory")
; #define PG8_WAIT_L(n) asm volatile("s_waitcnt lgkmcnt(" #n ")" ::: "memory")
; #define PG8_BAR __builtin_amdgcn_s_barrier()
; template <class CF, class Epi, class Sched, bool ALIGN_EPI, bool SP2>
; __device__ __forceinline__ void gemm_phase(LAS unsigned char* lds, const char* gA, const char* gB, const Sched& S, const Epi& E, const char* gB2 = nullptr) {
;     ...
;         for (int t = 0; t < nt; t += 2) {
;             const bool last = (t == nt - 2);
;             const bool tz = BMODE == 1 && !last && (t + 2 >= 4);
;             const char* a1 = cA + (size_t)(t + 1) * akstep;
;             const char* a2 = last ? nA : cA + (size_t)(t + 2) * akstep;
;             const char* b2 = last ? nB : (tz ? cT - (size_t)(t - 2) * 2048 : cB + (size_t)(t + 2) * bkstep);
;             const char* a3 = a2 + akstep; const char* b3 = tz ? b2 - 2048 : b2 + bkstep;
;             PG8_LDB(B0, 0, 0); PG8_LDB(B1, 0, 1); PG8_SCHED; PG8_LDA(At, 0, 0); PG8_STAGE_A(PG8_SA(1, 1), a1 + ahstep);
;             PG8_WAIT_V(8); PG8_WAIT_L(0); PG8_BAR; PG8_MMA(0, 0, At, B0); PG8_MMA(0, 1, At, B1); PG8_BAR; PG8_SCHED;
;             PG8_LDA(At, 0, 1); PG8_STAGE_B(PG8_SB(0, 0), b2, 0, tz); PG8_STAGE_B(PG8_SB(0, 1), b2, 1, tz); PG8_STAGE_A(PG8_SA(0, 0), a2);
.LBB0_993:
	ds_read_b128 v[118:121], v1
	ds_read_b128 v[142:145], v1 offset:1024
	ds_read_b128 v[154:157], v1 offset:2048
	ds_read_b128 v[158:161], v1 offset:3072
	ds_read_b128 v[162:165], v31
	ds_read_b128 v[166:169], v31 offset:1024
	ds_read_b128 v[170:173], v31 offset:2048
	ds_read_b128 v[174:177], v31 offset:3072
	s_add_i32 s36, s28, 0x200
	s_cmpk_eq_i32 s28, 0x400
	s_cselect_b64 vcc, -1, 0
	s_and_b64 s[20:21], vcc, exec
	s_cselect_b32 s20, 0, s36
	s_cselect_b32 s21, 0, -1
	s_cselect_b32 s76, s69, 0xfffff800
	s_cselect_b32 s37, s7, s56
	s_cselect_b32 s36, s6, s55
	s_cselect_b32 s73, 0x8000, s70
	s_cselect_b32 s75, 0x10000, s71
	s_cselect_b32 s74, 0x18000, s72
	s_add_u32 s40, s4, s20
	s_addc_u32 s41, s5, 0
	v_lshl_add_u64 v[132:133], v[32:33], 0, s[28:29]
	s_mov_b32 m0, s63
	v_lshl_add_u64 v[210:211], v[132:133], 0, s[30:31]
	ds_read_b128 v[178:181], v106
	ds_read_b128 v[182:185], v106 offset:1024
	ds_read_b128 v[186:189], v106 offset:2048
	ds_read_b128 v[190:193], v106 offset:3072
	ds_read_b128 v[194:197], v106 offset:4096
	ds_read_b128 v[198:201], v106 offset:5120
	ds_read_b128 v[202:205], v106 offset:6144
	ds_read_b128 v[206:209], v106 offset:7168
	global_load_lds_dwordx4 v[210:211], off
	v_lshl_add_u64 v[132:133], v[132:133], 0, s[34:35]
	s_mov_b32 m0, s64
	s_nop 0
	global_load_lds_dwordx4 v[132:133], off
	s_waitcnt vmcnt(8)
	s_waitcnt lgkmcnt(0)
	s_barrier
	s_setprio 1
	s_waitcnt lgkmcnt(0)
	v_mfma_f32_16x16x32_bf16 v[150:153], v[118:121], v[178:181], v[150:153]
	v_mfma_f32_16x16x32_bf16 v[146:149], v[154:157], v[178:181], v[146:149]
	v_mfma_f32_16x16x32_bf16 v[126:129], v[118:121], v[186:189], v[126:129]
	v_mfma_f32_16x16x32_bf16 v[122:125], v[154:157], v[186:189], v[122:125]
	v_mfma_f32_16x16x32_bf16 v[102:105], v[118:121], v[194:197], v[102:105]
	v_mfma_f32_16x16x32_bf16 v[98:101], v[154:157], v[194:197], v[98:101]
	v_mfma_f32_16x16x32_bf16 v[86:89], v[118:121], v[202:205], v[86:89]
	v_mfma_f32_16x16x32_bf16 v[82:85], v[154:157], v[202:205], v[82:85]
	v_mfma_f32_16x16x32_bf16 v[150:153], v[142:145], v[182:185], v[150:153]
	v_mfma_f32_16x16x32_bf16 v[146:149], v[158:161], v[182:185], v[146:149]
	v_mfma_f32_16x16x32_bf16 v[126:129], v[142:145], v[190:193], v[126:129]
	v_mfma_f32_16x16x32_bf16 v[122:125], v[158:161], v[190:193], v[122:125]
	v_mfma_f32_16x16x32_bf16 v[102:105], v[142:145], v[198:201], v[102:105]
	v_mfma_f32_16x16x32_bf16 v[98:101], v[158:161], v[198:201], v[98:101]
	v_mfma_f32_16x16x32_bf16 v[86:89], v[142:145], v[206:209], v[86:89]
	v_mfma_f32_16x16x32_bf16 v[82:85], v[158:161], v[206:209], v[82:85]
	s_setprio 0
	s_setprio 1
	v_mfma_f32_16x16x32_bf16 v[138:141], v[162:165], v[178:181], v[138:141]
	v_mfma_f32_16x16x32_bf16 v[132:135], v[170:173], v[178:181], v[134:137]
	v_mfma_f32_16x16x32_bf16 v[114:117], v[162:165], v[186:189], v[114:117]
	v_mfma_f32_16x16x32_bf16 v[110:113], v[170:173], v[186:189], v[110:113]
	v_mfma_f32_16x16x32_bf16 v[94:97], v[162:165], v[194:197], v[94:97]
	v_mfma_f32_16x16x32_bf16 v[90:93], v[170:173], v[194:197], v[90:93]
	v_mfma_f32_16x16x32_bf16 v[78:81], v[162:165], v[202:205], v[78:81]
	v_mfma_f32_16x16x32_bf16 v[74:77], v[170:173], v[202:205], v[74:77]
	v_mfma_f32_16x16x32_bf16 v[138:141], v[166:169], v[182:185], v[138:141]
	v_mfma_f32_16x16x32_bf16 v[132:135], v[174:177], v[182:185], v[132:135]
	v_mfma_f32_16x16x32_bf16 v[114:117], v[166:169], v[190:193], v[114:117]
	v_mfma_f32_16x16x32_bf16 v[110:113], v[174:177], v[190:193], v[110:113]
	v_mfma_f32_16x16x32_bf16 v[94:97], v[166:169], v[198:201], v[94:97]
	v_mfma_f32_16x16x32_bf16 v[90:93], v[174:177], v[198:201], v[90:93]
	v_mfma_f32_16x16x32_bf16 v[78:81], v[166:169], v[206:209], v[78:81]
	v_mfma_f32_16x16x32_bf16 v[74:77], v[174:177], v[206:209], v[74:77]
	s_setprio 0
	s_barrier
	s_add_u32 s20, s36, s76
	s_addc_u32 s21, s37, s21
	v_cndmask_b32_e32 v28, v30, v26, vcc
	s_add_u32 s76, s36, s73
	s_mov_b32 m0, s65
	v_lshl_add_u64 v[136:137], s[36:37], 0, v[28:29]
	s_addc_u32 s77, s37, 0
	ds_read_b128 v[178:181], v106 offset:16384
	ds_read_b128 v[182:185], v106 offset:17408
	ds_read_b128 v[186:189], v106 offset:18432
	ds_read_b128 v[190:193], v106 offset:19456
	ds_read_b128 v[194:197], v106 offset:20480
	ds_read_b128 v[198:201], v106 offset:21504
	ds_read_b128 v[202:205], v106 offset:22528
	ds_read_b128 v[206:209], v106 offset:23552
	global_load_lds_dwordx4 v[136:137], off
	v_lshl_add_u64 v[136:137], s[76:77], 0, v[28:29]
	s_add_u32 s76, s36, s75
	s_addc_u32 s77, s37, 0
	s_mov_b32 m0, s66
	s_add_u32 s36, s36, s74
	global_load_lds_dwordx4 v[136:137], off
	v_lshl_add_u64 v[136:137], s[76:77], 0, v[28:29]
	s_mov_b32 m0, s67
	s_addc_u32 s37, s37, 0
	global_load_lds_dwordx4 v[136:137], off
	v_lshl_add_u64 v[136:137], s[36:37], 0, v[28:29]
	s_mov_b32 m0, s68
	v_lshl_add_u64 v[210:211], s[40:41], 0, v[130:131]
	global_load_lds_dwordx4 v[136:137], off
	s_mov_b32 m0, s18
	v_lshl_add_u64 v[136:137], v[210:211], 0, s[8:9]
	global_load_lds_dwordx4 v[210:211], off
	s_mov_b32 m0, s19
	s_nop 0
	global_load_lds_dwordx4 v[136:137], off
	s_waitcnt vmcnt(8)
	s_waitcnt lgkmcnt(0)
	s_barrier
; #define PG8_STAGE_A(bufoff, gbase) PG8_STAGE(bufoff, gbase, voffA, a64)
; #define PG8_STAGE_B(bufoff, bp, hb, tz) do { if (BMODE == 1 && (tz)) PG8_STAGE(bufoff, (bp) + (hb) * 4096, voffT, t64); else PG8_STAGE(bufoff, (bp) + (hb) * bhstep, voffB, b64); } while (0)
; #define PG8_LDA(dst, b, h) do { _Pragma("unroll") for (int m = 0; m < 4; ++m) _Pragma("unroll") for (int k = 0; k < 2; ++k) dst[m][k] = *(const LAS f16x8*)(lds + PG8_SA(b, h) + aoff + m * 2048 + k * 1024); } while (0)
; #define PG8_LDB(dst, b, h) do { _Pragma("unroll") for (int n = 0; n < 2; ++n) _Pragma("unroll") for (int k = 0; k < 2; ++k) dst[n][k] = *(const LAS f16x8*)(lds + PG8_SB(b, h) + boff + n * 2048 + k * 1024); } while (0)
; #define PG8_MMA(ai, bj, At, Bt) do { __builtin_amdgcn_s_setprio(1); _Pragma("unroll") for (int m = 0; m < 4; ++m) _Pragma("unroll") for (int n = 0; n < 2; ++n) _Pragma("unroll") for (int k = 0; k < 2; ++k) \
;         acc[ai][bj][m][n] = MFMA16(Bt[n][k], At[m][k], acc[ai][bj][m][n]); __builtin_amdgcn_s_setprio(0); } while (0)
; #define PG8_WAIT_V(n) asm volatile("s_waitcnt vmcnt(" #n ")" ::: "memory")
; #define PG8_WAIT_L(n) asm volatile("s_waitcnt lgkmcnt(" #n ")" ::: "memory")
; #define PG8_BAR __builtin_amdgcn_s_barrier()
; #define PG8_SCHED __builtin_amdgcn_sched_barrier(0)
; template <class CF, class Epi, class Sched, bool ALIGN_EPI, bool SP2>
; __device__ __forceinline__ void gemm_phase(LAS unsigned char* lds, const char* gA, const char* gB, const Sched& S, const Epi& E, const char* gB2 = nullptr) {
;     ...
;             PG8_LDA(At, 0, 1); PG8_STAGE_B(PG8_SB(0, 0), b2, 0, tz); PG8_STAGE_B(PG8_SB(0, 1), b2, 1, tz); PG8_STAGE_A(PG8_SA(0, 0), a2);
;             PG8_WAIT_V(8); PG8_WAIT_L(0); PG8_BAR; PG8_MMA(1, 0, At, B0); PG8_MMA(1, 1, At, B1); PG8_BAR; PG8_SCHED;
;             PG8_LDB(B0, 1, 0); PG8_LDB(B1, 1, 1); PG8_SCHED; PG8_LDA(At, 1, 0); PG8_STAGE_A(PG8_SA(0, 1), a2 + ahstep);
;             PG8_WAIT_V(8); PG8_WAIT_L(0); PG8_BAR; PG8_MMA(0, 0, At, B0); PG8_MMA(0, 1, At, B1); PG8_BAR; PG8_SCHED;
	s_setprio 1
	s_waitcnt lgkmcnt(0)
	v_mfma_f32_16x16x32_bf16 v[70:73], v[118:121], v[178:181], v[70:73]
	v_mfma_f32_16x16x32_bf16 v[66:69], v[154:157], v[178:181], v[66:69]
	v_mfma_f32_16x16x32_bf16 v[54:57], v[118:121], v[186:189], v[54:57]
	v_mfma_f32_16x16x32_bf16 v[50:53], v[154:157], v[186:189], v[50:53]
	v_mfma_f32_16x16x32_bf16 v[38:41], v[118:121], v[194:197], v[38:41]
	v_mfma_f32_16x16x32_bf16 v[34:37], v[154:157], v[194:197], v[34:37]
	v_mfma_f32_16x16x32_bf16 v[14:17], v[118:121], v[202:205], v[14:17]
	v_mfma_f32_16x16x32_bf16 v[10:13], v[154:157], v[202:205], v[10:13]
	v_mfma_f32_16x16x32_bf16 v[70:73], v[142:145], v[182:185], v[70:73]
	v_mfma_f32_16x16x32_bf16 v[66:69], v[158:161], v[182:185], v[66:69]
	v_mfma_f32_16x16x32_bf16 v[54:57], v[142:145], v[190:193], v[54:57]
	v_mfma_f32_16x16x32_bf16 v[50:53], v[158:161], v[190:193], v[50:53]
	v_mfma_f32_16x16x32_bf16 v[38:41], v[142:145], v[198:201], v[38:41]
	v_mfma_f32_16x16x32_bf16 v[34:37], v[158:161], v[198:201], v[34:37]
	v_mfma_f32_16x16x32_bf16 v[14:17], v[142:145], v[206:209], v[14:17]
	v_mfma_f32_16x16x32_bf16 v[10:13], v[158:161], v[206:209], v[10:13]
	s_setprio 0
	s_setprio 1
	v_mfma_f32_16x16x32_bf16 v[62:65], v[162:165], v[178:181], v[62:65]
	v_mfma_f32_16x16x32_bf16 v[58:61], v[170:173], v[178:181], v[58:61]
	v_mfma_f32_16x16x32_bf16 v[46:49], v[162:165], v[186:189], v[46:49]
	v_mfma_f32_16x16x32_bf16 v[42:45], v[170:173], v[186:189], v[42:45]
	v_mfma_f32_16x16x32_bf16 v[22:25], v[162:165], v[194:197], v[22:25]
	v_mfma_f32_16x16x32_bf16 v[18:21], v[170:173], v[194:197], v[18:21]
	v_mfma_f32_16x16x32_bf16 v[6:9], v[162:165], v[202:205], v[6:9]
	v_mfma_f32_16x16x32_bf16 v[2:5], v[170:173], v[202:205], v[2:5]
	v_mfma_f32_16x16x32_bf16 v[62:65], v[166:169], v[182:185], v[62:65]
	v_mfma_f32_16x16x32_bf16 v[58:61], v[174:177], v[182:185], v[58:61]
	v_mfma_f32_16x16x32_bf16 v[46:49], v[166:169], v[190:193], v[46:49]
	v_mfma_f32_16x16x32_bf16 v[42:45], v[174:177], v[190:193], v[42:45]
	v_mfma_f32_16x16x32_bf16 v[22:25], v[166:169], v[198:201], v[22:25]
	v_mfma_f32_16x16x32_bf16 v[18:21], v[174:177], v[198:201], v[18:21]
	v_mfma_f32_16x16x32_bf16 v[6:9], v[166:169], v[206:209], v[6:9]
	v_mfma_f32_16x16x32_bf16 v[2:5], v[174:177], v[206:209], v[2:5]
	s_setprio 0
	s_barrier
	ds_read_b128 v[118:121], v107
	ds_read_b128 v[142:145], v107 offset:1024
	ds_read_b128 v[154:157], v107 offset:2048
	ds_read_b128 v[158:161], v107 offset:3072
	ds_read_b128 v[162:165], v108
	ds_read_b128 v[166:169], v108 offset:1024
	ds_read_b128 v[170:173], v108 offset:2048
	ds_read_b128 v[174:177], v108 offset:3072
	s_mov_b32 m0, s33
	v_lshl_add_u64 v[136:137], v[210:211], 0, s[10:11]
	ds_read_b128 v[178:181], v106 offset:32768
	ds_read_b128 v[182:185], v106 offset:33792
	ds_read_b128 v[186:189], v106 offset:34816
	ds_read_b128 v[190:193], v106 offset:35840
	ds_read_b128 v[194:197], v106 offset:36864
	ds_read_b128 v[198:201], v106 offset:37888
	ds_read_b128 v[202:205], v106 offset:38912
	ds_read_b128 v[206:209], v106 offset:39936
	global_load_lds_dwordx4 v[136:137], off
	v_lshl_add_u64 v[136:137], v[210:211], 0, s[12:13]
	s_mov_b32 m0, s44
	s_nop 0
	global_load_lds_dwordx4 v[136:137], off
	s_waitcnt vmcnt(8)
	s_waitcnt lgkmcnt(0)
	s_barrier
	s_setprio 1
	s_waitcnt lgkmcnt(0)
	v_mfma_f32_16x16x32_bf16 v[150:153], v[118:121], v[178:181], v[150:153]
	v_mfma_f32_16x16x32_bf16 v[146:149], v[154:157], v[178:181], v[146:149]
	v_mfma_f32_16x16x32_bf16 v[126:129], v[118:121], v[186:189], v[126:129]
	v_mfma_f32_16x16x32_bf16 v[122:125], v[154:157], v[186:189], v[122:125]
	v_mfma_f32_16x16x32_bf16 v[102:105], v[118:121], v[194:197], v[102:105]
	v_mfma_f32_16x16x32_bf16 v[98:101], v[154:157], v[194:197], v[98:101]
	v_mfma_f32_16x16x32_bf16 v[86:89], v[118:121], v[202:205], v[86:89]
	v_mfma_f32_16x16x32_bf16 v[82:85], v[154:157], v[202:205], v[82:85]
	v_mfma_f32_16x16x32_bf16 v[150:153], v[142:145], v[182:185], v[150:153]
	v_mfma_f32_16x16x32_bf16 v[146:149], v[158:161], v[182:185], v[146:149]
	v_mfma_f32_16x16x32_bf16 v[126:129], v[142:145], v[190:193], v[126:129]
	v_mfma_f32_16x16x32_bf16 v[122:125], v[158:161], v[190:193], v[122:125]
	v_mfma_f32_16x16x32_bf16 v[102:105], v[142:145], v[198:201], v[102:105]
	v_mfma_f32_16x16x32_bf16 v[98:101], v[158:161], v[198:201], v[98:101]
	v_mfma_f32_16x16x32_bf16 v[86:89], v[142:145], v[206:209], v[86:89]
	v_mfma_f32_16x16x32_bf16 v[82:85], v[158:161], v[206:209], v[82:85]
	s_setprio 0
	s_setprio 1
	v_mfma_f32_16x16x32_bf16 v[136:139], v[162:165], v[178:181], v[138:141]
	v_mfma_f32_16x16x32_bf16 v[132:135], v[170:173], v[178:181], v[132:135]
	v_mfma_f32_16x16x32_bf16 v[114:117], v[162:165], v[186:189], v[114:117]
	v_mfma_f32_16x16x32_bf16 v[110:113], v[170:173], v[186:189], v[110:113]
	v_mfma_f32_16x16x32_bf16 v[94:97], v[162:165], v[194:197], v[94:97]
	v_mfma_f32_16x16x32_bf16 v[90:93], v[170:173], v[194:197], v[90:93]
	v_mfma_f32_16x16x32_bf16 v[78:81], v[162:165], v[202:205], v[78:81]
	v_mfma_f32_16x16x32_bf16 v[74:77], v[170:173], v[202:205], v[74:77]
	v_mfma_f32_16x16x32_bf16 v[138:141], v[166:169], v[182:185], v[136:139]
	v_mfma_f32_16x16x32_bf16 v[134:137], v[174:177], v[182:185], v[132:135]
	v_mfma_f32_16x16x32_bf16 v[114:117], v[166:169], v[190:193], v[114:117]
	v_mfma_f32_16x16x32_bf16 v[110:113], v[174:177], v[190:193], v[110:113]
	v_mfma_f32_16x16x32_bf16 v[94:97], v[166:169], v[198:201], v[94:97]
	v_mfma_f32_16x16x32_bf16 v[90:93], v[174:177], v[198:201], v[90:93]
	v_mfma_f32_16x16x32_bf16 v[78:81], v[166:169], v[206:209], v[78:81]
	v_mfma_f32_16x16x32_bf16 v[74:77], v[174:177], v[206:209], v[74:77]
	s_setprio 0
	s_barrier
; #define PG8_STAGE_A(bufoff, gbase) PG8_STAGE(bufoff, gbase, voffA, a64)
; #define PG8_STAGE_B(bufoff, bp, hb, tz) do { if (BMODE == 1 && (tz)) PG8_STAGE(bufoff, (bp) + (hb) * 4096, voffT, t64); else PG8_STAGE(bufoff, (bp) + (hb) * bhstep, voffB, b64); } while (0)
; #define PG8_LDA(dst, b, h) do { _Pragma("unroll") for (int m = 0; m < 4; ++m) _Pragma("unroll") for (int k = 0; k < 2; ++k) dst[m][k] = *(const LAS f16x8*)(lds + PG8_SA(b, h) + aoff + m * 2048 + k * 1024); } while (0)
; #define PG8_MMA(ai, bj, At, Bt) do { __builtin_amdgcn_s_setprio(1); _Pragma("unroll") for (int m = 0; m < 4; ++m) _Pragma("unroll") for (int n = 0; n < 2; ++n) _Pragma("unroll") for (int k = 0; k < 2; ++k) \
;         acc[ai][bj][m][n] = MFMA16(Bt[n][k], At[m][k], acc[ai][bj][m][n]); __builtin_amdgcn_s_setprio(0); } while (0)
; #define PG8_WAIT_V(n) asm volatile("s_waitcnt vmcnt(" #n ")" ::: "memory")
; #define PG8_WAIT_L(n) asm volatile("s_waitcnt lgkmcnt(" #n ")" ::: "memory")
; #define PG8_BAR __builtin_amdgcn_s_barrier()
; #define PG8_SCHED __builtin_amdgcn_sched_barrier(0)
; template <class CF, class Epi, class Sched, bool ALIGN_EPI, bool SP2>
; __device__ __forceinline__ void gemm_phase(LAS unsigned char* lds, const char* gA, const char* gB, const Sched& S, const Epi& E, const char* gB2 = nullptr) {
;     ...
;             PG8_WAIT_V(8); PG8_WAIT_L(0); PG8_BAR; PG8_MMA(0, 0, At, B0); PG8_MMA(0, 1, At, B1); PG8_BAR; PG8_SCHED;
;             PG8_LDA(At, 1, 1); PG8_STAGE_B(PG8_SB(1, 0), b3, 0, tz); PG8_STAGE_B(PG8_SB(1, 1), b3, 1, tz); PG8_STAGE_A(PG8_SA(1, 0), a3);
;             PG8_WAIT_V(8); PG8_WAIT_L(0); PG8_BAR; PG8_MMA(1, 0, At, B0); PG8_MMA(1, 1, At, B1); PG8_BAR; PG8_SCHED;
	s_add_u32 s36, s20, s73
	s_mov_b32 m0, s57
	v_lshl_add_u64 v[132:133], s[20:21], 0, v[28:29]
	s_addc_u32 s37, s21, 0
	ds_read_b128 v[178:181], v106 offset:49152
	ds_read_b128 v[182:185], v106 offset:50176
	ds_read_b128 v[186:189], v106 offset:51200
	ds_read_b128 v[190:193], v106 offset:52224
	ds_read_b128 v[194:197], v106 offset:53248
	ds_read_b128 v[198:201], v106 offset:54272
	ds_read_b128 v[202:205], v106 offset:55296
	ds_read_b128 v[206:209], v106 offset:56320
	global_load_lds_dwordx4 v[132:133], off
	v_lshl_add_u64 v[132:133], s[36:37], 0, v[28:29]
	s_add_u32 s36, s20, s75
	s_addc_u32 s37, s21, 0
	s_mov_b32 m0, s58
	s_add_u32 s20, s20, s74
	global_load_lds_dwordx4 v[132:133], off
	v_lshl_add_u64 v[132:133], s[36:37], 0, v[28:29]
	s_mov_b32 m0, s61
	s_addc_u32 s21, s21, 0
	global_load_lds_dwordx4 v[132:133], off
	v_lshl_add_u64 v[132:133], s[20:21], 0, v[28:29]
	s_mov_b32 m0, s62
	s_nop 0
	global_load_lds_dwordx4 v[132:133], off
	v_lshl_add_u64 v[132:133], v[210:211], 0, s[14:15]
	s_mov_b32 m0, s59
	s_nop 0
	global_load_lds_dwordx4 v[132:133], off
	v_lshl_add_u64 v[132:133], v[210:211], 0, s[26:27]
	s_mov_b32 m0, s60
	s_nop 0
	global_load_lds_dwordx4 v[132:133], off
	s_waitcnt vmcnt(8)
	s_waitcnt lgkmcnt(0)
	s_barrier
	s_setprio 1
	s_waitcnt lgkmcnt(0)
	v_mfma_f32_16x16x32_bf16 v[70:73], v[118:121], v[178:181], v[70:73]
	v_mfma_f32_16x16x32_bf16 v[66:69], v[154:157], v[178:181], v[66:69]
	v_mfma_f32_16x16x32_bf16 v[54:57], v[118:121], v[186:189], v[54:57]
	v_mfma_f32_16x16x32_bf16 v[50:53], v[154:157], v[186:189], v[50:53]
	v_mfma_f32_16x16x32_bf16 v[38:41], v[118:121], v[194:197], v[38:41]
	v_mfma_f32_16x16x32_bf16 v[34:37], v[154:157], v[194:197], v[34:37]
	v_mfma_f32_16x16x32_bf16 v[14:17], v[118:121], v[202:205], v[14:17]
	v_mfma_f32_16x16x32_bf16 v[10:13], v[154:157], v[202:205], v[10:13]
	v_mfma_f32_16x16x32_bf16 v[70:73], v[142:145], v[182:185], v[70:73]
	v_mfma_f32_16x16x32_bf16 v[66:69], v[158:161], v[182:185], v[66:69]
	v_mfma_f32_16x16x32_bf16 v[54:57], v[142:145], v[190:193], v[54:57]
	v_mfma_f32_16x16x32_bf16 v[50:53], v[158:161], v[190:193], v[50:53]
	v_mfma_f32_16x16x32_bf16 v[38:41], v[142:145], v[198:201], v[38:41]
	v_mfma_f32_16x16x32_bf16 v[34:37], v[158:161], v[198:201], v[34:37]
	v_mfma_f32_16x16x32_bf16 v[14:17], v[142:145], v[206:209], v[14:17]
	v_mfma_f32_16x16x32_bf16 v[10:13], v[158:161], v[206:209], v[10:13]
	s_setprio 0
	s_setprio 1
	v_mfma_f32_16x16x32_bf16 v[62:65], v[162:165], v[178:181], v[62:65]
	v_mfma_f32_16x16x32_bf16 v[58:61], v[170:173], v[178:181], v[58:61]
	v_mfma_f32_16x16x32_bf16 v[46:49], v[162:165], v[186:189], v[46:49]
	v_mfma_f32_16x16x32_bf16 v[42:45], v[170:173], v[186:189], v[42:45]
	v_mfma_f32_16x16x32_bf16 v[22:25], v[162:165], v[194:197], v[22:25]
	v_mfma_f32_16x16x32_bf16 v[18:21], v[170:173], v[194:197], v[18:21]
	v_mfma_f32_16x16x32_bf16 v[6:9], v[162:165], v[202:205], v[6:9]
	v_mfma_f32_16x16x32_bf16 v[2:5], v[170:173], v[202:205], v[2:5]
	v_mfma_f32_16x16x32_bf16 v[62:65], v[166:169], v[182:185], v[62:65]
	v_mfma_f32_16x16x32_bf16 v[58:61], v[174:177], v[182:185], v[58:61]
	v_mfma_f32_16x16x32_bf16 v[46:49], v[166:169], v[190:193], v[46:49]
	v_mfma_f32_16x16x32_bf16 v[42:45], v[174:177], v[190:193], v[42:45]
	v_mfma_f32_16x16x32_bf16 v[22:25], v[166:169], v[198:201], v[22:25]
	v_mfma_f32_16x16x32_bf16 v[18:21], v[174:177], v[198:201], v[18:21]
	v_mfma_f32_16x16x32_bf16 v[6:9], v[166:169], v[206:209], v[6:9]
	v_mfma_f32_16x16x32_bf16 v[2:5], v[174:177], v[206:209], v[2:5]
	s_setprio 0
	s_add_i32 s45, s45, 2
	s_add_u32 s55, s55, 0xfffff000
	s_addc_u32 s56, s56, -1
	s_add_u32 s28, s28, 0x100
	s_addc_u32 s29, s29, 0
	s_cmp_gt_u32 s45, 9
	s_barrier
	s_cbranch_scc0 .LBB0_993
	s_cmpk_lt_u32 s1, 0x100
	s_mov_b32 s81, s53
	s_cbranch_scc0 .LBB0_996
	s_barrier

; #define PG8_STAGE_A(bufoff, gbase) PG8_STAGE(bufoff, gbase, voffA, a64)
; #define PG8_STAGE_B(bufoff, bp, hb, tz) do { if (BMODE == 1 && (tz)) PG8_STAGE(bufoff, (bp) + (hb) * 4096, voffT, t64); else PG8_STAGE(bufoff, (bp) + (hb) * bhstep, voffB, b64); } while (0)
; #define PG8_LDA(dst, b, h) do { _Pragma("unroll") for (int m = 0; m < 4; ++m) _Pragma("unroll") for (int k = 0; k < 2; ++k) dst[m][k] = *(const LAS f16x8*)(lds + PG8_SA(b, h) + aoff + m * 2048 + k * 1024); } while (0)
; #define PG8_LDB(dst, b, h) do { _Pragma("unroll") for (int n = 0; n < 2; ++n) _Pragma("unroll") for (int k = 0; k < 2; ++k) dst[n][k] = *(const LAS f16x8*)(lds + PG8_SB(b, h) + boff + n * 2048 + k * 1024); } while (0)
; #define PG8_MMA(ai, bj, At, Bt) do { __builtin_amdgcn_s_setprio(1); _Pragma("unroll") for (int m = 0; m < 4; ++m) _Pragma("unroll") for (int n = 0; n < 2; ++n) _Pragma("unroll") for (int k = 0; k < 2; ++k) \
;         acc[ai][bj][m][n] = MFMA16(Bt[n][k], At[m][k], acc[ai][bj][m][n]); __builtin_amdgcn_s_setprio(0); } while (0)
; #define PG8_WAIT_V(n) asm volatile("s_waitcnt vmcnt(" #n ")" ::: "memory")
; #define PG8_WAIT_L(n) asm volatile("s_waitcnt lgkmcnt(" #n ")" ::: "memory")
; #define PG8_BAR __builtin_amdgcn_s_barrier()
; template <class CF, class Epi, class Sched, bool ALIGN_EPI, bool SP2>
; __device__ __forceinline__ void gemm_phase(LAS unsigned char* lds, const char* gA, const char* gB, const Sched& S, const Epi& E, const char* gB2 = nullptr) {
;     ...
;         for (int t = 0; t < nt; t += 2) {
;             const bool last = (t == nt - 2);
;             const bool tz = BMODE == 1 && !last && (t + 2 >= 4);
;             const char* a1 = cA + (size_t)(t + 1) * akstep;
;             const char* a2 = last ? nA : cA + (size_t)(t + 2) * akstep;
;             const char* b2 = last ? nB : (tz ? cT - (size_t)(t - 2) * 2048 : cB + (size_t)(t + 2) * bkstep);
;             const char* a3 = a2 + akstep; const char* b3 = tz ? b2 - 2048 : b2 + bkstep;
;             PG8_LDB(B0, 0, 0); PG8_LDB(B1, 0, 1); PG8_SCHED; PG8_LDA(At, 0, 0); PG8_STAGE_A(PG8_SA(1, 1), a1 + ahstep);
;             PG8_WAIT_V(8); PG8_WAIT_L(0); PG8_BAR; PG8_MMA(0, 0, At, B0); PG8_MMA(0, 1, At, B1); PG8_BAR; PG8_SCHED;
;             PG8_LDA(At, 0, 1); PG8_STAGE_B(PG8_SB(0, 0), b2, 0, tz); PG8_STAGE_B(PG8_SB(0, 1), b2, 1, tz); PG8_STAGE_A(PG8_SA(0, 0), a2);
.LBB0_1070:
	ds_read_b128 v[122:125], v196
	ds_read_b128 v[126:129], v196 offset:1024
	ds_read_b128 v[130:133], v196 offset:2048
	ds_read_b128 v[134:137], v196 offset:3072
	ds_read_b128 v[142:145], v197
	ds_read_b128 v[150:153], v197 offset:1024
	ds_read_b128 v[154:157], v197 offset:2048
	ds_read_b128 v[158:161], v197 offset:3072
	s_cmp_eq_u32 s20, 12
	s_cselect_b32 s93, s18, s77
	s_cselect_b32 s92, s19, s76
	s_cselect_b32 s95, s65, s90
	s_cselect_b32 s94, s67, s89
	s_mov_b32 s96, 0xffe01000
	v_lshl_add_u64 v[192:193], s[76:77], 0, v[174:175]
	s_mov_b32 s97, -1
	v_lshl_add_u64 v[214:215], v[192:193], 0, s[96:97]
	s_mov_b32 s96, 0xffe01800
	s_add_i32 m0, s73, 0xc000
	s_mov_b32 s97, -1
	ds_read_b128 v[162:165], v198
	ds_read_b128 v[166:169], v198 offset:1024
	ds_read_b128 v[180:183], v198 offset:2048
	ds_read_b128 v[184:187], v198 offset:3072
	ds_read_b128 v[188:191], v198 offset:4096
	ds_read_b128 v[200:203], v198 offset:5120
	ds_read_b128 v[204:207], v198 offset:6144
	ds_read_b128 v[208:211], v198 offset:7168
	global_load_lds_dwordx4 v[214:215], off
	v_lshl_add_u64 v[192:193], v[192:193], 0, s[96:97]
	s_add_i32 m0, s73, 0xe000
	s_nop 0
	global_load_lds_dwordx4 v[192:193], off
	s_waitcnt vmcnt(8)
	s_waitcnt lgkmcnt(0)
	s_barrier
	s_setprio 1
	s_waitcnt lgkmcnt(0)
	v_mfma_f32_16x16x32_bf16 v[146:149], v[122:125], v[162:165], v[146:149]
	v_mfma_f32_16x16x32_bf16 v[138:141], v[130:133], v[162:165], v[138:141]
	v_mfma_f32_16x16x32_bf16 v[110:113], v[122:125], v[180:183], v[110:113]
	v_mfma_f32_16x16x32_bf16 v[106:109], v[130:133], v[180:183], v[106:109]
	v_mfma_f32_16x16x32_bf16 v[94:97], v[122:125], v[188:191], v[94:97]
	v_mfma_f32_16x16x32_bf16 v[90:93], v[130:133], v[188:191], v[90:93]
	v_mfma_f32_16x16x32_bf16 v[78:81], v[122:125], v[204:207], v[78:81]
	v_mfma_f32_16x16x32_bf16 v[74:77], v[130:133], v[204:207], v[74:77]
	v_mfma_f32_16x16x32_bf16 v[146:149], v[126:129], v[166:169], v[146:149]
	v_mfma_f32_16x16x32_bf16 v[138:141], v[134:137], v[166:169], v[138:141]
	v_mfma_f32_16x16x32_bf16 v[110:113], v[126:129], v[184:187], v[110:113]
	v_mfma_f32_16x16x32_bf16 v[106:109], v[134:137], v[184:187], v[106:109]
	v_mfma_f32_16x16x32_bf16 v[94:97], v[126:129], v[200:203], v[94:97]
	v_mfma_f32_16x16x32_bf16 v[90:93], v[134:137], v[200:203], v[90:93]
	v_mfma_f32_16x16x32_bf16 v[78:81], v[126:129], v[208:211], v[78:81]
	v_mfma_f32_16x16x32_bf16 v[74:77], v[134:137], v[208:211], v[74:77]
	s_setprio 0
	s_setprio 1
	v_mfma_f32_16x16x32_bf16 v[118:121], v[142:145], v[162:165], v[118:121]
	v_mfma_f32_16x16x32_bf16 v[114:117], v[154:157], v[162:165], v[114:117]
	v_mfma_f32_16x16x32_bf16 v[102:105], v[142:145], v[180:183], v[102:105]
	v_mfma_f32_16x16x32_bf16 v[98:101], v[154:157], v[180:183], v[98:101]
	v_mfma_f32_16x16x32_bf16 v[86:89], v[142:145], v[188:191], v[86:89]
	v_mfma_f32_16x16x32_bf16 v[82:85], v[154:157], v[188:191], v[82:85]
	v_mfma_f32_16x16x32_bf16 v[70:73], v[142:145], v[204:207], v[70:73]
	v_mfma_f32_16x16x32_bf16 v[66:69], v[154:157], v[204:207], v[66:69]
	v_mfma_f32_16x16x32_bf16 v[118:121], v[150:153], v[166:169], v[118:121]
	v_mfma_f32_16x16x32_bf16 v[114:117], v[158:161], v[166:169], v[114:117]
	v_mfma_f32_16x16x32_bf16 v[102:105], v[150:153], v[184:187], v[102:105]
	v_mfma_f32_16x16x32_bf16 v[98:101], v[158:161], v[184:187], v[98:101]
	v_mfma_f32_16x16x32_bf16 v[86:89], v[150:153], v[200:203], v[86:89]
	v_mfma_f32_16x16x32_bf16 v[82:85], v[158:161], v[200:203], v[82:85]
	v_mfma_f32_16x16x32_bf16 v[70:73], v[150:153], v[208:211], v[70:73]
	v_mfma_f32_16x16x32_bf16 v[66:69], v[158:161], v[208:211], v[66:69]
	s_setprio 0
	s_barrier
	s_add_i32 s21, s87, s80
	v_lshl_add_u64 v[192:193], s[94:95], 0, v[172:173]
	s_mov_b32 m0, s21
	ds_read_b128 v[162:165], v198 offset:16384
	ds_read_b128 v[166:169], v198 offset:17408
	ds_read_b128 v[180:183], v198 offset:18432
	ds_read_b128 v[184:187], v198 offset:19456
	ds_read_b128 v[188:191], v198 offset:20480
	ds_read_b128 v[200:203], v198 offset:21504
	ds_read_b128 v[204:207], v198 offset:22528
	ds_read_b128 v[208:211], v198 offset:23552
	global_load_lds_dwordx4 v[192:193], off
	v_lshl_add_u64 v[214:215], v[192:193], 0, s[6:7]
	s_add_i32 m0, s21, 0x2000
	s_add_i32 s21, s88, s80
	global_load_lds_dwordx4 v[214:215], off
	v_lshl_add_u64 v[214:215], v[192:193], 0, s[8:9]
	s_mov_b32 m0, s21
	s_nop 0
	global_load_lds_dwordx4 v[214:215], off
	v_lshl_add_u64 v[214:215], v[192:193], 0, s[10:11]
	s_add_i32 m0, s21, 0x2000
	s_nop 0
	global_load_lds_dwordx4 v[214:215], off
	v_lshl_add_u64 v[214:215], s[92:93], 0, v[170:171]
	s_mov_b32 m0, s73
	v_lshl_add_u64 v[216:217], v[214:215], 0, s[12:13]
	global_load_lds_dwordx4 v[214:215], off
	s_mov_b32 m0, s75
	s_nop 0
	global_load_lds_dwordx4 v[216:217], off
	s_waitcnt vmcnt(8)
	s_waitcnt lgkmcnt(0)
	s_barrier
; #define PG8_STAGE_A(bufoff, gbase) PG8_STAGE(bufoff, gbase, voffA, a64)
; #define PG8_STAGE_B(bufoff, bp, hb, tz) do { if (BMODE == 1 && (tz)) PG8_STAGE(bufoff, (bp) + (hb) * 4096, voffT, t64); else PG8_STAGE(bufoff, (bp) + (hb) * bhstep, voffB, b64); } while (0)
; #define PG8_LDA(dst, b, h) do { _Pragma("unroll") for (int m = 0; m < 4; ++m) _Pragma("unroll") for (int k = 0; k < 2; ++k) dst[m][k] = *(const LAS f16x8*)(lds + PG8_SA(b, h) + aoff + m * 2048 + k * 1024); } while (0)
; #define PG8_LDB(dst, b, h) do { _Pragma("unroll") for (int n = 0; n < 2; ++n) _Pragma("unroll") for (int k = 0; k < 2; ++k) dst[n][k] = *(const LAS f16x8*)(lds + PG8_SB(b, h) + boff + n * 2048 + k * 1024); } while (0)
; #define PG8_MMA(ai, bj, At, Bt) do { __builtin_amdgcn_s_setprio(1); _Pragma("unroll") for (int m = 0; m < 4; ++m) _Pragma("unroll") for (int n = 0; n < 2; ++n) _Pragma("unroll") for (int k = 0; k < 2; ++k) \
;         acc[ai][bj][m][n] = MFMA16(Bt[n][k], At[m][k], acc[ai][bj][m][n]); __builtin_amdgcn_s_setprio(0); } while (0)
; #define PG8_WAIT_V(n) asm volatile("s_waitcnt vmcnt(" #n ")" ::: "memory")
; #define PG8_WAIT_L(n) asm volatile("s_waitcnt lgkmcnt(" #n ")" ::: "memory")
; #define PG8_BAR __builtin_amdgcn_s_barrier()
; #define PG8_SCHED __builtin_amdgcn_sched_barrier(0)
; template <class CF, class Epi, class Sched, bool ALIGN_EPI, bool SP2>
; __device__ __forceinline__ void gemm_phase(LAS unsigned char* lds, const char* gA, const char* gB, const Sched& S, const Epi& E, const char* gB2 = nullptr) {
;     ...
;             PG8_LDA(At, 0, 1); PG8_STAGE_B(PG8_SB(0, 0), b2, 0, tz); PG8_STAGE_B(PG8_SB(0, 1), b2, 1, tz); PG8_STAGE_A(PG8_SA(0, 0), a2);
;             PG8_WAIT_V(8); PG8_WAIT_L(0); PG8_BAR; PG8_MMA(1, 0, At, B0); PG8_MMA(1, 1, At, B1); PG8_BAR; PG8_SCHED;
;             PG8_LDB(B0, 1, 0); PG8_LDB(B1, 1, 1); PG8_SCHED; PG8_LDA(At, 1, 0); PG8_STAGE_A(PG8_SA(0, 1), a2 + ahstep);
;             PG8_WAIT_V(8); PG8_WAIT_L(0); PG8_BAR; PG8_MMA(0, 0, At, B0); PG8_MMA(0, 1, At, B1); PG8_BAR; PG8_SCHED;
	s_setprio 1
	s_waitcnt lgkmcnt(0)
	v_mfma_f32_16x16x32_bf16 v[62:65], v[122:125], v[162:165], v[62:65]
	v_mfma_f32_16x16x32_bf16 v[58:61], v[130:133], v[162:165], v[58:61]
	v_mfma_f32_16x16x32_bf16 v[46:49], v[122:125], v[180:183], v[46:49]
	v_mfma_f32_16x16x32_bf16 v[42:45], v[130:133], v[180:183], v[42:45]
	v_mfma_f32_16x16x32_bf16 v[30:33], v[122:125], v[188:191], v[30:33]
	v_mfma_f32_16x16x32_bf16 v[26:29], v[130:133], v[188:191], v[26:29]
	v_mfma_f32_16x16x32_bf16 v[14:17], v[122:125], v[204:207], v[14:17]
	v_mfma_f32_16x16x32_bf16 v[10:13], v[130:133], v[204:207], v[10:13]
	v_mfma_f32_16x16x32_bf16 v[62:65], v[126:129], v[166:169], v[62:65]
	v_mfma_f32_16x16x32_bf16 v[58:61], v[134:137], v[166:169], v[58:61]
	v_mfma_f32_16x16x32_bf16 v[46:49], v[126:129], v[184:187], v[46:49]
	v_mfma_f32_16x16x32_bf16 v[42:45], v[134:137], v[184:187], v[42:45]
	v_mfma_f32_16x16x32_bf16 v[30:33], v[126:129], v[200:203], v[30:33]
	v_mfma_f32_16x16x32_bf16 v[26:29], v[134:137], v[200:203], v[26:29]
	v_mfma_f32_16x16x32_bf16 v[14:17], v[126:129], v[208:211], v[14:17]
	v_mfma_f32_16x16x32_bf16 v[10:13], v[134:137], v[208:211], v[10:13]
	s_setprio 0
	s_setprio 1
	v_mfma_f32_16x16x32_bf16 v[54:57], v[142:145], v[162:165], v[54:57]
	v_mfma_f32_16x16x32_bf16 v[50:53], v[154:157], v[162:165], v[50:53]
	v_mfma_f32_16x16x32_bf16 v[38:41], v[142:145], v[180:183], v[38:41]
	v_mfma_f32_16x16x32_bf16 v[34:37], v[154:157], v[180:183], v[34:37]
	v_mfma_f32_16x16x32_bf16 v[22:25], v[142:145], v[188:191], v[22:25]
	v_mfma_f32_16x16x32_bf16 v[18:21], v[154:157], v[188:191], v[18:21]
	v_mfma_f32_16x16x32_bf16 v[6:9], v[142:145], v[204:207], v[6:9]
	v_mfma_f32_16x16x32_bf16 v[2:5], v[154:157], v[204:207], v[2:5]
	v_mfma_f32_16x16x32_bf16 v[54:57], v[150:153], v[166:169], v[54:57]
	v_mfma_f32_16x16x32_bf16 v[50:53], v[158:161], v[166:169], v[50:53]
	v_mfma_f32_16x16x32_bf16 v[38:41], v[150:153], v[184:187], v[38:41]
	v_mfma_f32_16x16x32_bf16 v[34:37], v[158:161], v[184:187], v[34:37]
	v_mfma_f32_16x16x32_bf16 v[22:25], v[150:153], v[200:203], v[22:25]
	v_mfma_f32_16x16x32_bf16 v[18:21], v[158:161], v[200:203], v[18:21]
	v_mfma_f32_16x16x32_bf16 v[6:9], v[150:153], v[208:211], v[6:9]
	v_mfma_f32_16x16x32_bf16 v[2:5], v[158:161], v[208:211], v[2:5]
	s_setprio 0
	s_barrier
	s_add_i32 s21, 0, 0x18000
	s_add_i32 s91, 0, 0x1c000
	v_add_u32_e32 v134, s21, v194
	v_add_u32_e32 v158, s91, v194
	ds_read_b128 v[122:125], v134
	ds_read_b128 v[126:129], v134 offset:1024
	ds_read_b128 v[130:133], v134 offset:2048
	ds_read_b128 v[134:137], v134 offset:3072
	ds_read_b128 v[142:145], v158
	ds_read_b128 v[150:153], v158 offset:1024
	ds_read_b128 v[154:157], v158 offset:2048
	ds_read_b128 v[158:161], v158 offset:3072
	s_mov_b32 m0, s81
	v_lshl_add_u64 v[216:217], v[214:215], 0, s[14:15]
	ds_read_b128 v[162:165], v198 offset:32768
	ds_read_b128 v[166:169], v198 offset:33792
	ds_read_b128 v[180:183], v198 offset:34816
	ds_read_b128 v[184:187], v198 offset:35840
	ds_read_b128 v[188:191], v198 offset:36864
	ds_read_b128 v[200:203], v198 offset:37888
	ds_read_b128 v[204:207], v198 offset:38912
	ds_read_b128 v[208:211], v198 offset:39936
	global_load_lds_dwordx4 v[216:217], off
	v_lshl_add_u64 v[216:217], v[214:215], 0, s[22:23]
	s_mov_b32 m0, s82
	s_nop 0
	global_load_lds_dwordx4 v[216:217], off
	s_waitcnt vmcnt(8)
	s_waitcnt lgkmcnt(0)
	s_barrier
	s_setprio 1
	s_waitcnt lgkmcnt(0)
	v_mfma_f32_16x16x32_bf16 v[146:149], v[122:125], v[162:165], v[146:149]
	v_mfma_f32_16x16x32_bf16 v[138:141], v[130:133], v[162:165], v[138:141]
	v_mfma_f32_16x16x32_bf16 v[110:113], v[122:125], v[180:183], v[110:113]
	v_mfma_f32_16x16x32_bf16 v[106:109], v[130:133], v[180:183], v[106:109]
	v_mfma_f32_16x16x32_bf16 v[94:97], v[122:125], v[188:191], v[94:97]
	v_mfma_f32_16x16x32_bf16 v[90:93], v[130:133], v[188:191], v[90:93]
	v_mfma_f32_16x16x32_bf16 v[78:81], v[122:125], v[204:207], v[78:81]
	v_mfma_f32_16x16x32_bf16 v[74:77], v[130:133], v[204:207], v[74:77]
	v_mfma_f32_16x16x32_bf16 v[146:149], v[126:129], v[166:169], v[146:149]
	v_mfma_f32_16x16x32_bf16 v[138:141], v[134:137], v[166:169], v[138:141]
	v_mfma_f32_16x16x32_bf16 v[110:113], v[126:129], v[184:187], v[110:113]
	v_mfma_f32_16x16x32_bf16 v[106:109], v[134:137], v[184:187], v[106:109]
	v_mfma_f32_16x16x32_bf16 v[94:97], v[126:129], v[200:203], v[94:97]
	v_mfma_f32_16x16x32_bf16 v[90:93], v[134:137], v[200:203], v[90:93]
	v_mfma_f32_16x16x32_bf16 v[78:81], v[126:129], v[208:211], v[78:81]
	v_mfma_f32_16x16x32_bf16 v[74:77], v[134:137], v[208:211], v[74:77]
	s_setprio 0
	s_setprio 1
	v_mfma_f32_16x16x32_bf16 v[118:121], v[142:145], v[162:165], v[118:121]
	v_mfma_f32_16x16x32_bf16 v[114:117], v[154:157], v[162:165], v[114:117]
	v_mfma_f32_16x16x32_bf16 v[102:105], v[142:145], v[180:183], v[102:105]
	v_mfma_f32_16x16x32_bf16 v[98:101], v[154:157], v[180:183], v[98:101]
	v_mfma_f32_16x16x32_bf16 v[86:89], v[142:145], v[188:191], v[86:89]
	v_mfma_f32_16x16x32_bf16 v[82:85], v[154:157], v[188:191], v[82:85]
	v_mfma_f32_16x16x32_bf16 v[70:73], v[142:145], v[204:207], v[70:73]
	v_mfma_f32_16x16x32_bf16 v[66:69], v[154:157], v[204:207], v[66:69]
	v_mfma_f32_16x16x32_bf16 v[118:121], v[150:153], v[166:169], v[118:121]
	v_mfma_f32_16x16x32_bf16 v[114:117], v[158:161], v[166:169], v[114:117]
	v_mfma_f32_16x16x32_bf16 v[102:105], v[150:153], v[184:187], v[102:105]
	v_mfma_f32_16x16x32_bf16 v[98:101], v[158:161], v[184:187], v[98:101]
	v_mfma_f32_16x16x32_bf16 v[86:89], v[150:153], v[200:203], v[86:89]
	v_mfma_f32_16x16x32_bf16 v[82:85], v[158:161], v[200:203], v[82:85]
	v_mfma_f32_16x16x32_bf16 v[70:73], v[150:153], v[208:211], v[70:73]
	v_mfma_f32_16x16x32_bf16 v[66:69], v[158:161], v[208:211], v[66:69]
	s_setprio 0
	s_barrier
; #define PG8_STAGE_A(bufoff, gbase) PG8_STAGE(bufoff, gbase, voffA, a64)
; #define PG8_STAGE_B(bufoff, bp, hb, tz) do { if (BMODE == 1 && (tz)) PG8_STAGE(bufoff, (bp) + (hb) * 4096, voffT, t64); else PG8_STAGE(bufoff, (bp) + (hb) * bhstep, voffB, b64); } while (0)
; #define PG8_LDA(dst, b, h) do { _Pragma("unroll") for (int m = 0; m < 4; ++m) _Pragma("unroll") for (int k = 0; k < 2; ++k) dst[m][k] = *(const LAS f16x8*)(lds + PG8_SA(b, h) + aoff + m * 2048 + k * 1024); } while (0)
; #define PG8_MMA(ai, bj, At, Bt) do { __builtin_amdgcn_s_setprio(1); _Pragma("unroll") for (int m = 0; m < 4; ++m) _Pragma("unroll") for (int n = 0; n < 2; ++n) _Pragma("unroll") for (int k = 0; k < 2; ++k) \
;         acc[ai][bj][m][n] = MFMA16(Bt[n][k], At[m][k], acc[ai][bj][m][n]); __builtin_amdgcn_s_setprio(0); } while (0)
; #define PG8_WAIT_V(n) asm volatile("s_waitcnt vmcnt(" #n ")" ::: "memory")
; #define PG8_WAIT_L(n) asm volatile("s_waitcnt lgkmcnt(" #n ")" ::: "memory")
; #define PG8_BAR __builtin_amdgcn_s_barrier()
; #define PG8_SCHED __builtin_amdgcn_sched_barrier(0)
; template <class CF, class Epi, class Sched, bool ALIGN_EPI, bool SP2>
; __device__ __forceinline__ void gemm_phase(LAS unsigned char* lds, const char* gA, const char* gB, const Sched& S, const Epi& E, const char* gB2 = nullptr) {
;     ...
;             PG8_WAIT_V(8); PG8_WAIT_L(0); PG8_BAR; PG8_MMA(0, 0, At, B0); PG8_MMA(0, 1, At, B1); PG8_BAR; PG8_SCHED;
;             PG8_LDA(At, 1, 1); PG8_STAGE_B(PG8_SB(1, 0), b3, 0, tz); PG8_STAGE_B(PG8_SB(1, 1), b3, 1, tz); PG8_STAGE_A(PG8_SA(1, 0), a3);
;             PG8_WAIT_V(8); PG8_WAIT_L(0); PG8_BAR; PG8_MMA(1, 0, At, B0); PG8_MMA(1, 1, At, B1); PG8_BAR; PG8_SCHED;
	s_add_i32 s21, s21, s80
	v_lshl_add_u64 v[216:217], v[192:193], 0, s[30:31]
	s_mov_b32 m0, s21
	ds_read_b128 v[162:165], v198 offset:49152
	ds_read_b128 v[166:169], v198 offset:50176
	ds_read_b128 v[180:183], v198 offset:51200
	ds_read_b128 v[184:187], v198 offset:52224
	ds_read_b128 v[188:191], v198 offset:53248
	ds_read_b128 v[200:203], v198 offset:54272
	ds_read_b128 v[204:207], v198 offset:55296
	ds_read_b128 v[208:211], v198 offset:56320
	global_load_lds_dwordx4 v[216:217], off
	v_lshl_add_u64 v[216:217], v[192:193], 0, s[34:35]
	s_add_i32 m0, s21, 0x2000
	s_add_i32 s21, s91, s80
	global_load_lds_dwordx4 v[216:217], off
	v_lshl_add_u64 v[216:217], v[192:193], 0, s[38:39]
	s_mov_b32 m0, s21
	v_lshl_add_u64 v[192:193], v[192:193], 0, s[40:41]
	global_load_lds_dwordx4 v[216:217], off
	s_add_i32 m0, s21, 0x2000
	s_nop 0
	global_load_lds_dwordx4 v[192:193], off
	v_lshl_add_u64 v[192:193], v[214:215], 0, s[8:9]
	s_mov_b32 m0, s84
	s_nop 0
	global_load_lds_dwordx4 v[192:193], off
	v_lshl_add_u64 v[192:193], v[214:215], 0, s[36:37]
	s_mov_b32 m0, s85
	s_nop 0
	global_load_lds_dwordx4 v[192:193], off
	s_waitcnt vmcnt(8)
	s_waitcnt lgkmcnt(0)
	s_barrier
	s_setprio 1
	s_waitcnt lgkmcnt(0)
	v_mfma_f32_16x16x32_bf16 v[62:65], v[122:125], v[162:165], v[62:65]
	v_mfma_f32_16x16x32_bf16 v[58:61], v[130:133], v[162:165], v[58:61]
	v_mfma_f32_16x16x32_bf16 v[46:49], v[122:125], v[180:183], v[46:49]
	v_mfma_f32_16x16x32_bf16 v[42:45], v[130:133], v[180:183], v[42:45]
	v_mfma_f32_16x16x32_bf16 v[30:33], v[122:125], v[188:191], v[30:33]
	v_mfma_f32_16x16x32_bf16 v[26:29], v[130:133], v[188:191], v[26:29]
	v_mfma_f32_16x16x32_bf16 v[14:17], v[122:125], v[204:207], v[14:17]
	v_mfma_f32_16x16x32_bf16 v[10:13], v[130:133], v[204:207], v[10:13]
	v_mfma_f32_16x16x32_bf16 v[62:65], v[126:129], v[166:169], v[62:65]
	v_mfma_f32_16x16x32_bf16 v[58:61], v[134:137], v[166:169], v[58:61]
	v_mfma_f32_16x16x32_bf16 v[46:49], v[126:129], v[184:187], v[46:49]
	v_mfma_f32_16x16x32_bf16 v[42:45], v[134:137], v[184:187], v[42:45]
	v_mfma_f32_16x16x32_bf16 v[30:33], v[126:129], v[200:203], v[30:33]
	v_mfma_f32_16x16x32_bf16 v[26:29], v[134:137], v[200:203], v[26:29]
	v_mfma_f32_16x16x32_bf16 v[14:17], v[126:129], v[208:211], v[14:17]
	v_mfma_f32_16x16x32_bf16 v[10:13], v[134:137], v[208:211], v[10:13]
	s_setprio 0
	s_setprio 1
	v_mfma_f32_16x16x32_bf16 v[54:57], v[142:145], v[162:165], v[54:57]
	v_mfma_f32_16x16x32_bf16 v[50:53], v[154:157], v[162:165], v[50:53]
	v_mfma_f32_16x16x32_bf16 v[38:41], v[142:145], v[180:183], v[38:41]
	v_mfma_f32_16x16x32_bf16 v[34:37], v[154:157], v[180:183], v[34:37]
	v_mfma_f32_16x16x32_bf16 v[22:25], v[142:145], v[188:191], v[22:25]
	v_mfma_f32_16x16x32_bf16 v[18:21], v[154:157], v[188:191], v[18:21]
	v_mfma_f32_16x16x32_bf16 v[6:9], v[142:145], v[204:207], v[6:9]
	v_mfma_f32_16x16x32_bf16 v[2:5], v[154:157], v[204:207], v[2:5]
	v_mfma_f32_16x16x32_bf16 v[54:57], v[150:153], v[166:169], v[54:57]
	v_mfma_f32_16x16x32_bf16 v[50:53], v[158:161], v[166:169], v[50:53]
	v_mfma_f32_16x16x32_bf16 v[38:41], v[150:153], v[184:187], v[38:41]
	v_mfma_f32_16x16x32_bf16 v[34:37], v[158:161], v[184:187], v[34:37]
	v_mfma_f32_16x16x32_bf16 v[22:25], v[150:153], v[200:203], v[22:25]
	v_mfma_f32_16x16x32_bf16 v[18:21], v[158:161], v[200:203], v[18:21]
	v_mfma_f32_16x16x32_bf16 v[6:9], v[150:153], v[208:211], v[6:9]
	v_mfma_f32_16x16x32_bf16 v[2:5], v[158:161], v[208:211], v[2:5]
	s_setprio 0
	s_add_i32 s20, s20, 2
	s_add_u32 s89, s89, 0x100
	s_addc_u32 s90, s90, 0
	s_add_u32 s76, s76, 0x400000
	s_addc_u32 s77, s77, 0
	s_cmp_gt_u32 s20, 13
	s_barrier
	s_cbranch_scc0 .LBB0_1070
	s_and_b64 vcc, exec, s[44:45]
	s_cbranch_vccz .LBB0_1073
	s_barrier

; #define PG8_STAGE_A(bufoff, gbase) PG8_STAGE(bufoff, gbase, voffA, a64)
; #define PG8_STAGE_B(bufoff, bp, hb, tz) do { if (BMODE == 1 && (tz)) PG8_STAGE(bufoff, (bp) + (hb) * 4096, voffT, t64); else PG8_STAGE(bufoff, (bp) + (hb) * bhstep, voffB, b64); } while (0)
; #define PG8_LDA(dst, b, h) do { _Pragma("unroll") for (int m = 0; m < 4; ++m) _Pragma("unroll") for (int k = 0; k < 2; ++k) dst[m][k] = *(const LAS f16x8*)(lds + PG8_SA(b, h) + aoff + m * 2048 + k * 1024); } while (0)
; #define PG8_LDB(dst, b, h) do { _Pragma("unroll") for (int n = 0; n < 2; ++n) _Pragma("unroll") for (int k = 0; k < 2; ++k) dst[n][k] = *(const LAS f16x8*)(lds + PG8_SB(b, h) + boff + n * 2048 + k * 1024); } while (0)
; #define PG8_MMA(ai, bj, At, Bt) do { __builtin_amdgcn_s_setprio(1); _Pragma("unroll") for (int m = 0; m < 4; ++m) _Pragma("unroll") for (int n = 0; n < 2; ++n) _Pragma("unroll") for (int k = 0; k < 2; ++k) \
;         acc[ai][bj][m][n] = MFMA16(Bt[n][k], At[m][k], acc[ai][bj][m][n]); __builtin_amdgcn_s_setprio(0); } while (0)
; #define PG8_WAIT_V(n) asm volatile("s_waitcnt vmcnt(" #n ")" ::: "memory")
; #define PG8_WAIT_L(n) asm volatile("s_waitcnt lgkmcnt(" #n ")" ::: "memory")
; #define PG8_BAR __builtin_amdgcn_s_barrier()
; template <class CF, class Epi, class Sched, bool ALIGN_EPI, bool SP2>
; __device__ __forceinline__ void gemm_phase(LAS unsigned char* lds, const char* gA, const char* gB, const Sched& S, const Epi& E, const char* gB2 = nullptr) {
;     ...
;         for (int t = 0; t < nt; t += 2) {
;             const bool last = (t == nt - 2);
;             const bool tz = BMODE == 1 && !last && (t + 2 >= 4);
;             const char* a1 = cA + (size_t)(t + 1) * akstep;
;             const char* a2 = last ? nA : cA + (size_t)(t + 2) * akstep;
;             const char* b2 = last ? nB : (tz ? cT - (size_t)(t - 2) * 2048 : cB + (size_t)(t + 2) * bkstep);
;             const char* a3 = a2 + akstep; const char* b3 = tz ? b2 - 2048 : b2 + bkstep;
;             PG8_LDB(B0, 0, 0); PG8_LDB(B1, 0, 1); PG8_SCHED; PG8_LDA(At, 0, 0); PG8_STAGE_A(PG8_SA(1, 1), a1 + ahstep);
;             PG8_WAIT_V(8); PG8_WAIT_L(0); PG8_BAR; PG8_MMA(0, 0, At, B0); PG8_MMA(0, 1, At, B1); PG8_BAR; PG8_SCHED;
;             PG8_LDA(At, 0, 1); PG8_STAGE_B(PG8_SB(0, 0), b2, 0, tz); PG8_STAGE_B(PG8_SB(0, 1), b2, 1, tz); PG8_STAGE_A(PG8_SA(0, 0), a2);
.LBB0_1151:
	ds_read_b128 v[104:107], v181
	ds_read_b128 v[108:111], v181 offset:1024
	ds_read_b128 v[112:115], v181 offset:2048
	ds_read_b128 v[120:123], v181 offset:3072
	ds_read_b128 v[144:147], v182
	ds_read_b128 v[148:151], v182 offset:1024
	ds_read_b128 v[152:155], v182 offset:2048
	ds_read_b128 v[156:159], v182 offset:3072
	s_add_u32 s62, s60, 0xfff80080
	s_addc_u32 s63, s61, -1
	s_cmp_eq_u32 s59, 28
	s_cselect_b32 s63, s18, s63
	s_cselect_b32 s62, s19, s62
	s_cselect_b32 s81, s43, s21
	s_cselect_b32 s80, s45, s20
	v_lshl_add_u64 v[210:211], s[60:61], 0, v[164:165]
	s_add_i32 m0, s66, 0xc000
	ds_read_b128 v[170:173], v183
	ds_read_b128 v[174:177], v183 offset:1024
	ds_read_b128 v[186:189], v183 offset:2048
	ds_read_b128 v[190:193], v183 offset:3072
	ds_read_b128 v[194:197], v183 offset:4096
	ds_read_b128 v[198:201], v183 offset:5120
	ds_read_b128 v[202:205], v183 offset:6144
	ds_read_b128 v[206:209], v183 offset:7168
	global_load_lds_dwordx4 v[210:211], off
	v_lshl_add_u64 v[210:211], v[210:211], 0, s[8:9]
	s_add_i32 m0, s66, 0xe000
	s_nop 0
	global_load_lds_dwordx4 v[210:211], off
	s_waitcnt vmcnt(8)
	s_waitcnt lgkmcnt(0)
	s_barrier
	s_setprio 1
	s_waitcnt lgkmcnt(0)
	v_mfma_f32_16x16x32_bf16 v[140:143], v[104:107], v[170:173], v[140:143]
	v_mfma_f32_16x16x32_bf16 v[136:139], v[112:115], v[170:173], v[136:139]
	v_mfma_f32_16x16x32_bf16 v[124:127], v[104:107], v[186:189], v[124:127]
	v_mfma_f32_16x16x32_bf16 v[116:119], v[112:115], v[186:189], v[116:119]
	v_mfma_f32_16x16x32_bf16 v[92:95], v[104:107], v[194:197], v[92:95]
	v_mfma_f32_16x16x32_bf16 v[88:91], v[112:115], v[194:197], v[88:91]
	v_mfma_f32_16x16x32_bf16 v[76:79], v[104:107], v[202:205], v[76:79]
	v_mfma_f32_16x16x32_bf16 v[72:75], v[112:115], v[202:205], v[72:75]
	v_mfma_f32_16x16x32_bf16 v[140:143], v[108:111], v[174:177], v[140:143]
	v_mfma_f32_16x16x32_bf16 v[136:139], v[120:123], v[174:177], v[136:139]
	v_mfma_f32_16x16x32_bf16 v[124:127], v[108:111], v[190:193], v[124:127]
	v_mfma_f32_16x16x32_bf16 v[116:119], v[120:123], v[190:193], v[116:119]
	v_mfma_f32_16x16x32_bf16 v[92:95], v[108:111], v[198:201], v[92:95]
	v_mfma_f32_16x16x32_bf16 v[88:91], v[120:123], v[198:201], v[88:91]
	v_mfma_f32_16x16x32_bf16 v[76:79], v[108:111], v[206:209], v[76:79]
	v_mfma_f32_16x16x32_bf16 v[72:75], v[120:123], v[206:209], v[72:75]
	s_setprio 0
	s_setprio 1
	v_mfma_f32_16x16x32_bf16 v[132:135], v[144:147], v[170:173], v[132:135]
	v_mfma_f32_16x16x32_bf16 v[128:131], v[152:155], v[170:173], v[128:131]
	v_mfma_f32_16x16x32_bf16 v[100:103], v[144:147], v[186:189], v[100:103]
	v_mfma_f32_16x16x32_bf16 v[96:99], v[152:155], v[186:189], v[96:99]
	v_mfma_f32_16x16x32_bf16 v[84:87], v[144:147], v[194:197], v[84:87]
	v_mfma_f32_16x16x32_bf16 v[80:83], v[152:155], v[194:197], v[80:83]
	v_mfma_f32_16x16x32_bf16 v[68:71], v[144:147], v[202:205], v[68:71]
	v_mfma_f32_16x16x32_bf16 v[64:67], v[152:155], v[202:205], v[64:67]
	v_mfma_f32_16x16x32_bf16 v[132:135], v[148:151], v[174:177], v[132:135]
	v_mfma_f32_16x16x32_bf16 v[128:131], v[156:159], v[174:177], v[128:131]
	v_mfma_f32_16x16x32_bf16 v[100:103], v[148:151], v[190:193], v[100:103]
	v_mfma_f32_16x16x32_bf16 v[96:99], v[156:159], v[190:193], v[96:99]
	v_mfma_f32_16x16x32_bf16 v[84:87], v[148:151], v[198:201], v[84:87]
	v_mfma_f32_16x16x32_bf16 v[80:83], v[156:159], v[198:201], v[80:83]
	v_mfma_f32_16x16x32_bf16 v[68:71], v[148:151], v[206:209], v[68:71]
	v_mfma_f32_16x16x32_bf16 v[64:67], v[156:159], v[206:209], v[64:67]
	s_setprio 0
	s_barrier
	s_add_i32 s79, s75, s65
	v_lshl_add_u64 v[210:211], s[80:81], 0, v[162:163]
	s_mov_b32 m0, s79
	ds_read_b128 v[170:173], v183 offset:16384
	ds_read_b128 v[174:177], v183 offset:17408
	ds_read_b128 v[186:189], v183 offset:18432
	ds_read_b128 v[190:193], v183 offset:19456
	ds_read_b128 v[194:197], v183 offset:20480
	ds_read_b128 v[198:201], v183 offset:21504
	ds_read_b128 v[202:205], v183 offset:22528
	ds_read_b128 v[206:209], v183 offset:23552
	global_load_lds_dwordx4 v[210:211], off
	v_lshl_add_u64 v[214:215], v[210:211], 0, s[8:9]
	s_add_i32 m0, s79, 0x2000
	s_add_i32 s79, s76, s65
	global_load_lds_dwordx4 v[214:215], off
	v_lshl_add_u64 v[214:215], v[210:211], 0, s[10:11]
	s_mov_b32 m0, s79
	s_nop 0
	global_load_lds_dwordx4 v[214:215], off
	v_lshl_add_u64 v[214:215], v[210:211], 0, s[12:13]
	s_add_i32 m0, s79, 0x2000
	s_nop 0
	global_load_lds_dwordx4 v[214:215], off
	v_lshl_add_u64 v[214:215], s[62:63], 0, v[160:161]
	s_mov_b32 m0, s66
	v_lshl_add_u64 v[216:217], v[214:215], 0, s[8:9]
	global_load_lds_dwordx4 v[214:215], off
	s_mov_b32 m0, s67
	s_nop 0
	global_load_lds_dwordx4 v[216:217], off
	s_waitcnt vmcnt(8)
	s_waitcnt lgkmcnt(0)
	s_barrier
; #define PG8_STAGE_A(bufoff, gbase) PG8_STAGE(bufoff, gbase, voffA, a64)
; #define PG8_STAGE_B(bufoff, bp, hb, tz) do { if (BMODE == 1 && (tz)) PG8_STAGE(bufoff, (bp) + (hb) * 4096, voffT, t64); else PG8_STAGE(bufoff, (bp) + (hb) * bhstep, voffB, b64); } while (0)
; #define PG8_LDA(dst, b, h) do { _Pragma("unroll") for (int m = 0; m < 4; ++m) _Pragma("unroll") for (int k = 0; k < 2; ++k) dst[m][k] = *(const LAS f16x8*)(lds + PG8_SA(b, h) + aoff + m * 2048 + k * 1024); } while (0)
; #define PG8_LDB(dst, b, h) do { _Pragma("unroll") for (int n = 0; n < 2; ++n) _Pragma("unroll") for (int k = 0; k < 2; ++k) dst[n][k] = *(const LAS f16x8*)(lds + PG8_SB(b, h) + boff + n * 2048 + k * 1024); } while (0)
; #define PG8_MMA(ai, bj, At, Bt) do { __builtin_amdgcn_s_setprio(1); _Pragma("unroll") for (int m = 0; m < 4; ++m) _Pragma("unroll") for (int n = 0; n < 2; ++n) _Pragma("unroll") for (int k = 0; k < 2; ++k) \
;         acc[ai][bj][m][n] = MFMA16(Bt[n][k], At[m][k], acc[ai][bj][m][n]); __builtin_amdgcn_s_setprio(0); } while (0)
; #define PG8_WAIT_V(n) asm volatile("s_waitcnt vmcnt(" #n ")" ::: "memory")
; #define PG8_WAIT_L(n) asm volatile("s_waitcnt lgkmcnt(" #n ")" ::: "memory")
; #define PG8_BAR __builtin_amdgcn_s_barrier()
; #define PG8_SCHED __builtin_amdgcn_sched_barrier(0)
; template <class CF, class Epi, class Sched, bool ALIGN_EPI, bool SP2>
; __device__ __forceinline__ void gemm_phase(LAS unsigned char* lds, const char* gA, const char* gB, const Sched& S, const Epi& E, const char* gB2 = nullptr) {
;     ...
;             PG8_LDA(At, 0, 1); PG8_STAGE_B(PG8_SB(0, 0), b2, 0, tz); PG8_STAGE_B(PG8_SB(0, 1), b2, 1, tz); PG8_STAGE_A(PG8_SA(0, 0), a2);
;             PG8_WAIT_V(8); PG8_WAIT_L(0); PG8_BAR; PG8_MMA(1, 0, At, B0); PG8_MMA(1, 1, At, B1); PG8_BAR; PG8_SCHED;
;             PG8_LDB(B0, 1, 0); PG8_LDB(B1, 1, 1); PG8_SCHED; PG8_LDA(At, 1, 0); PG8_STAGE_A(PG8_SA(0, 1), a2 + ahstep);
;             PG8_WAIT_V(8); PG8_WAIT_L(0); PG8_BAR; PG8_MMA(0, 0, At, B0); PG8_MMA(0, 1, At, B1); PG8_BAR; PG8_SCHED;
	s_setprio 1
	s_waitcnt lgkmcnt(0)
	v_mfma_f32_16x16x32_bf16 v[60:63], v[104:107], v[170:173], v[60:63]
	v_mfma_f32_16x16x32_bf16 v[56:59], v[112:115], v[170:173], v[56:59]
	v_mfma_f32_16x16x32_bf16 v[44:47], v[104:107], v[186:189], v[44:47]
	v_mfma_f32_16x16x32_bf16 v[40:43], v[112:115], v[186:189], v[40:43]
	v_mfma_f32_16x16x32_bf16 v[28:31], v[104:107], v[194:197], v[28:31]
	v_mfma_f32_16x16x32_bf16 v[24:27], v[112:115], v[194:197], v[24:27]
	v_mfma_f32_16x16x32_bf16 v[12:15], v[104:107], v[202:205], v[12:15]
	v_mfma_f32_16x16x32_bf16 v[8:11], v[112:115], v[202:205], v[8:11]
	v_mfma_f32_16x16x32_bf16 v[60:63], v[108:111], v[174:177], v[60:63]
	v_mfma_f32_16x16x32_bf16 v[56:59], v[120:123], v[174:177], v[56:59]
	v_mfma_f32_16x16x32_bf16 v[44:47], v[108:111], v[190:193], v[44:47]
	v_mfma_f32_16x16x32_bf16 v[40:43], v[120:123], v[190:193], v[40:43]
	v_mfma_f32_16x16x32_bf16 v[28:31], v[108:111], v[198:201], v[28:31]
	v_mfma_f32_16x16x32_bf16 v[24:27], v[120:123], v[198:201], v[24:27]
	v_mfma_f32_16x16x32_bf16 v[12:15], v[108:111], v[206:209], v[12:15]
	v_mfma_f32_16x16x32_bf16 v[8:11], v[120:123], v[206:209], v[8:11]
	s_setprio 0
	s_setprio 1
	v_mfma_f32_16x16x32_bf16 v[52:55], v[144:147], v[170:173], v[52:55]
	v_mfma_f32_16x16x32_bf16 v[48:51], v[152:155], v[170:173], v[48:51]
	v_mfma_f32_16x16x32_bf16 v[36:39], v[144:147], v[186:189], v[36:39]
	v_mfma_f32_16x16x32_bf16 v[32:35], v[152:155], v[186:189], v[32:35]
	v_mfma_f32_16x16x32_bf16 v[20:23], v[144:147], v[194:197], v[20:23]
	v_mfma_f32_16x16x32_bf16 v[16:19], v[152:155], v[194:197], v[16:19]
	v_mfma_f32_16x16x32_bf16 v[4:7], v[144:147], v[202:205], v[4:7]
	v_mfma_f32_16x16x32_bf16 v[0:3], v[152:155], v[202:205], v[0:3]
	v_mfma_f32_16x16x32_bf16 v[52:55], v[148:151], v[174:177], v[52:55]
	v_mfma_f32_16x16x32_bf16 v[48:51], v[156:159], v[174:177], v[48:51]
	v_mfma_f32_16x16x32_bf16 v[36:39], v[148:151], v[190:193], v[36:39]
	v_mfma_f32_16x16x32_bf16 v[32:35], v[156:159], v[190:193], v[32:35]
	v_mfma_f32_16x16x32_bf16 v[20:23], v[148:151], v[198:201], v[20:23]
	v_mfma_f32_16x16x32_bf16 v[16:19], v[156:159], v[198:201], v[16:19]
	v_mfma_f32_16x16x32_bf16 v[4:7], v[148:151], v[206:209], v[4:7]
	v_mfma_f32_16x16x32_bf16 v[0:3], v[156:159], v[206:209], v[0:3]
	s_setprio 0
	s_barrier
	s_add_i32 s62, 0, 0x18000
	s_add_i32 s63, 0, 0x1c000
	v_add_u32_e32 v120, s62, v179
	v_add_u32_e32 v156, s63, v179
	ds_read_b128 v[104:107], v120
	ds_read_b128 v[108:111], v120 offset:1024
	ds_read_b128 v[112:115], v120 offset:2048
	ds_read_b128 v[120:123], v120 offset:3072
	ds_read_b128 v[144:147], v156
	ds_read_b128 v[148:151], v156 offset:1024
	ds_read_b128 v[152:155], v156 offset:2048
	ds_read_b128 v[156:159], v156 offset:3072
	s_mov_b32 m0, s68
	v_lshl_add_u64 v[216:217], v[214:215], 0, s[10:11]
	ds_read_b128 v[170:173], v183 offset:32768
	ds_read_b128 v[174:177], v183 offset:33792
	ds_read_b128 v[186:189], v183 offset:34816
	ds_read_b128 v[190:193], v183 offset:35840
	ds_read_b128 v[194:197], v183 offset:36864
	ds_read_b128 v[198:201], v183 offset:37888
	ds_read_b128 v[202:205], v183 offset:38912
	ds_read_b128 v[206:209], v183 offset:39936
	global_load_lds_dwordx4 v[216:217], off
	v_lshl_add_u64 v[216:217], v[214:215], 0, s[12:13]
	s_mov_b32 m0, s69
	s_nop 0
	global_load_lds_dwordx4 v[216:217], off
	s_waitcnt vmcnt(8)
	s_waitcnt lgkmcnt(0)
	s_barrier
	s_setprio 1
	s_waitcnt lgkmcnt(0)
	v_mfma_f32_16x16x32_bf16 v[140:143], v[104:107], v[170:173], v[140:143]
	v_mfma_f32_16x16x32_bf16 v[136:139], v[112:115], v[170:173], v[136:139]
	v_mfma_f32_16x16x32_bf16 v[124:127], v[104:107], v[186:189], v[124:127]
	v_mfma_f32_16x16x32_bf16 v[116:119], v[112:115], v[186:189], v[116:119]
	v_mfma_f32_16x16x32_bf16 v[92:95], v[104:107], v[194:197], v[92:95]
	v_mfma_f32_16x16x32_bf16 v[88:91], v[112:115], v[194:197], v[88:91]
	v_mfma_f32_16x16x32_bf16 v[76:79], v[104:107], v[202:205], v[76:79]
	v_mfma_f32_16x16x32_bf16 v[72:75], v[112:115], v[202:205], v[72:75]
	v_mfma_f32_16x16x32_bf16 v[140:143], v[108:111], v[174:177], v[140:143]
	v_mfma_f32_16x16x32_bf16 v[136:139], v[120:123], v[174:177], v[136:139]
	v_mfma_f32_16x16x32_bf16 v[124:127], v[108:111], v[190:193], v[124:127]
	v_mfma_f32_16x16x32_bf16 v[116:119], v[120:123], v[190:193], v[116:119]
	v_mfma_f32_16x16x32_bf16 v[92:95], v[108:111], v[198:201], v[92:95]
	v_mfma_f32_16x16x32_bf16 v[88:91], v[120:123], v[198:201], v[88:91]
	v_mfma_f32_16x16x32_bf16 v[76:79], v[108:111], v[206:209], v[76:79]
	v_mfma_f32_16x16x32_bf16 v[72:75], v[120:123], v[206:209], v[72:75]
	s_setprio 0
	s_setprio 1
	v_mfma_f32_16x16x32_bf16 v[132:135], v[144:147], v[170:173], v[132:135]
	v_mfma_f32_16x16x32_bf16 v[128:131], v[152:155], v[170:173], v[128:131]
	v_mfma_f32_16x16x32_bf16 v[100:103], v[144:147], v[186:189], v[100:103]
	v_mfma_f32_16x16x32_bf16 v[96:99], v[152:155], v[186:189], v[96:99]
	v_mfma_f32_16x16x32_bf16 v[84:87], v[144:147], v[194:197], v[84:87]
	v_mfma_f32_16x16x32_bf16 v[80:83], v[152:155], v[194:197], v[80:83]
	v_mfma_f32_16x16x32_bf16 v[68:71], v[144:147], v[202:205], v[68:71]
	v_mfma_f32_16x16x32_bf16 v[64:67], v[152:155], v[202:205], v[64:67]
	v_mfma_f32_16x16x32_bf16 v[132:135], v[148:151], v[174:177], v[132:135]
	v_mfma_f32_16x16x32_bf16 v[128:131], v[156:159], v[174:177], v[128:131]
	v_mfma_f32_16x16x32_bf16 v[100:103], v[148:151], v[190:193], v[100:103]
	v_mfma_f32_16x16x32_bf16 v[96:99], v[156:159], v[190:193], v[96:99]
	v_mfma_f32_16x16x32_bf16 v[84:87], v[148:151], v[198:201], v[84:87]
	v_mfma_f32_16x16x32_bf16 v[80:83], v[156:159], v[198:201], v[80:83]
	v_mfma_f32_16x16x32_bf16 v[68:71], v[148:151], v[206:209], v[68:71]
	v_mfma_f32_16x16x32_bf16 v[64:67], v[156:159], v[206:209], v[64:67]
	s_setprio 0
	s_barrier
; #define PG8_STAGE_A(bufoff, gbase) PG8_STAGE(bufoff, gbase, voffA, a64)
; #define PG8_STAGE_B(bufoff, bp, hb, tz) do { if (BMODE == 1 && (tz)) PG8_STAGE(bufoff, (bp) + (hb) * 4096, voffT, t64); else PG8_STAGE(bufoff, (bp) + (hb) * bhstep, voffB, b64); } while (0)
; #define PG8_LDA(dst, b, h) do { _Pragma("unroll") for (int m = 0; m < 4; ++m) _Pragma("unroll") for (int k = 0; k < 2; ++k) dst[m][k] = *(const LAS f16x8*)(lds + PG8_SA(b, h) + aoff + m * 2048 + k * 1024); } while (0)
; #define PG8_MMA(ai, bj, At, Bt) do { __builtin_amdgcn_s_setprio(1); _Pragma("unroll") for (int m = 0; m < 4; ++m) _Pragma("unroll") for (int n = 0; n < 2; ++n) _Pragma("unroll") for (int k = 0; k < 2; ++k) \
;         acc[ai][bj][m][n] = MFMA16(Bt[n][k], At[m][k], acc[ai][bj][m][n]); __builtin_amdgcn_s_setprio(0); } while (0)
; #define PG8_WAIT_V(n) asm volatile("s_waitcnt vmcnt(" #n ")" ::: "memory")
; #define PG8_WAIT_L(n) asm volatile("s_waitcnt lgkmcnt(" #n ")" ::: "memory")
; #define PG8_BAR __builtin_amdgcn_s_barrier()
; #define PG8_SCHED __builtin_amdgcn_sched_barrier(0)
; template <class CF, class Epi, class Sched, bool ALIGN_EPI, bool SP2>
; __device__ __forceinline__ void gemm_phase(LAS unsigned char* lds, const char* gA, const char* gB, const Sched& S, const Epi& E, const char* gB2 = nullptr) {
;     ...
;             PG8_WAIT_V(8); PG8_WAIT_L(0); PG8_BAR; PG8_MMA(0, 0, At, B0); PG8_MMA(0, 1, At, B1); PG8_BAR; PG8_SCHED;
;             PG8_LDA(At, 1, 1); PG8_STAGE_B(PG8_SB(1, 0), b3, 0, tz); PG8_STAGE_B(PG8_SB(1, 1), b3, 1, tz); PG8_STAGE_A(PG8_SA(1, 0), a3);
;             PG8_WAIT_V(8); PG8_WAIT_L(0); PG8_BAR; PG8_MMA(1, 0, At, B0); PG8_MMA(1, 1, At, B1); PG8_BAR; PG8_SCHED;
	s_add_i32 s62, s62, s65
	v_lshl_add_u64 v[216:217], v[210:211], 0, s[28:29]
	s_mov_b32 m0, s62
	ds_read_b128 v[170:173], v183 offset:49152
	ds_read_b128 v[174:177], v183 offset:50176
	ds_read_b128 v[186:189], v183 offset:51200
	ds_read_b128 v[190:193], v183 offset:52224
	ds_read_b128 v[194:197], v183 offset:53248
	ds_read_b128 v[198:201], v183 offset:54272
	ds_read_b128 v[202:205], v183 offset:55296
	ds_read_b128 v[206:209], v183 offset:56320
	global_load_lds_dwordx4 v[216:217], off
	v_lshl_add_u64 v[216:217], v[210:211], 0, s[30:31]
	s_add_i32 m0, s62, 0x2000
	s_add_i32 s62, s63, s65
	global_load_lds_dwordx4 v[216:217], off
	v_lshl_add_u64 v[216:217], v[210:211], 0, s[34:35]
	s_mov_b32 m0, s62
	v_lshl_add_u64 v[210:211], v[210:211], 0, s[36:37]
	global_load_lds_dwordx4 v[216:217], off
	s_add_i32 m0, s62, 0x2000
	s_nop 0
	global_load_lds_dwordx4 v[210:211], off
	v_lshl_add_u64 v[210:211], v[214:215], 0, s[28:29]
	s_mov_b32 m0, s70
	s_nop 0
	global_load_lds_dwordx4 v[210:211], off
	v_lshl_add_u64 v[210:211], v[214:215], 0, s[30:31]
	s_mov_b32 m0, s71
	s_nop 0
	global_load_lds_dwordx4 v[210:211], off
	s_waitcnt vmcnt(8)
	s_waitcnt lgkmcnt(0)
	s_barrier
	s_setprio 1
	s_waitcnt lgkmcnt(0)
	v_mfma_f32_16x16x32_bf16 v[60:63], v[104:107], v[170:173], v[60:63]
	v_mfma_f32_16x16x32_bf16 v[56:59], v[112:115], v[170:173], v[56:59]
	v_mfma_f32_16x16x32_bf16 v[44:47], v[104:107], v[186:189], v[44:47]
	v_mfma_f32_16x16x32_bf16 v[40:43], v[112:115], v[186:189], v[40:43]
	v_mfma_f32_16x16x32_bf16 v[28:31], v[104:107], v[194:197], v[28:31]
	v_mfma_f32_16x16x32_bf16 v[24:27], v[112:115], v[194:197], v[24:27]
	v_mfma_f32_16x16x32_bf16 v[12:15], v[104:107], v[202:205], v[12:15]
	v_mfma_f32_16x16x32_bf16 v[8:11], v[112:115], v[202:205], v[8:11]
	v_mfma_f32_16x16x32_bf16 v[60:63], v[108:111], v[174:177], v[60:63]
	v_mfma_f32_16x16x32_bf16 v[56:59], v[120:123], v[174:177], v[56:59]
	v_mfma_f32_16x16x32_bf16 v[44:47], v[108:111], v[190:193], v[44:47]
	v_mfma_f32_16x16x32_bf16 v[40:43], v[120:123], v[190:193], v[40:43]
	v_mfma_f32_16x16x32_bf16 v[28:31], v[108:111], v[198:201], v[28:31]
	v_mfma_f32_16x16x32_bf16 v[24:27], v[120:123], v[198:201], v[24:27]
	v_mfma_f32_16x16x32_bf16 v[12:15], v[108:111], v[206:209], v[12:15]
	v_mfma_f32_16x16x32_bf16 v[8:11], v[120:123], v[206:209], v[8:11]
	s_setprio 0
	s_setprio 1
	v_mfma_f32_16x16x32_bf16 v[52:55], v[144:147], v[170:173], v[52:55]
	v_mfma_f32_16x16x32_bf16 v[48:51], v[152:155], v[170:173], v[48:51]
	v_mfma_f32_16x16x32_bf16 v[36:39], v[144:147], v[186:189], v[36:39]
	v_mfma_f32_16x16x32_bf16 v[32:35], v[152:155], v[186:189], v[32:35]
	v_mfma_f32_16x16x32_bf16 v[20:23], v[144:147], v[194:197], v[20:23]
	v_mfma_f32_16x16x32_bf16 v[16:19], v[152:155], v[194:197], v[16:19]
	v_mfma_f32_16x16x32_bf16 v[4:7], v[144:147], v[202:205], v[4:7]
	v_mfma_f32_16x16x32_bf16 v[0:3], v[152:155], v[202:205], v[0:3]
	v_mfma_f32_16x16x32_bf16 v[52:55], v[148:151], v[174:177], v[52:55]
	v_mfma_f32_16x16x32_bf16 v[48:51], v[156:159], v[174:177], v[48:51]
	v_mfma_f32_16x16x32_bf16 v[36:39], v[148:151], v[190:193], v[36:39]
	v_mfma_f32_16x16x32_bf16 v[32:35], v[156:159], v[190:193], v[32:35]
	v_mfma_f32_16x16x32_bf16 v[20:23], v[148:151], v[198:201], v[20:23]
	v_mfma_f32_16x16x32_bf16 v[16:19], v[156:159], v[198:201], v[16:19]
	v_mfma_f32_16x16x32_bf16 v[4:7], v[148:151], v[206:209], v[4:7]
	v_mfma_f32_16x16x32_bf16 v[0:3], v[156:159], v[206:209], v[0:3]
	s_setprio 0
	s_add_i32 s59, s59, 2
	s_add_u32 s60, s60, 0x100
	s_addc_u32 s61, s61, 0
	s_add_u32 s20, s20, 0x100
	s_addc_u32 s21, s21, 0
	s_cmp_gt_u32 s59, 29
	s_barrier
	s_cbranch_scc0 .LBB0_1151
	s_and_b64 vcc, exec, s[38:39]
	s_cbranch_vccz .LBB0_1154
	s_barrier
